# preload swiglu-epilogue bias and row sumsq before K-loop in 4 up-GEMM phases (removes 2 exposed load waits per unit)
# speedup vs baseline: 1.0095x; 1.0095x over previous
; #define PG8_BAR __builtin_amdgcn_s_barrier()
; template <class Epi, class Sched, bool ALIGN_EPI = false, bool SP2 = false>
; __device__ __forceinline__ void gemm_phase(LAS unsigned char* lds, const Gemm g, const Sched& S, const Epi& E) {
;     ...
;         const bool has_next = S.next(ui + 1, nxt);
;         const char* nA = has_next ? (const char*)g.A + (size_t)nxt.pm * tstep + nxt.koff : cA; const char* nB = has_next ? (const char*)g.Bt + (size_t)nxt.pn * tstep + nxt.koff : cB;
;         for (int t = 0; t < nt; t += 2) {
;             const bool last = (t == nt - 2);
;             const char* a1 = cA + (size_t)(t + 1) * kstep;
;             const char* a2 = last ? nA : cA + (size_t)(t + 2) * kstep; const char* b2 = last ? nB : cB + (size_t)(t + 2) * kstep;
;             const char* a3 = a2 + kstep; const char* b3 = b2 + kstep;
;             if (last && has_next) S.a_ready(nxt);
;             if constexpr (SP2) {
;             PG8_LDB(B0, 0, 0); PG8_LDB(B1, 0, 1); PG8_SCHED; PG8_LDA(At, 0, 0); PG8_STAGE(PG8_SA(1, 1), a1 + hstep, voffA);
;             PG8_WAIT_V(8); PG8_WAIT_L(0); PG8_BAR; PG8_MMA(0, 0, At, B0); PG8_MMA(0, 1, At, B1); PG8_BAR; PG8_SCHED;
;             PG8_LDA(At, 0, 1); PG8_STAGE(PG8_SB(0, 0), b2, voffB); PG8_STAGE(PG8_SB(0, 1), b2 + hstepB, voffB); PG8_STAGE(PG8_SA(0, 0), a2, voffA);
;             PG8_WAIT_V(8); PG8_WAIT_L(0); PG8_BAR; PG8_MMA(1, 0, At, B0); PG8_MMA(1, 1, At, B1); PG8_BAR; PG8_SCHED;
;             PG8_LDB(B0, 1, 0); PG8_LDB(B1, 1, 1); PG8_SCHED; PG8_LDA(At, 1, 0); PG8_STAGE(PG8_SA(0, 1), a2 + hstep, voffA);
;             PG8_WAIT_V(8); PG8_WAIT_L(0); PG8_BAR; PG8_MMA(0, 0, At, B0); PG8_MMA(0, 1, At, B1); PG8_BAR; PG8_SCHED;
;             PG8_LDA(At, 1, 1); PG8_STAGE(PG8_SB(1, 0), b3, voffB); PG8_STAGE(PG8_SB(1, 1), b3 + hstepB, voffB); PG8_STAGE(PG8_SA(1, 0), a3, voffA);
;             PG8_WAIT_V(8); PG8_WAIT_L(0); PG8_BAR; PG8_MMA(1, 0, At, B0); PG8_MMA(1, 1, At, B1); PG8_BAR; PG8_SCHED;
;             } else {
;             PG8_LDB(B0, 0, 0); PG8_SCHED; PG8_LDA(At, 0, 0); PG8_STAGE(PG8_SA(1, 1), a1 + hstep, voffA);
;             PG8_WAIT_L(8); PG8_BAR; PG8_WAIT_L(0); PG8_MMA(0, 0, At, B0); PG8_BAR; PG8_SCHED;
;             PG8_LDB(B1, 0, 1); PG8_STAGE(PG8_SB(0, 0), b2, voffB);
;             PG8_BAR; PG8_WAIT_L(0); PG8_MMA(0, 1, At, B1); PG8_BAR;
;             PG8_LDA(At, 0, 1); PG8_STAGE(PG8_SA(0, 0), a2, voffA);
.LBB0_187:
	s_ashr_i32 s45, s44, 31
	s_lshl_b64 s[12:13], s[44:45], 20
	s_add_u32 s46, s93, s12
	s_addc_u32 s47, s92, s13
	s_and_b64 s[12:13], s[38:39], exec
	s_cselect_b32 s3, s47, s17
	s_cselect_b32 s12, s46, s16
	s_ashr_i32 s43, s42, 31
	s_lshl_b64 s[14:15], s[42:43], 20
	s_add_u32 s48, s28, s14
	s_addc_u32 s49, s29, s15
	s_and_b64 s[14:15], s[38:39], exec
	s_cselect_b32 s13, s49, s51
	s_cselect_b32 s14, s48, s50
	s_add_u32 s16, s16, 0x80080
	s_addc_u32 s17, s17, 0
	s_add_u32 s15, s50, 0x100
	v_mov_b32_e32 v2, 0
	s_addc_u32 s18, s51, 0
	s_mov_b32 s19, -2
	v_mov_b32_e32 v3, v2
	v_mov_b32_e32 v4, v2
	v_mov_b32_e32 v5, v2
	v_mov_b32_e32 v6, v2
	v_mov_b32_e32 v7, v2
	v_mov_b32_e32 v8, v2
	v_mov_b32_e32 v9, v2
	v_mov_b32_e32 v18, v2
	v_mov_b32_e32 v19, v2
	v_mov_b32_e32 v20, v2
	v_mov_b32_e32 v21, v2
	v_mov_b32_e32 v22, v2
	v_mov_b32_e32 v23, v2
	v_mov_b32_e32 v24, v2
	v_mov_b32_e32 v25, v2
	v_mov_b32_e32 v34, v2
	v_mov_b32_e32 v35, v2
	v_mov_b32_e32 v36, v2
	v_mov_b32_e32 v37, v2
	v_mov_b32_e32 v38, v2
	v_mov_b32_e32 v39, v2
	v_mov_b32_e32 v40, v2
	v_mov_b32_e32 v41, v2
	v_mov_b32_e32 v50, v2
	v_mov_b32_e32 v51, v2
	v_mov_b32_e32 v52, v2
	v_mov_b32_e32 v53, v2
	v_mov_b32_e32 v54, v2
	v_mov_b32_e32 v55, v2
	v_mov_b32_e32 v56, v2
	v_mov_b32_e32 v57, v2
	v_mov_b32_e32 v10, v2
	v_mov_b32_e32 v11, v2
	v_mov_b32_e32 v12, v2
	v_mov_b32_e32 v13, v2
	v_mov_b32_e32 v14, v2
	v_mov_b32_e32 v15, v2
	v_mov_b32_e32 v16, v2
	v_mov_b32_e32 v17, v2
	v_mov_b32_e32 v26, v2
	v_mov_b32_e32 v27, v2
	v_mov_b32_e32 v28, v2
	v_mov_b32_e32 v29, v2
	v_mov_b32_e32 v30, v2
	v_mov_b32_e32 v31, v2
	v_mov_b32_e32 v32, v2
	v_mov_b32_e32 v33, v2
	v_mov_b32_e32 v42, v2
	v_mov_b32_e32 v43, v2
	v_mov_b32_e32 v44, v2
	v_mov_b32_e32 v45, v2
	v_mov_b32_e32 v46, v2
	v_mov_b32_e32 v47, v2
	v_mov_b32_e32 v48, v2
	v_mov_b32_e32 v49, v2
	v_mov_b32_e32 v58, v2
	v_mov_b32_e32 v59, v2
	v_mov_b32_e32 v60, v2
	v_mov_b32_e32 v61, v2
	v_mov_b32_e32 v62, v2
	v_mov_b32_e32 v63, v2
	v_mov_b32_e32 v64, v2
	v_mov_b32_e32 v65, v2
	v_mov_b32_e32 v82, v2
	v_mov_b32_e32 v83, v2
	v_mov_b32_e32 v84, v2
	v_mov_b32_e32 v85, v2
	v_mov_b32_e32 v86, v2
	v_mov_b32_e32 v87, v2
	v_mov_b32_e32 v88, v2
	v_mov_b32_e32 v89, v2
	v_mov_b32_e32 v98, v2
	v_mov_b32_e32 v99, v2
	v_mov_b32_e32 v100, v2
	v_mov_b32_e32 v101, v2
	v_mov_b32_e32 v102, v2
	v_mov_b32_e32 v103, v2
	v_mov_b32_e32 v104, v2
	v_mov_b32_e32 v105, v2
	v_mov_b32_e32 v114, v2
	v_mov_b32_e32 v115, v2
	v_mov_b32_e32 v116, v2
	v_mov_b32_e32 v117, v2
	v_mov_b32_e32 v118, v2
	v_mov_b32_e32 v119, v2
	v_mov_b32_e32 v120, v2
	v_mov_b32_e32 v121, v2
	v_mov_b32_e32 v130, v2
	v_mov_b32_e32 v131, v2
	v_mov_b32_e32 v132, v2
	v_mov_b32_e32 v133, v2
	v_mov_b32_e32 v134, v2
	v_mov_b32_e32 v135, v2
	v_mov_b32_e32 v136, v2
	v_mov_b32_e32 v137, v2
	v_mov_b32_e32 v90, v2
	v_mov_b32_e32 v91, v2
	v_mov_b32_e32 v92, v2
	v_mov_b32_e32 v93, v2
	v_mov_b32_e32 v94, v2
	v_mov_b32_e32 v95, v2
	v_mov_b32_e32 v96, v2
	v_mov_b32_e32 v97, v2
	v_mov_b32_e32 v106, v2
	v_mov_b32_e32 v107, v2
	v_mov_b32_e32 v108, v2
	v_mov_b32_e32 v109, v2
	v_mov_b32_e32 v110, v2
	v_mov_b32_e32 v111, v2
	v_mov_b32_e32 v112, v2
	v_mov_b32_e32 v113, v2
	v_mov_b32_e32 v122, v2
	v_mov_b32_e32 v123, v2
	v_mov_b32_e32 v124, v2
	v_mov_b32_e32 v125, v2
	v_mov_b32_e32 v126, v2
	v_mov_b32_e32 v127, v2
	v_mov_b32_e32 v128, v2
	v_mov_b32_e32 v129, v2
	v_mov_b32_e32 v138, v2
	v_mov_b32_e32 v139, v2
	v_mov_b32_e32 v140, v2
	v_mov_b32_e32 v141, v2
	v_mov_b32_e32 v142, v2
	v_mov_b32_e32 v143, v2
	v_mov_b32_e32 v144, v2
	v_mov_b32_e32 v145, v2
	s_cmpk_gt_i32 s2, 0x7f
	s_mov_b64 s[98:99], 0xb000
	s_cbranch_scc1 .Lpre_up1l0
	s_ashr_i32 s100, s2, 5
	s_mul_hi_i32 s99, s100, 0x2c00
	s_mul_i32 s98, s100, 0x2c00
.Lpre_up1l0:
	s_lshl_b64 s[98:99], s[98:99], 2
	s_add_u32 s98, s68, s98
	s_addc_u32 s99, s69, s99
	s_lshl_b32 s100, s0, 8
	s_ashr_i32 s101, s100, 31
	s_lshl_b64 s[100:101], s[100:101], 2
	s_add_u32 s98, s98, s100
	s_addc_u32 s99, s99, s101
	s_add_u32 s98, s98, s60
	s_addc_u32 s99, s99, 0
	s_lshl_b32 s100, s2, 8
	s_add_i32 s100, s100, s54
	v_or_b32_e32 v162, s100, v171
	v_ashrrev_i32_e32 v163, 31, v162
	v_lshl_add_u64 v[162:163], v[162:163], 2, s[8:9]
	v_add_u32_e32 v164, s100, v172
	v_ashrrev_i32_e32 v165, 31, v164
	v_lshl_add_u64 v[164:165], v[164:165], 2, s[8:9]
	global_load_dwordx4 v[234:237], v177, s[98:99] offset:16
	global_load_dwordx4 v[238:241], v177, s[98:99]
	global_load_dwordx4 v[242:245], v177, s[98:99] offset:528
	global_load_dwordx4 v[246:249], v177, s[98:99] offset:512
	global_load_dword v250, v[162:163], off
	global_load_dword v251, v[164:165], off

; __device__ __forceinline__ unsigned cvt_pk_bf16(float lo, float hi) { unsigned r; asm volatile("v_cvt_pk_bf16_f32 %0, %1, %2" : "=v"(r) : "v"(lo), "v"(hi)); return r; }
; __device__ __forceinline__ float silu_mul(float a, float b) { return a * b * __builtin_amdgcn_rcpf(1.0f + __builtin_amdgcn_exp2f(-a * LOG2E)); }
; __device__ __forceinline__ float row_rstd(const float* ss, int row) { return 1.0f / sqrtf(ss[row] * (1.0f / DM) + 1e-6f); }
;     __device__ __forceinline__ void operator()(const f32x4 (&acc)[2][2][4][2], const Unit& u, int wr, int wc, int fr, int fq) const {
;         const int row0 = u.pm * BM + wr * 64 + fr, col0 = u.pn * HALF + wc * 32 + 8 * fq;
;         const int s = (u.pm < ML / BM) ? (u.pm >> 5) : 4;
;         const float* bp = bias + (size_t)s * BIAS_N + u.pn * BM + wc * 32 + 8 * fq;
;         const f32x4 ba0 = *(const f32x4*)bp, ba1 = *(const f32x4*)(bp + 4), bb0 = *(const f32x4*)(bp + HALF), bb1 = *(const f32x4*)(bp + HALF + 4);
;         const int lane = fq * 16 + fr;
;         const float rsl0 = row_rstd(ss, u.pm * BM + wr * 64 + lane), rsl1 = row_rstd(ss, u.pm * BM + HALF + wr * 64 + lane);
; #pragma unroll
;         for (int ai = 0; ai < 2; ++ai)
; #pragma unroll
;             for (int m = 0; m < 4; ++m) { const int row = row0 + ai * HALF + m * 16; const float rs = __shfl(ai ? rsl1 : rsl0, m * 16 + fr); bf16_t* rowp = O + (size_t)row * DFF + col0;
;                 const f32x4 a0 = acc[ai][0][m][0] * rs + ba0, a1 = acc[ai][0][m][1] * rs + ba1, b0 = acc[ai][1][m][0] * rs + bb0, b1 = acc[ai][1][m][1] * rs + bb1;
;                 u32x4 w; w.x = cvt_pk_bf16(silu_mul(a0[0], b0[0]), silu_mul(a0[1], b0[1])); w.y = cvt_pk_bf16(silu_mul(a0[2], b0[2]), silu_mul(a0[3], b0[3]));
;                 w.z = cvt_pk_bf16(silu_mul(a1[0], b1[0]), silu_mul(a1[1], b1[1])); w.w = cvt_pk_bf16(silu_mul(a1[2], b1[2]), silu_mul(a1[3], b1[3]));
;                 *(u32x4*)rowp = w; }
.LBB0_193:
	s_lshl_b32 s2, s2, 8
	s_add_i32 s12, s2, s54
	s_lshl_b64 s[2:3], s[16:17], 2
	s_add_u32 s13, s68, s2
	s_addc_u32 s14, s69, s3
	s_lshl_b32 s2, s0, 8
	s_ashr_i32 s3, s2, 31
	s_lshl_b64 s[2:3], s[2:3], 2
	v_lshl_or_b32 v164, s0, 7, v173
	s_add_u32 s0, s13, s2
	s_addc_u32 s3, s14, s3
	v_or_b32_e32 v162, s12, v171
	s_add_u32 s2, s0, s60
	v_ashrrev_i32_e32 v163, 31, v162
	s_addc_u32 s3, s3, 0
	v_lshl_add_u64 v[162:163], v[162:163], 2, s[8:9]
	v_mov_b32_e32 v74, v234
	v_mov_b32_e32 v75, v235
	v_mov_b32_e32 v76, v236
	v_mov_b32_e32 v77, v237
	v_mov_b32_e32 v78, v238
	v_mov_b32_e32 v79, v239
	v_mov_b32_e32 v80, v240
	v_mov_b32_e32 v81, v241
	v_mov_b32_e32 v66, v242
	v_mov_b32_e32 v67, v243
	v_mov_b32_e32 v68, v244
	v_mov_b32_e32 v69, v245
	v_mov_b32_e32 v70, v246
	v_mov_b32_e32 v71, v247
	v_mov_b32_e32 v72, v248
	v_mov_b32_e32 v73, v249
	v_or_b32_e32 v181, s12, v169
	v_mov_b32_e32 v162, v250
	v_fmamk_f32 v162, v162, 0x3a000000, v178
	v_cmp_gt_f32_e32 vcc, s61, v162
	v_mul_f32_e32 v163, 0x4f800000, v162
	s_nop 0
	v_cndmask_b32_e32 v162, v162, v163, vcc
	v_sqrt_f32_e32 v163, v162
	s_nop 0
	v_add_u32_e32 v165, -1, v163
	v_fma_f32 v166, -v165, v163, v162
	v_cmp_ge_f32_e64 s[2:3], 0, v166
	v_add_u32_e32 v166, 1, v163
	s_nop 0
	v_cndmask_b32_e64 v165, v163, v165, s[2:3]
	v_fma_f32 v163, -v166, v163, v162
	v_cmp_lt_f32_e64 s[2:3], 0, v163
	s_nop 1
	v_cndmask_b32_e64 v163, v165, v166, s[2:3]
	v_mul_f32_e32 v165, 0x37800000, v163
	v_cndmask_b32_e32 v163, v163, v165, vcc
	v_cmp_class_f32_e32 vcc, v162, v179
	s_nop 1
	v_cndmask_b32_e32 v166, v163, v162, vcc
	v_add_u32_e32 v162, s12, v172
	v_ashrrev_i32_e32 v163, 31, v162
	v_lshl_add_u64 v[162:163], v[162:163], 2, s[8:9]
	v_mov_b32_e32 v162, v251
	v_fmamk_f32 v162, v162, 0x3a000000, v178
	v_cmp_gt_f32_e32 vcc, s61, v162
	v_mul_f32_e32 v163, 0x4f800000, v162
	s_nop 0
	v_cndmask_b32_e32 v162, v162, v163, vcc
	v_sqrt_f32_e32 v163, v162
	s_nop 0
	v_add_u32_e32 v165, -1, v163
	v_fma_f32 v167, -v165, v163, v162
	v_cmp_ge_f32_e64 s[2:3], 0, v167
	v_add_u32_e32 v167, 1, v163
	s_nop 0
	v_cndmask_b32_e64 v165, v163, v165, s[2:3]
	v_fma_f32 v163, -v167, v163, v162
	v_cmp_lt_f32_e64 s[2:3], 0, v163
	s_nop 1
	v_cndmask_b32_e64 v163, v165, v167, s[2:3]
	v_mul_f32_e32 v165, 0x37800000, v163
	v_cndmask_b32_e32 v163, v163, v165, vcc
	v_cmp_class_f32_e32 vcc, v162, v179
	v_ashrrev_i32_e32 v165, 31, v164
	v_lshlrev_b64 v[164:165], 1, v[164:165]
	v_cndmask_b32_e32 v182, v163, v162, vcc
	v_div_scale_f32 v162, s[2:3], v166, v166, 1.0
	v_rcp_f32_e32 v163, v162
	s_nop 0
	v_fma_f32 v167, -v162, v163, 1.0
	v_fmac_f32_e32 v163, v167, v163
	v_div_scale_f32 v167, vcc, 1.0, v166, 1.0
	v_mul_f32_e32 v168, v167, v163
	v_fma_f32 v183, -v162, v168, v167
	v_fmac_f32_e32 v168, v183, v163
	v_fma_f32 v162, -v162, v168, v167
	v_div_fmas_f32 v162, v162, v163, v168
	v_div_fixup_f32 v183, v162, v166, 1.0
	ds_bpermute_b32 v168, v180, v183
	v_mov_b64_e32 v[162:163], s[96:97]
	v_mad_i64_i32 v[166:167], s[2:3], v181, s59, v[162:163]
	v_lshl_add_u64 v[166:167], v[166:167], 0, v[164:165]
	s_waitcnt lgkmcnt(0)
	v_pk_fma_f32 v[142:143], v[142:143], v[168:169], v[78:79] op_sel_hi:[1,0,1]
	v_pk_fma_f32 v[134:135], v[134:135], v[168:169], v[70:71] op_sel_hi:[1,0,1]
	v_pk_fma_f32 v[184:185], v[132:133], v[168:169], v[68:69] op_sel_hi:[1,0,1]
	v_pk_fma_f32 v[132:133], v[130:131], v[168:169], v[66:67] op_sel_hi:[1,0,1]
	v_mul_f32_e32 v131, 0xbfb8aa3b, v142
	v_mul_f32_e32 v130, v142, v134
	v_exp_f32_e32 v131, v131
	v_mul_f32_e32 v134, 0xbfb8aa3b, v143
	v_exp_f32_e32 v134, v134
	v_pk_fma_f32 v[144:145], v[144:145], v[168:169], v[80:81] op_sel_hi:[1,0,1]
	v_add_f32_e32 v131, 1.0, v131
	v_rcp_f32_e32 v131, v131
	v_add_f32_e32 v134, 1.0, v134
	v_rcp_f32_e32 v134, v134
	v_pk_fma_f32 v[136:137], v[136:137], v[168:169], v[72:73] op_sel_hi:[1,0,1]
	v_mul_f32_e32 v130, v130, v131
	v_mul_f32_e32 v131, v143, v135
	v_mul_f32_e32 v131, v131, v134
	v_mul_f32_e32 v134, 0xbfb8aa3b, v144
	v_exp_f32_e32 v134, v134
	v_mul_f32_e32 v135, 0xbfb8aa3b, v145
	v_exp_f32_e32 v135, v135
	v_cvt_pk_bf16_f32 v130, v130, v131
	v_add_f32_e32 v134, 1.0, v134
	v_rcp_f32_e32 v134, v134
	v_add_f32_e32 v135, 1.0, v135
	v_rcp_f32_e32 v135, v135
	v_mul_f32_e32 v131, v144, v136
	v_mul_f32_e32 v131, v131, v134
	v_mul_f32_e32 v134, v145, v137
	v_pk_fma_f32 v[138:139], v[138:139], v[168:169], v[74:75] op_sel_hi:[1,0,1]
	v_mul_f32_e32 v134, v134, v135
	v_cvt_pk_bf16_f32 v131, v131, v134
	v_mul_f32_e32 v134, 0xbfb8aa3b, v138
	v_exp_f32_e32 v134, v134
	v_mul_f32_e32 v132, v138, v132
	v_pk_fma_f32 v[140:141], v[140:141], v[168:169], v[76:77] op_sel_hi:[1,0,1]
	v_mul_f32_e32 v133, v139, v133
	v_add_f32_e32 v134, 1.0, v134
	v_rcp_f32_e32 v134, v134
	v_mul_f32_e32 v135, 0xbfb8aa3b, v141
	v_exp_f32_e32 v135, v135
	v_mul_f32_e32 v132, v132, v134
	v_mul_f32_e32 v134, 0xbfb8aa3b, v139
	v_exp_f32_e32 v134, v134
	v_add_f32_e32 v135, 1.0, v135
	v_rcp_f32_e32 v135, v135
	v_add_f32_e32 v134, 1.0, v134
	v_rcp_f32_e32 v134, v134
	s_nop 0
	v_mul_f32_e32 v133, v133, v134
	v_mul_f32_e32 v134, 0xbfb8aa3b, v140
	v_exp_f32_e32 v134, v134
	v_cvt_pk_bf16_f32 v132, v132, v133
	v_mul_f32_e32 v133, v140, v184
	v_add_f32_e32 v134, 1.0, v134
	v_rcp_f32_e32 v134, v134
	s_nop 0
	v_mul_f32_e32 v133, v133, v134
	v_mul_f32_e32 v134, v141, v185
	v_mul_f32_e32 v134, v134, v135
	v_cvt_pk_bf16_f32 v133, v133, v134
	global_store_dwordx4 v[166:167], v[130:133], off
	ds_bpermute_b32 v130, v180, v183 offset:64
	s_nop 0
	v_or_b32_e32 v131, 16, v181
	v_mad_i64_i32 v[132:133], s[2:3], v131, s59, v[162:163]
	s_waitcnt lgkmcnt(0)
; __device__ __forceinline__ unsigned cvt_pk_bf16(float lo, float hi) { unsigned r; asm volatile("v_cvt_pk_bf16_f32 %0, %1, %2" : "=v"(r) : "v"(lo), "v"(hi)); return r; }
; __device__ __forceinline__ float silu_mul(float a, float b) { return a * b * __builtin_amdgcn_rcpf(1.0f + __builtin_amdgcn_exp2f(-a * LOG2E)); }
;     __device__ __forceinline__ void operator()(const f32x4 (&acc)[2][2][4][2], const Unit& u, int wr, int wc, int fr, int fq) const {
;     ...
;             for (int m = 0; m < 4; ++m) { const int row = row0 + ai * HALF + m * 16; const float rs = __shfl(ai ? rsl1 : rsl0, m * 16 + fr); bf16_t* rowp = O + (size_t)row * DFF + col0;
;                 const f32x4 a0 = acc[ai][0][m][0] * rs + ba0, a1 = acc[ai][0][m][1] * rs + ba1, b0 = acc[ai][1][m][0] * rs + bb0, b1 = acc[ai][1][m][1] * rs + bb1;
;                 u32x4 w; w.x = cvt_pk_bf16(silu_mul(a0[0], b0[0]), silu_mul(a0[1], b0[1])); w.y = cvt_pk_bf16(silu_mul(a0[2], b0[2]), silu_mul(a0[3], b0[3]));
;                 w.z = cvt_pk_bf16(silu_mul(a1[0], b1[0]), silu_mul(a1[1], b1[1])); w.w = cvt_pk_bf16(silu_mul(a1[2], b1[2]), silu_mul(a1[3], b1[3]));
;                 *(u32x4*)rowp = w; }
	v_pk_fma_f32 v[126:127], v[126:127], v[130:131], v[78:79] op_sel_hi:[1,0,1]
	v_pk_fma_f32 v[118:119], v[118:119], v[130:131], v[70:71] op_sel_hi:[1,0,1]
	v_pk_fma_f32 v[134:135], v[116:117], v[130:131], v[68:69] op_sel_hi:[1,0,1]
	v_pk_fma_f32 v[116:117], v[114:115], v[130:131], v[66:67] op_sel_hi:[1,0,1]
	v_mul_f32_e32 v115, 0xbfb8aa3b, v126
	v_mul_f32_e32 v114, v126, v118
	v_exp_f32_e32 v115, v115
	v_mul_f32_e32 v118, 0xbfb8aa3b, v127
	v_exp_f32_e32 v118, v118
	v_pk_fma_f32 v[128:129], v[128:129], v[130:131], v[80:81] op_sel_hi:[1,0,1]
	v_add_f32_e32 v115, 1.0, v115
	v_rcp_f32_e32 v115, v115
	v_add_f32_e32 v118, 1.0, v118
	v_rcp_f32_e32 v118, v118
	v_pk_fma_f32 v[120:121], v[120:121], v[130:131], v[72:73] op_sel_hi:[1,0,1]
	v_mul_f32_e32 v114, v114, v115
	v_mul_f32_e32 v115, v127, v119
	v_mul_f32_e32 v115, v115, v118
	v_mul_f32_e32 v118, 0xbfb8aa3b, v128
	v_exp_f32_e32 v118, v118
	v_mul_f32_e32 v119, 0xbfb8aa3b, v129
	v_exp_f32_e32 v119, v119
	v_cvt_pk_bf16_f32 v114, v114, v115
	v_add_f32_e32 v118, 1.0, v118
	v_rcp_f32_e32 v118, v118
	v_add_f32_e32 v119, 1.0, v119
	v_rcp_f32_e32 v119, v119
	v_mul_f32_e32 v115, v128, v120
	v_mul_f32_e32 v115, v115, v118
	v_mul_f32_e32 v118, v129, v121
	v_pk_fma_f32 v[122:123], v[122:123], v[130:131], v[74:75] op_sel_hi:[1,0,1]
	v_mul_f32_e32 v118, v118, v119
	v_cvt_pk_bf16_f32 v115, v115, v118
	v_mul_f32_e32 v118, 0xbfb8aa3b, v122
	v_exp_f32_e32 v118, v118
	v_mul_f32_e32 v116, v122, v116
	v_pk_fma_f32 v[124:125], v[124:125], v[130:131], v[76:77] op_sel_hi:[1,0,1]
	v_mul_f32_e32 v117, v123, v117
	v_add_f32_e32 v118, 1.0, v118
	v_rcp_f32_e32 v118, v118
	v_mul_f32_e32 v119, 0xbfb8aa3b, v125
	v_exp_f32_e32 v119, v119
	v_lshl_add_u64 v[132:133], v[132:133], 0, v[164:165]
	v_mul_f32_e32 v116, v116, v118
	v_mul_f32_e32 v118, 0xbfb8aa3b, v123
	v_exp_f32_e32 v118, v118
	v_add_f32_e32 v119, 1.0, v119
	v_rcp_f32_e32 v119, v119
	v_add_f32_e32 v118, 1.0, v118
	v_rcp_f32_e32 v118, v118
	s_nop 0
	v_mul_f32_e32 v117, v117, v118
	v_mul_f32_e32 v118, 0xbfb8aa3b, v124
	v_exp_f32_e32 v118, v118
	v_cvt_pk_bf16_f32 v116, v116, v117
	v_mul_f32_e32 v117, v124, v134
	v_add_f32_e32 v118, 1.0, v118
	v_rcp_f32_e32 v118, v118
	s_nop 0
	v_mul_f32_e32 v117, v117, v118
	v_mul_f32_e32 v118, v125, v135
	v_mul_f32_e32 v118, v118, v119
	v_cvt_pk_bf16_f32 v117, v117, v118
	global_store_dwordx4 v[132:133], v[114:117], off
	ds_bpermute_b32 v114, v180, v183 offset:128
	s_nop 0
	v_or_b32_e32 v115, 32, v181
	v_mad_i64_i32 v[116:117], s[2:3], v115, s59, v[162:163]
	s_waitcnt lgkmcnt(0)
	v_pk_fma_f32 v[110:111], v[110:111], v[114:115], v[78:79] op_sel_hi:[1,0,1]
	v_pk_fma_f32 v[102:103], v[102:103], v[114:115], v[70:71] op_sel_hi:[1,0,1]
	v_pk_fma_f32 v[118:119], v[100:101], v[114:115], v[68:69] op_sel_hi:[1,0,1]
	v_pk_fma_f32 v[100:101], v[98:99], v[114:115], v[66:67] op_sel_hi:[1,0,1]
	v_mul_f32_e32 v99, 0xbfb8aa3b, v110
	v_mul_f32_e32 v98, v110, v102
	v_exp_f32_e32 v99, v99
	v_mul_f32_e32 v102, 0xbfb8aa3b, v111
	v_exp_f32_e32 v102, v102
	v_pk_fma_f32 v[112:113], v[112:113], v[114:115], v[80:81] op_sel_hi:[1,0,1]
	v_add_f32_e32 v99, 1.0, v99
	v_rcp_f32_e32 v99, v99
	v_add_f32_e32 v102, 1.0, v102
	v_rcp_f32_e32 v102, v102
	v_pk_fma_f32 v[104:105], v[104:105], v[114:115], v[72:73] op_sel_hi:[1,0,1]
	v_mul_f32_e32 v98, v98, v99
	v_mul_f32_e32 v99, v111, v103
	v_mul_f32_e32 v99, v99, v102
	v_mul_f32_e32 v102, 0xbfb8aa3b, v112
	v_exp_f32_e32 v102, v102
	v_mul_f32_e32 v103, 0xbfb8aa3b, v113
	v_exp_f32_e32 v103, v103
	v_cvt_pk_bf16_f32 v98, v98, v99
	v_add_f32_e32 v102, 1.0, v102
	v_rcp_f32_e32 v102, v102
	v_add_f32_e32 v103, 1.0, v103
	v_rcp_f32_e32 v103, v103
	v_mul_f32_e32 v99, v112, v104
	v_mul_f32_e32 v99, v99, v102
	v_mul_f32_e32 v102, v113, v105
	v_pk_fma_f32 v[106:107], v[106:107], v[114:115], v[74:75] op_sel_hi:[1,0,1]
	v_mul_f32_e32 v102, v102, v103
	v_cvt_pk_bf16_f32 v99, v99, v102
	v_mul_f32_e32 v102, 0xbfb8aa3b, v106
	v_exp_f32_e32 v102, v102
	v_mul_f32_e32 v100, v106, v100
	v_pk_fma_f32 v[108:109], v[108:109], v[114:115], v[76:77] op_sel_hi:[1,0,1]
	v_mul_f32_e32 v101, v107, v101
	v_add_f32_e32 v102, 1.0, v102
	v_rcp_f32_e32 v102, v102
	v_mul_f32_e32 v103, 0xbfb8aa3b, v109
	v_exp_f32_e32 v103, v103
	v_lshl_add_u64 v[116:117], v[116:117], 0, v[164:165]
	v_mul_f32_e32 v100, v100, v102
	v_mul_f32_e32 v102, 0xbfb8aa3b, v107
	v_exp_f32_e32 v102, v102
	v_add_f32_e32 v103, 1.0, v103
	v_rcp_f32_e32 v103, v103
	v_add_f32_e32 v102, 1.0, v102
	v_rcp_f32_e32 v102, v102
	s_nop 0
	v_mul_f32_e32 v101, v101, v102
	v_mul_f32_e32 v102, 0xbfb8aa3b, v108
	v_exp_f32_e32 v102, v102
	v_cvt_pk_bf16_f32 v100, v100, v101
	v_mul_f32_e32 v101, v108, v118
	v_add_f32_e32 v102, 1.0, v102
	v_rcp_f32_e32 v102, v102
	s_nop 0
	v_mul_f32_e32 v101, v101, v102
	v_mul_f32_e32 v102, v109, v119
	v_mul_f32_e32 v102, v102, v103
	v_cvt_pk_bf16_f32 v101, v101, v102
	global_store_dwordx4 v[116:117], v[98:101], off
	ds_bpermute_b32 v98, v180, v183 offset:192
	s_nop 0
	v_or_b32_e32 v99, 48, v181
	v_mad_i64_i32 v[100:101], s[2:3], v99, s59, v[162:163]
	s_waitcnt lgkmcnt(0)
; __device__ __forceinline__ unsigned cvt_pk_bf16(float lo, float hi) { unsigned r; asm volatile("v_cvt_pk_bf16_f32 %0, %1, %2" : "=v"(r) : "v"(lo), "v"(hi)); return r; }
; __device__ __forceinline__ float row_rstd(const float* ss, int row) { return 1.0f / sqrtf(ss[row] * (1.0f / DM) + 1e-6f); }
; __device__ __forceinline__ float silu_mul(float a, float b) { return a * b * __builtin_amdgcn_rcpf(1.0f + __builtin_amdgcn_exp2f(-a * LOG2E)); }
;     __device__ __forceinline__ void operator()(const f32x4 (&acc)[2][2][4][2], const Unit& u, int wr, int wc, int fr, int fq) const {
;     ...
;         const float rsl0 = row_rstd(ss, u.pm * BM + wr * 64 + lane), rsl1 = row_rstd(ss, u.pm * BM + HALF + wr * 64 + lane);
;     ...
;             for (int m = 0; m < 4; ++m) { const int row = row0 + ai * HALF + m * 16; const float rs = __shfl(ai ? rsl1 : rsl0, m * 16 + fr); bf16_t* rowp = O + (size_t)row * DFF + col0;
;                 const f32x4 a0 = acc[ai][0][m][0] * rs + ba0, a1 = acc[ai][0][m][1] * rs + ba1, b0 = acc[ai][1][m][0] * rs + bb0, b1 = acc[ai][1][m][1] * rs + bb1;
;                 u32x4 w; w.x = cvt_pk_bf16(silu_mul(a0[0], b0[0]), silu_mul(a0[1], b0[1])); w.y = cvt_pk_bf16(silu_mul(a0[2], b0[2]), silu_mul(a0[3], b0[3]));
;                 w.z = cvt_pk_bf16(silu_mul(a1[0], b1[0]), silu_mul(a1[1], b1[1])); w.w = cvt_pk_bf16(silu_mul(a1[2], b1[2]), silu_mul(a1[3], b1[3]));
;                 *(u32x4*)rowp = w; }
	v_pk_fma_f32 v[94:95], v[94:95], v[98:99], v[78:79] op_sel_hi:[1,0,1]
	v_pk_fma_f32 v[86:87], v[86:87], v[98:99], v[70:71] op_sel_hi:[1,0,1]
	v_pk_fma_f32 v[102:103], v[84:85], v[98:99], v[68:69] op_sel_hi:[1,0,1]
	v_pk_fma_f32 v[84:85], v[82:83], v[98:99], v[66:67] op_sel_hi:[1,0,1]
	v_mul_f32_e32 v83, 0xbfb8aa3b, v94
	v_mul_f32_e32 v82, v94, v86
	v_exp_f32_e32 v83, v83
	v_mul_f32_e32 v86, 0xbfb8aa3b, v95
	v_exp_f32_e32 v86, v86
	v_pk_fma_f32 v[96:97], v[96:97], v[98:99], v[80:81] op_sel_hi:[1,0,1]
	v_add_f32_e32 v83, 1.0, v83
	v_rcp_f32_e32 v83, v83
	v_add_f32_e32 v86, 1.0, v86
	v_rcp_f32_e32 v86, v86
	v_pk_fma_f32 v[88:89], v[88:89], v[98:99], v[72:73] op_sel_hi:[1,0,1]
	v_mul_f32_e32 v82, v82, v83
	v_mul_f32_e32 v83, v95, v87
	v_mul_f32_e32 v83, v83, v86
	v_mul_f32_e32 v86, 0xbfb8aa3b, v96
	v_exp_f32_e32 v86, v86
	v_mul_f32_e32 v87, 0xbfb8aa3b, v97
	v_exp_f32_e32 v87, v87
	v_cvt_pk_bf16_f32 v82, v82, v83
	v_add_f32_e32 v86, 1.0, v86
	v_rcp_f32_e32 v86, v86
	v_add_f32_e32 v87, 1.0, v87
	v_rcp_f32_e32 v87, v87
	v_mul_f32_e32 v83, v96, v88
	v_mul_f32_e32 v83, v83, v86
	v_mul_f32_e32 v86, v97, v89
	v_pk_fma_f32 v[90:91], v[90:91], v[98:99], v[74:75] op_sel_hi:[1,0,1]
	v_mul_f32_e32 v86, v86, v87
	v_cvt_pk_bf16_f32 v83, v83, v86
	v_mul_f32_e32 v86, 0xbfb8aa3b, v90
	v_exp_f32_e32 v86, v86
	v_mul_f32_e32 v84, v90, v84
	v_pk_fma_f32 v[92:93], v[92:93], v[98:99], v[76:77] op_sel_hi:[1,0,1]
	v_mul_f32_e32 v85, v91, v85
	v_add_f32_e32 v86, 1.0, v86
	v_rcp_f32_e32 v86, v86
	v_mul_f32_e32 v87, 0xbfb8aa3b, v93
	v_exp_f32_e32 v87, v87
	v_lshl_add_u64 v[100:101], v[100:101], 0, v[164:165]
	v_mul_f32_e32 v84, v84, v86
	v_mul_f32_e32 v86, 0xbfb8aa3b, v91
	v_exp_f32_e32 v86, v86
	v_add_f32_e32 v87, 1.0, v87
	v_rcp_f32_e32 v87, v87
	v_add_f32_e32 v86, 1.0, v86
	v_rcp_f32_e32 v86, v86
	s_nop 0
	v_mul_f32_e32 v85, v85, v86
	v_mul_f32_e32 v86, 0xbfb8aa3b, v92
	v_exp_f32_e32 v86, v86
	v_cvt_pk_bf16_f32 v84, v84, v85
	v_mul_f32_e32 v85, v92, v102
	v_add_f32_e32 v86, 1.0, v86
	v_rcp_f32_e32 v86, v86
	s_nop 0
	v_mul_f32_e32 v85, v85, v86
	v_mul_f32_e32 v86, v93, v103
	v_mul_f32_e32 v86, v86, v87
	v_cvt_pk_bf16_f32 v85, v85, v86
	global_store_dwordx4 v[100:101], v[82:85], off
	s_nop 1
	v_div_scale_f32 v82, s[2:3], v182, v182, 1.0
	v_rcp_f32_e32 v84, v82
	v_add_u32_e32 v83, 0x80, v181
	v_fma_f32 v85, -v82, v84, 1.0
	v_fmac_f32_e32 v84, v85, v84
	v_div_scale_f32 v85, vcc, 1.0, v182, 1.0
	v_mul_f32_e32 v86, v85, v84
	v_fma_f32 v87, -v82, v86, v85
	v_fmac_f32_e32 v86, v87, v84
	v_fma_f32 v82, -v82, v86, v85
	v_div_fmas_f32 v82, v82, v84, v86
	v_div_fixup_f32 v82, v82, v182, 1.0
	ds_bpermute_b32 v84, v180, v82
	v_mad_i64_i32 v[86:87], s[2:3], v83, s59, v[162:163]
	v_lshl_add_u64 v[86:87], v[86:87], 0, v[164:165]
	s_andn2_b64 vcc, exec, s[38:39]
	s_waitcnt lgkmcnt(0)
	v_pk_fma_f32 v[62:63], v[62:63], v[84:85], v[78:79] op_sel_hi:[1,0,1]
	v_pk_fma_f32 v[54:55], v[54:55], v[84:85], v[70:71] op_sel_hi:[1,0,1]
	v_pk_fma_f32 v[88:89], v[52:53], v[84:85], v[68:69] op_sel_hi:[1,0,1]
	v_pk_fma_f32 v[52:53], v[50:51], v[84:85], v[66:67] op_sel_hi:[1,0,1]
	v_mul_f32_e32 v51, 0xbfb8aa3b, v62
	v_mul_f32_e32 v50, v62, v54
	v_exp_f32_e32 v51, v51
	v_mul_f32_e32 v54, 0xbfb8aa3b, v63
	v_exp_f32_e32 v54, v54
	v_pk_fma_f32 v[64:65], v[64:65], v[84:85], v[80:81] op_sel_hi:[1,0,1]
	v_add_f32_e32 v51, 1.0, v51
	v_rcp_f32_e32 v51, v51
	v_add_f32_e32 v54, 1.0, v54
	v_rcp_f32_e32 v54, v54
	v_pk_fma_f32 v[56:57], v[56:57], v[84:85], v[72:73] op_sel_hi:[1,0,1]
	v_mul_f32_e32 v50, v50, v51
	v_mul_f32_e32 v51, v63, v55
	v_mul_f32_e32 v51, v51, v54
	v_mul_f32_e32 v54, 0xbfb8aa3b, v64
	v_exp_f32_e32 v54, v54
	v_mul_f32_e32 v55, 0xbfb8aa3b, v65
	v_exp_f32_e32 v55, v55
	v_cvt_pk_bf16_f32 v50, v50, v51
	v_add_f32_e32 v54, 1.0, v54
	v_rcp_f32_e32 v54, v54
	v_add_f32_e32 v55, 1.0, v55
	v_rcp_f32_e32 v55, v55
	v_mul_f32_e32 v51, v64, v56
	v_mul_f32_e32 v51, v51, v54
	v_mul_f32_e32 v54, v65, v57
	v_pk_fma_f32 v[58:59], v[58:59], v[84:85], v[74:75] op_sel_hi:[1,0,1]
	v_mul_f32_e32 v54, v54, v55
	v_cvt_pk_bf16_f32 v51, v51, v54
	v_mul_f32_e32 v54, 0xbfb8aa3b, v58
	v_exp_f32_e32 v54, v54
	v_mul_f32_e32 v52, v58, v52
	v_pk_fma_f32 v[60:61], v[60:61], v[84:85], v[76:77] op_sel_hi:[1,0,1]
	v_mul_f32_e32 v53, v59, v53
	v_add_f32_e32 v54, 1.0, v54
	v_rcp_f32_e32 v54, v54
	v_mul_f32_e32 v55, 0xbfb8aa3b, v61
	v_exp_f32_e32 v55, v55
	v_mul_f32_e32 v52, v52, v54
	v_mul_f32_e32 v54, 0xbfb8aa3b, v59
	v_exp_f32_e32 v54, v54
	v_add_f32_e32 v55, 1.0, v55
	v_rcp_f32_e32 v55, v55
	v_add_f32_e32 v54, 1.0, v54
	v_rcp_f32_e32 v54, v54
	s_nop 0
	v_mul_f32_e32 v53, v53, v54
	v_mul_f32_e32 v54, 0xbfb8aa3b, v60
	v_exp_f32_e32 v54, v54
	v_cvt_pk_bf16_f32 v52, v52, v53
	v_mul_f32_e32 v53, v60, v88
	v_add_f32_e32 v54, 1.0, v54
	v_rcp_f32_e32 v54, v54
	s_nop 0
	v_mul_f32_e32 v53, v53, v54
	v_mul_f32_e32 v54, v61, v89
	v_mul_f32_e32 v54, v54, v55
	v_cvt_pk_bf16_f32 v53, v53, v54
	global_store_dwordx4 v[86:87], v[50:53], off
	ds_bpermute_b32 v50, v180, v82 offset:64
	s_nop 0
	v_add_u32_e32 v51, 0x90, v181
	v_mad_i64_i32 v[52:53], s[2:3], v51, s59, v[162:163]
	s_waitcnt lgkmcnt(0)
; __device__ __forceinline__ unsigned cvt_pk_bf16(float lo, float hi) { unsigned r; asm volatile("v_cvt_pk_bf16_f32 %0, %1, %2" : "=v"(r) : "v"(lo), "v"(hi)); return r; }
; __device__ __forceinline__ float silu_mul(float a, float b) { return a * b * __builtin_amdgcn_rcpf(1.0f + __builtin_amdgcn_exp2f(-a * LOG2E)); }
; #define PG8_BAR __builtin_amdgcn_s_barrier()
;     __device__ __forceinline__ void operator()(const f32x4 (&acc)[2][2][4][2], const Unit& u, int wr, int wc, int fr, int fq) const {
;     ...
;             for (int m = 0; m < 4; ++m) { const int row = row0 + ai * HALF + m * 16; const float rs = __shfl(ai ? rsl1 : rsl0, m * 16 + fr); bf16_t* rowp = O + (size_t)row * DFF + col0;
;                 const f32x4 a0 = acc[ai][0][m][0] * rs + ba0, a1 = acc[ai][0][m][1] * rs + ba1, b0 = acc[ai][1][m][0] * rs + bb0, b1 = acc[ai][1][m][1] * rs + bb1;
;                 u32x4 w; w.x = cvt_pk_bf16(silu_mul(a0[0], b0[0]), silu_mul(a0[1], b0[1])); w.y = cvt_pk_bf16(silu_mul(a0[2], b0[2]), silu_mul(a0[3], b0[3]));
;                 w.z = cvt_pk_bf16(silu_mul(a1[0], b1[0]), silu_mul(a1[1], b1[1])); w.w = cvt_pk_bf16(silu_mul(a1[2], b1[2]), silu_mul(a1[3], b1[3]));
;                 *(u32x4*)rowp = w; }
; template <class Epi, class Sched, bool ALIGN_EPI = false, bool SP2 = false>
; __device__ __forceinline__ void gemm_phase(LAS unsigned char* lds, const Gemm g, const Sched& S, const Epi& E) {
;     ...
;         if (!has_next) break;
; #pragma unroll
;         for (int a = 0; a < 2; ++a)
; #pragma unroll
;             for (int b = 0; b < 2; ++b)
; #pragma unroll
;                 for (int m = 0; m < 4; ++m)
; #pragma unroll
;                     for (int n = 0; n < 2; ++n) acc[a][b][m][n] = (f32x4){0.f, 0.f, 0.f, 0.f};
;         cur = nxt; cA = nA; cB = nB; ++ui;
;         if constexpr (ALIGN_EPI) { if (wr == 1) PG8_BAR; }
	v_pk_fma_f32 v[46:47], v[46:47], v[50:51], v[78:79] op_sel_hi:[1,0,1]
	v_pk_fma_f32 v[38:39], v[38:39], v[50:51], v[70:71] op_sel_hi:[1,0,1]
	v_pk_fma_f32 v[54:55], v[36:37], v[50:51], v[68:69] op_sel_hi:[1,0,1]
	v_pk_fma_f32 v[36:37], v[34:35], v[50:51], v[66:67] op_sel_hi:[1,0,1]
	v_mul_f32_e32 v35, 0xbfb8aa3b, v46
	v_mul_f32_e32 v34, v46, v38
	v_exp_f32_e32 v35, v35
	v_mul_f32_e32 v38, 0xbfb8aa3b, v47
	v_exp_f32_e32 v38, v38
	v_pk_fma_f32 v[48:49], v[48:49], v[50:51], v[80:81] op_sel_hi:[1,0,1]
	v_add_f32_e32 v35, 1.0, v35
	v_rcp_f32_e32 v35, v35
	v_add_f32_e32 v38, 1.0, v38
	v_rcp_f32_e32 v38, v38
	v_pk_fma_f32 v[40:41], v[40:41], v[50:51], v[72:73] op_sel_hi:[1,0,1]
	v_mul_f32_e32 v34, v34, v35
	v_mul_f32_e32 v35, v47, v39
	v_mul_f32_e32 v35, v35, v38
	v_mul_f32_e32 v38, 0xbfb8aa3b, v48
	v_exp_f32_e32 v38, v38
	v_mul_f32_e32 v39, 0xbfb8aa3b, v49
	v_exp_f32_e32 v39, v39
	v_cvt_pk_bf16_f32 v34, v34, v35
	v_add_f32_e32 v38, 1.0, v38
	v_rcp_f32_e32 v38, v38
	v_add_f32_e32 v39, 1.0, v39
	v_rcp_f32_e32 v39, v39
	v_mul_f32_e32 v35, v48, v40
	v_mul_f32_e32 v35, v35, v38
	v_mul_f32_e32 v38, v49, v41
	v_pk_fma_f32 v[42:43], v[42:43], v[50:51], v[74:75] op_sel_hi:[1,0,1]
	v_mul_f32_e32 v38, v38, v39
	v_cvt_pk_bf16_f32 v35, v35, v38
	v_mul_f32_e32 v38, 0xbfb8aa3b, v42
	v_exp_f32_e32 v38, v38
	v_mul_f32_e32 v36, v42, v36
	v_pk_fma_f32 v[44:45], v[44:45], v[50:51], v[76:77] op_sel_hi:[1,0,1]
	v_mul_f32_e32 v37, v43, v37
	v_add_f32_e32 v38, 1.0, v38
	v_rcp_f32_e32 v38, v38
	v_mul_f32_e32 v39, 0xbfb8aa3b, v45
	v_exp_f32_e32 v39, v39
	v_lshl_add_u64 v[52:53], v[52:53], 0, v[164:165]
	v_mul_f32_e32 v36, v36, v38
	v_mul_f32_e32 v38, 0xbfb8aa3b, v43
	v_exp_f32_e32 v38, v38
	v_add_f32_e32 v39, 1.0, v39
	v_rcp_f32_e32 v39, v39
	v_add_f32_e32 v38, 1.0, v38
	v_rcp_f32_e32 v38, v38
	s_nop 0
	v_mul_f32_e32 v37, v37, v38
	v_mul_f32_e32 v38, 0xbfb8aa3b, v44
	v_exp_f32_e32 v38, v38
	v_cvt_pk_bf16_f32 v36, v36, v37
	v_mul_f32_e32 v37, v44, v54
	v_add_f32_e32 v38, 1.0, v38
	v_rcp_f32_e32 v38, v38
	s_nop 0
	v_mul_f32_e32 v37, v37, v38
	v_mul_f32_e32 v38, v45, v55
	v_mul_f32_e32 v38, v38, v39
	v_cvt_pk_bf16_f32 v37, v37, v38
	global_store_dwordx4 v[52:53], v[34:37], off
	ds_bpermute_b32 v34, v180, v82 offset:128
	s_nop 0
	v_add_u32_e32 v35, 0xa0, v181
	v_mad_i64_i32 v[36:37], s[2:3], v35, s59, v[162:163]
	s_waitcnt lgkmcnt(0)
	v_pk_fma_f32 v[30:31], v[30:31], v[34:35], v[78:79] op_sel_hi:[1,0,1]
	v_pk_fma_f32 v[22:23], v[22:23], v[34:35], v[70:71] op_sel_hi:[1,0,1]
	v_pk_fma_f32 v[38:39], v[20:21], v[34:35], v[68:69] op_sel_hi:[1,0,1]
	v_pk_fma_f32 v[20:21], v[18:19], v[34:35], v[66:67] op_sel_hi:[1,0,1]
	v_mul_f32_e32 v19, 0xbfb8aa3b, v30
	v_mul_f32_e32 v18, v30, v22
	v_exp_f32_e32 v19, v19
	v_mul_f32_e32 v22, 0xbfb8aa3b, v31
	v_exp_f32_e32 v22, v22
	v_pk_fma_f32 v[32:33], v[32:33], v[34:35], v[80:81] op_sel_hi:[1,0,1]
	v_add_f32_e32 v19, 1.0, v19
	v_rcp_f32_e32 v19, v19
	v_add_f32_e32 v22, 1.0, v22
	v_rcp_f32_e32 v22, v22
	v_pk_fma_f32 v[24:25], v[24:25], v[34:35], v[72:73] op_sel_hi:[1,0,1]
	v_mul_f32_e32 v18, v18, v19
	v_mul_f32_e32 v19, v31, v23
	v_mul_f32_e32 v19, v19, v22
	v_mul_f32_e32 v22, 0xbfb8aa3b, v32
	v_exp_f32_e32 v22, v22
	v_mul_f32_e32 v23, 0xbfb8aa3b, v33
	v_exp_f32_e32 v23, v23
	v_cvt_pk_bf16_f32 v18, v18, v19
	v_add_f32_e32 v22, 1.0, v22
	v_rcp_f32_e32 v22, v22
	v_add_f32_e32 v23, 1.0, v23
	v_rcp_f32_e32 v23, v23
	v_mul_f32_e32 v19, v32, v24
	v_mul_f32_e32 v19, v19, v22
	v_mul_f32_e32 v22, v33, v25
	v_pk_fma_f32 v[26:27], v[26:27], v[34:35], v[74:75] op_sel_hi:[1,0,1]
	v_mul_f32_e32 v22, v22, v23
	v_cvt_pk_bf16_f32 v19, v19, v22
	v_mul_f32_e32 v22, 0xbfb8aa3b, v26
	v_exp_f32_e32 v22, v22
	v_mul_f32_e32 v20, v26, v20
	v_pk_fma_f32 v[28:29], v[28:29], v[34:35], v[76:77] op_sel_hi:[1,0,1]
	v_mul_f32_e32 v21, v27, v21
	v_add_f32_e32 v22, 1.0, v22
	v_rcp_f32_e32 v22, v22
	v_mul_f32_e32 v23, 0xbfb8aa3b, v29
	v_exp_f32_e32 v23, v23
	v_lshl_add_u64 v[36:37], v[36:37], 0, v[164:165]
	v_mul_f32_e32 v20, v20, v22
	v_mul_f32_e32 v22, 0xbfb8aa3b, v27
	v_exp_f32_e32 v22, v22
	v_add_f32_e32 v23, 1.0, v23
	v_rcp_f32_e32 v23, v23
	v_add_f32_e32 v22, 1.0, v22
	v_rcp_f32_e32 v22, v22
	s_nop 0
	v_mul_f32_e32 v21, v21, v22
	v_mul_f32_e32 v22, 0xbfb8aa3b, v28
	v_exp_f32_e32 v22, v22
	v_cvt_pk_bf16_f32 v20, v20, v21
	v_mul_f32_e32 v21, v28, v38
	v_add_f32_e32 v22, 1.0, v22
	v_rcp_f32_e32 v22, v22
	s_nop 0
	v_mul_f32_e32 v21, v21, v22
	v_mul_f32_e32 v22, v29, v39
	v_mul_f32_e32 v22, v22, v23
	v_cvt_pk_bf16_f32 v21, v21, v22
	global_store_dwordx4 v[36:37], v[18:21], off
	ds_bpermute_b32 v18, v180, v82 offset:192
	s_nop 0
	v_add_u32_e32 v19, 0xb0, v181
	v_mad_i64_i32 v[20:21], s[2:3], v19, s59, v[162:163]
	s_waitcnt lgkmcnt(0)
	v_pk_fma_f32 v[14:15], v[14:15], v[18:19], v[78:79] op_sel_hi:[1,0,1]
	v_pk_fma_f32 v[6:7], v[6:7], v[18:19], v[70:71] op_sel_hi:[1,0,1]
	v_pk_fma_f32 v[22:23], v[4:5], v[18:19], v[68:69] op_sel_hi:[1,0,1]
	v_pk_fma_f32 v[4:5], v[2:3], v[18:19], v[66:67] op_sel_hi:[1,0,1]
	v_mul_f32_e32 v3, 0xbfb8aa3b, v14
	v_mul_f32_e32 v2, v14, v6
	v_exp_f32_e32 v3, v3
	v_mul_f32_e32 v6, 0xbfb8aa3b, v15
	v_exp_f32_e32 v6, v6
	v_pk_fma_f32 v[16:17], v[16:17], v[18:19], v[80:81] op_sel_hi:[1,0,1]
	v_add_f32_e32 v3, 1.0, v3
	v_rcp_f32_e32 v3, v3
	v_add_f32_e32 v6, 1.0, v6
	v_rcp_f32_e32 v6, v6
	v_pk_fma_f32 v[8:9], v[8:9], v[18:19], v[72:73] op_sel_hi:[1,0,1]
	v_mul_f32_e32 v2, v2, v3
	v_mul_f32_e32 v3, v15, v7
	v_mul_f32_e32 v3, v3, v6
	v_mul_f32_e32 v6, 0xbfb8aa3b, v16
	v_exp_f32_e32 v6, v6
	v_mul_f32_e32 v7, 0xbfb8aa3b, v17
	v_exp_f32_e32 v7, v7
	v_cvt_pk_bf16_f32 v2, v2, v3
	v_add_f32_e32 v6, 1.0, v6
	v_rcp_f32_e32 v6, v6
	v_add_f32_e32 v7, 1.0, v7
	v_rcp_f32_e32 v7, v7
	v_mul_f32_e32 v3, v16, v8
	v_mul_f32_e32 v3, v3, v6
	v_mul_f32_e32 v6, v17, v9
	v_pk_fma_f32 v[10:11], v[10:11], v[18:19], v[74:75] op_sel_hi:[1,0,1]
	v_mul_f32_e32 v6, v6, v7
	v_cvt_pk_bf16_f32 v3, v3, v6
	v_mul_f32_e32 v6, 0xbfb8aa3b, v10
	v_exp_f32_e32 v6, v6
	v_mul_f32_e32 v4, v10, v4
	v_pk_fma_f32 v[12:13], v[12:13], v[18:19], v[76:77] op_sel_hi:[1,0,1]
	v_mul_f32_e32 v5, v11, v5
	v_add_f32_e32 v6, 1.0, v6
	v_rcp_f32_e32 v6, v6
	v_mul_f32_e32 v7, 0xbfb8aa3b, v13
	v_exp_f32_e32 v7, v7
	v_lshl_add_u64 v[20:21], v[20:21], 0, v[164:165]
	v_mul_f32_e32 v4, v4, v6
	v_mul_f32_e32 v6, 0xbfb8aa3b, v11
	v_exp_f32_e32 v6, v6
	v_add_f32_e32 v7, 1.0, v7
	v_rcp_f32_e32 v7, v7
	s_mov_b64 s[2:3], -1
	v_add_f32_e32 v6, 1.0, v6
	v_rcp_f32_e32 v6, v6
	s_nop 0
	v_mul_f32_e32 v5, v5, v6
	v_mul_f32_e32 v6, 0xbfb8aa3b, v12
	v_exp_f32_e32 v6, v6
	v_cvt_pk_bf16_f32 v4, v4, v5
	v_mul_f32_e32 v5, v12, v22
	v_add_f32_e32 v6, 1.0, v6
	v_rcp_f32_e32 v6, v6
	s_nop 0
	v_mul_f32_e32 v5, v5, v6
	v_mul_f32_e32 v6, v13, v23
	v_mul_f32_e32 v6, v6, v7
	v_cvt_pk_bf16_f32 v5, v5, v6
	global_store_dwordx4 v[20:21], v[2:5], off
	s_cbranch_vccnz .LBB0_184
	s_andn2_b64 vcc, exec, s[4:5]
	s_cbranch_vccnz .LBB0_183
	s_barrier
	s_branch .LBB0_183

; #define PG8_BAR __builtin_amdgcn_s_barrier()
; template <class Epi, class Sched, bool ALIGN_EPI = false, bool SP2 = false>
; __device__ __forceinline__ void gemm_phase(LAS unsigned char* lds, const Gemm g, const Sched& S, const Epi& E) {
;     ...
;         const bool has_next = S.next(ui + 1, nxt);
;         const char* nA = has_next ? (const char*)g.A + (size_t)nxt.pm * tstep + nxt.koff : cA; const char* nB = has_next ? (const char*)g.Bt + (size_t)nxt.pn * tstep + nxt.koff : cB;
;         for (int t = 0; t < nt; t += 2) {
;             const bool last = (t == nt - 2);
;             const char* a1 = cA + (size_t)(t + 1) * kstep;
;             const char* a2 = last ? nA : cA + (size_t)(t + 2) * kstep; const char* b2 = last ? nB : cB + (size_t)(t + 2) * kstep;
;             const char* a3 = a2 + kstep; const char* b3 = b2 + kstep;
;             if (last && has_next) S.a_ready(nxt);
;             if constexpr (SP2) {
;             PG8_LDB(B0, 0, 0); PG8_LDB(B1, 0, 1); PG8_SCHED; PG8_LDA(At, 0, 0); PG8_STAGE(PG8_SA(1, 1), a1 + hstep, voffA);
;             PG8_WAIT_V(8); PG8_WAIT_L(0); PG8_BAR; PG8_MMA(0, 0, At, B0); PG8_MMA(0, 1, At, B1); PG8_BAR; PG8_SCHED;
;             PG8_LDA(At, 0, 1); PG8_STAGE(PG8_SB(0, 0), b2, voffB); PG8_STAGE(PG8_SB(0, 1), b2 + hstepB, voffB); PG8_STAGE(PG8_SA(0, 0), a2, voffA);
;             PG8_WAIT_V(8); PG8_WAIT_L(0); PG8_BAR; PG8_MMA(1, 0, At, B0); PG8_MMA(1, 1, At, B1); PG8_BAR; PG8_SCHED;
;             PG8_LDB(B0, 1, 0); PG8_LDB(B1, 1, 1); PG8_SCHED; PG8_LDA(At, 1, 0); PG8_STAGE(PG8_SA(0, 1), a2 + hstep, voffA);
;             PG8_WAIT_V(8); PG8_WAIT_L(0); PG8_BAR; PG8_MMA(0, 0, At, B0); PG8_MMA(0, 1, At, B1); PG8_BAR; PG8_SCHED;
;             PG8_LDA(At, 1, 1); PG8_STAGE(PG8_SB(1, 0), b3, voffB); PG8_STAGE(PG8_SB(1, 1), b3 + hstepB, voffB); PG8_STAGE(PG8_SA(1, 0), a3, voffA);
;             PG8_WAIT_V(8); PG8_WAIT_L(0); PG8_BAR; PG8_MMA(1, 0, At, B0); PG8_MMA(1, 1, At, B1); PG8_BAR; PG8_SCHED;
;             } else {
;             PG8_LDB(B0, 0, 0); PG8_SCHED; PG8_LDA(At, 0, 0); PG8_STAGE(PG8_SA(1, 1), a1 + hstep, voffA);
;             PG8_WAIT_L(8); PG8_BAR; PG8_WAIT_L(0); PG8_MMA(0, 0, At, B0); PG8_BAR; PG8_SCHED;
;             PG8_LDB(B1, 0, 1); PG8_STAGE(PG8_SB(0, 0), b2, voffB);
;             PG8_BAR; PG8_WAIT_L(0); PG8_MMA(0, 1, At, B1); PG8_BAR;
;             PG8_LDA(At, 0, 1); PG8_STAGE(PG8_SA(0, 0), a2, voffA);
.LBB0_1464:
	s_ashr_i32 s15, s14, 31
	s_lshl_b64 s[18:19], s[14:15], 20
	s_add_u32 s18, s93, s18
	s_addc_u32 s19, s92, s19
	s_and_b64 s[20:21], s[38:39], exec
	s_cselect_b32 s3, s19, s17
	s_cselect_b32 s15, s18, s16
	s_ashr_i32 s13, s12, 31
	s_lshl_b64 s[20:21], s[12:13], 20
	s_add_u32 s20, s27, s20
	s_addc_u32 s21, s28, s21
	s_and_b64 s[24:25], s[38:39], exec
	s_cselect_b32 s13, s21, s23
	s_cselect_b32 s24, s20, s22
	s_add_u32 s16, s16, 0x80080
	s_addc_u32 s17, s17, 0
	s_add_u32 s25, s22, 0x100
	v_mov_b32_e32 v2, 0
	s_addc_u32 s52, s23, 0
	s_mov_b32 s53, -2
	v_mov_b32_e32 v3, v2
	v_mov_b32_e32 v4, v2
	v_mov_b32_e32 v5, v2
	v_mov_b32_e32 v6, v2
	v_mov_b32_e32 v7, v2
	v_mov_b32_e32 v8, v2
	v_mov_b32_e32 v9, v2
	v_mov_b32_e32 v18, v2
	v_mov_b32_e32 v19, v2
	v_mov_b32_e32 v20, v2
	v_mov_b32_e32 v21, v2
	v_mov_b32_e32 v22, v2
	v_mov_b32_e32 v23, v2
	v_mov_b32_e32 v24, v2
	v_mov_b32_e32 v25, v2
	v_mov_b32_e32 v34, v2
	v_mov_b32_e32 v35, v2
	v_mov_b32_e32 v36, v2
	v_mov_b32_e32 v37, v2
	v_mov_b32_e32 v38, v2
	v_mov_b32_e32 v39, v2
	v_mov_b32_e32 v40, v2
	v_mov_b32_e32 v41, v2
	v_mov_b32_e32 v50, v2
	v_mov_b32_e32 v51, v2
	v_mov_b32_e32 v52, v2
	v_mov_b32_e32 v53, v2
	v_mov_b32_e32 v54, v2
	v_mov_b32_e32 v55, v2
	v_mov_b32_e32 v56, v2
	v_mov_b32_e32 v57, v2
	v_mov_b32_e32 v10, v2
	v_mov_b32_e32 v11, v2
	v_mov_b32_e32 v12, v2
	v_mov_b32_e32 v13, v2
	v_mov_b32_e32 v14, v2
	v_mov_b32_e32 v15, v2
	v_mov_b32_e32 v16, v2
	v_mov_b32_e32 v17, v2
	v_mov_b32_e32 v26, v2
	v_mov_b32_e32 v27, v2
	v_mov_b32_e32 v28, v2
	v_mov_b32_e32 v29, v2
	v_mov_b32_e32 v30, v2
	v_mov_b32_e32 v31, v2
	v_mov_b32_e32 v32, v2
	v_mov_b32_e32 v33, v2
	v_mov_b32_e32 v42, v2
	v_mov_b32_e32 v43, v2
	v_mov_b32_e32 v44, v2
	v_mov_b32_e32 v45, v2
	v_mov_b32_e32 v46, v2
	v_mov_b32_e32 v47, v2
	v_mov_b32_e32 v48, v2
	v_mov_b32_e32 v49, v2
	v_mov_b32_e32 v58, v2
	v_mov_b32_e32 v59, v2
	v_mov_b32_e32 v60, v2
	v_mov_b32_e32 v61, v2
	v_mov_b32_e32 v62, v2
	v_mov_b32_e32 v63, v2
	v_mov_b32_e32 v64, v2
	v_mov_b32_e32 v65, v2
	v_mov_b32_e32 v82, v2
	v_mov_b32_e32 v83, v2
	v_mov_b32_e32 v84, v2
	v_mov_b32_e32 v85, v2
	v_mov_b32_e32 v86, v2
	v_mov_b32_e32 v87, v2
	v_mov_b32_e32 v88, v2
	v_mov_b32_e32 v89, v2
	s_waitcnt vmcnt(0)
	v_mov_b32_e32 v98, v2
	v_mov_b32_e32 v99, v2
	v_mov_b32_e32 v100, v2
	v_mov_b32_e32 v101, v2
	v_mov_b32_e32 v102, v2
	v_mov_b32_e32 v103, v2
	v_mov_b32_e32 v104, v2
	v_mov_b32_e32 v105, v2
	v_mov_b32_e32 v114, v2
	v_mov_b32_e32 v115, v2
	v_mov_b32_e32 v116, v2
	v_mov_b32_e32 v117, v2
	v_mov_b32_e32 v118, v2
	v_mov_b32_e32 v119, v2
	v_mov_b32_e32 v120, v2
	v_mov_b32_e32 v121, v2
	v_mov_b32_e32 v130, v2
	v_mov_b32_e32 v131, v2
	v_mov_b32_e32 v132, v2
	v_mov_b32_e32 v133, v2
	v_mov_b32_e32 v134, v2
	v_mov_b32_e32 v135, v2
	v_mov_b32_e32 v136, v2
	v_mov_b32_e32 v137, v2
	v_mov_b32_e32 v90, v2
	v_mov_b32_e32 v91, v2
	v_mov_b32_e32 v92, v2
	v_mov_b32_e32 v93, v2
	v_mov_b32_e32 v94, v2
	v_mov_b32_e32 v95, v2
	v_mov_b32_e32 v96, v2
	v_mov_b32_e32 v97, v2
	v_mov_b32_e32 v106, v2
	v_mov_b32_e32 v107, v2
	v_mov_b32_e32 v108, v2
	v_mov_b32_e32 v109, v2
	v_mov_b32_e32 v110, v2
	v_mov_b32_e32 v111, v2
	v_mov_b32_e32 v112, v2
	v_mov_b32_e32 v113, v2
	v_mov_b32_e32 v122, v2
	v_mov_b32_e32 v123, v2
	v_mov_b32_e32 v124, v2
	v_mov_b32_e32 v125, v2
	v_mov_b32_e32 v126, v2
	v_mov_b32_e32 v127, v2
	v_mov_b32_e32 v128, v2
	v_mov_b32_e32 v129, v2
	v_mov_b32_e32 v138, v2
	v_mov_b32_e32 v139, v2
	v_mov_b32_e32 v140, v2
	v_mov_b32_e32 v141, v2
	v_mov_b32_e32 v142, v2
	v_mov_b32_e32 v143, v2
	v_mov_b32_e32 v144, v2
	v_mov_b32_e32 v145, v2
	s_cmpk_gt_i32 s2, 0x7f
	s_mov_b64 s[98:99], 0xb000
	s_cbranch_scc1 .Lpre_up2l0
	s_ashr_i32 s100, s2, 5
	s_mul_hi_i32 s99, s100, 0x2c00
	s_mul_i32 s98, s100, 0x2c00
.Lpre_up2l0:
	s_lshl_b64 s[98:99], s[98:99], 2
	s_add_u32 s98, s43, s98
	s_addc_u32 s99, s44, s99
	s_lshl_b32 s100, s0, 8
	s_ashr_i32 s101, s100, 31
	s_lshl_b64 s[100:101], s[100:101], 2
	s_add_u32 s98, s98, s100
	s_addc_u32 s99, s99, s101
	s_add_u32 s98, s98, s50
	s_addc_u32 s99, s99, 0
	s_lshl_b32 s100, s2, 8
	s_add_i32 s100, s100, s42
	v_or_b32_e32 v162, s100, v171
	v_ashrrev_i32_e32 v163, 31, v162
	v_lshl_add_u64 v[162:163], v[162:163], 2, s[64:65]
	v_add_u32_e32 v164, s100, v172
	v_ashrrev_i32_e32 v165, 31, v164
	v_lshl_add_u64 v[164:165], v[164:165], 2, s[64:65]
	global_load_dwordx4 v[234:237], v177, s[98:99] offset:16
	global_load_dwordx4 v[238:241], v177, s[98:99]
	global_load_dwordx4 v[242:245], v177, s[98:99] offset:528
	global_load_dwordx4 v[246:249], v177, s[98:99] offset:512
	global_load_dword v250, v[162:163], off
	global_load_dword v251, v[164:165], off

; __device__ __forceinline__ unsigned cvt_pk_bf16(float lo, float hi) { unsigned r; asm volatile("v_cvt_pk_bf16_f32 %0, %1, %2" : "=v"(r) : "v"(lo), "v"(hi)); return r; }
; __device__ __forceinline__ float silu_mul(float a, float b) { return a * b * __builtin_amdgcn_rcpf(1.0f + __builtin_amdgcn_exp2f(-a * LOG2E)); }
; __device__ __forceinline__ float row_rstd(const float* ss, int row) { return 1.0f / sqrtf(ss[row] * (1.0f / DM) + 1e-6f); }
;     __device__ __forceinline__ void operator()(const f32x4 (&acc)[2][2][4][2], const Unit& u, int wr, int wc, int fr, int fq) const {
;         const int row0 = u.pm * BM + wr * 64 + fr, col0 = u.pn * HALF + wc * 32 + 8 * fq;
;         const int s = (u.pm < ML / BM) ? (u.pm >> 5) : 4;
;         const float* bp = bias + (size_t)s * BIAS_N + u.pn * BM + wc * 32 + 8 * fq;
;         const f32x4 ba0 = *(const f32x4*)bp, ba1 = *(const f32x4*)(bp + 4), bb0 = *(const f32x4*)(bp + HALF), bb1 = *(const f32x4*)(bp + HALF + 4);
;         const int lane = fq * 16 + fr;
;         const float rsl0 = row_rstd(ss, u.pm * BM + wr * 64 + lane), rsl1 = row_rstd(ss, u.pm * BM + HALF + wr * 64 + lane);
; #pragma unroll
;         for (int ai = 0; ai < 2; ++ai)
; #pragma unroll
;             for (int m = 0; m < 4; ++m) { const int row = row0 + ai * HALF + m * 16; const float rs = __shfl(ai ? rsl1 : rsl0, m * 16 + fr); bf16_t* rowp = O + (size_t)row * DFF + col0;
;                 const f32x4 a0 = acc[ai][0][m][0] * rs + ba0, a1 = acc[ai][0][m][1] * rs + ba1, b0 = acc[ai][1][m][0] * rs + bb0, b1 = acc[ai][1][m][1] * rs + bb1;
;                 u32x4 w; w.x = cvt_pk_bf16(silu_mul(a0[0], b0[0]), silu_mul(a0[1], b0[1])); w.y = cvt_pk_bf16(silu_mul(a0[2], b0[2]), silu_mul(a0[3], b0[3]));
;                 w.z = cvt_pk_bf16(silu_mul(a1[0], b1[0]), silu_mul(a1[1], b1[1])); w.w = cvt_pk_bf16(silu_mul(a1[2], b1[2]), silu_mul(a1[3], b1[3]));
;                 *(u32x4*)rowp = w; }
.LBB0_1470:
	s_lshl_b32 s2, s2, 8
	s_add_i32 s13, s2, s42
	s_lshl_b64 s[2:3], s[16:17], 2
	s_add_u32 s15, s43, s2
	s_addc_u32 s16, s44, s3
	s_lshl_b32 s2, s0, 8
	s_ashr_i32 s3, s2, 31
	s_lshl_b64 s[2:3], s[2:3], 2
	v_lshl_or_b32 v164, s0, 7, v173
	s_add_u32 s0, s15, s2
	s_addc_u32 s3, s16, s3
	v_or_b32_e32 v162, s13, v171
	s_add_u32 s2, s0, s50
	v_ashrrev_i32_e32 v163, 31, v162
	s_addc_u32 s3, s3, 0
	v_lshl_add_u64 v[162:163], v[162:163], 2, s[64:65]
	v_mov_b32_e32 v74, v234
	v_mov_b32_e32 v75, v235
	v_mov_b32_e32 v76, v236
	v_mov_b32_e32 v77, v237
	v_mov_b32_e32 v78, v238
	v_mov_b32_e32 v79, v239
	v_mov_b32_e32 v80, v240
	v_mov_b32_e32 v81, v241
	v_mov_b32_e32 v66, v242
	v_mov_b32_e32 v67, v243
	v_mov_b32_e32 v68, v244
	v_mov_b32_e32 v69, v245
	v_mov_b32_e32 v70, v246
	v_mov_b32_e32 v71, v247
	v_mov_b32_e32 v72, v248
	v_mov_b32_e32 v73, v249
	v_or_b32_e32 v181, s13, v169
	v_mov_b32_e32 v162, v250
	v_fmamk_f32 v162, v162, 0x3a000000, v178
	v_cmp_gt_f32_e32 vcc, s51, v162
	v_mul_f32_e32 v163, 0x4f800000, v162
	s_nop 0
	v_cndmask_b32_e32 v162, v162, v163, vcc
	v_sqrt_f32_e32 v163, v162
	s_nop 0
	v_add_u32_e32 v165, -1, v163
	v_fma_f32 v166, -v165, v163, v162
	v_cmp_ge_f32_e64 s[2:3], 0, v166
	v_add_u32_e32 v166, 1, v163
	s_nop 0
	v_cndmask_b32_e64 v165, v163, v165, s[2:3]
	v_fma_f32 v163, -v166, v163, v162
	v_cmp_lt_f32_e64 s[2:3], 0, v163
	s_nop 1
	v_cndmask_b32_e64 v163, v165, v166, s[2:3]
	v_mul_f32_e32 v165, 0x37800000, v163
	v_cndmask_b32_e32 v163, v163, v165, vcc
	v_cmp_class_f32_e32 vcc, v162, v179
	s_nop 1
	v_cndmask_b32_e32 v166, v163, v162, vcc
	v_add_u32_e32 v162, s13, v172
	v_ashrrev_i32_e32 v163, 31, v162
	v_lshl_add_u64 v[162:163], v[162:163], 2, s[64:65]
	v_mov_b32_e32 v162, v251
	v_fmamk_f32 v162, v162, 0x3a000000, v178
	v_cmp_gt_f32_e32 vcc, s51, v162
	v_mul_f32_e32 v163, 0x4f800000, v162
	s_nop 0
	v_cndmask_b32_e32 v162, v162, v163, vcc
	v_sqrt_f32_e32 v163, v162
	s_nop 0
	v_add_u32_e32 v165, -1, v163
	v_fma_f32 v167, -v165, v163, v162
	v_cmp_ge_f32_e64 s[2:3], 0, v167
	v_add_u32_e32 v167, 1, v163
	s_nop 0
	v_cndmask_b32_e64 v165, v163, v165, s[2:3]
	v_fma_f32 v163, -v167, v163, v162
	v_cmp_lt_f32_e64 s[2:3], 0, v163
	s_nop 1
	v_cndmask_b32_e64 v163, v165, v167, s[2:3]
	v_mul_f32_e32 v165, 0x37800000, v163
	v_cndmask_b32_e32 v163, v163, v165, vcc
	v_cmp_class_f32_e32 vcc, v162, v179
	v_ashrrev_i32_e32 v165, 31, v164
	v_lshlrev_b64 v[164:165], 1, v[164:165]
	v_cndmask_b32_e32 v182, v163, v162, vcc
	v_div_scale_f32 v162, s[2:3], v166, v166, 1.0
	v_rcp_f32_e32 v163, v162
	s_nop 0
	v_fma_f32 v167, -v162, v163, 1.0
	v_fmac_f32_e32 v163, v167, v163
	v_div_scale_f32 v167, vcc, 1.0, v166, 1.0
	v_mul_f32_e32 v168, v167, v163
	v_fma_f32 v183, -v162, v168, v167
	v_fmac_f32_e32 v168, v183, v163
	v_fma_f32 v162, -v162, v168, v167
	v_div_fmas_f32 v162, v162, v163, v168
	v_div_fixup_f32 v183, v162, v166, 1.0
	ds_bpermute_b32 v168, v180, v183
	v_mov_b64_e32 v[162:163], s[96:97]
	v_mad_i64_i32 v[166:167], s[2:3], v181, s49, v[162:163]
	v_lshl_add_u64 v[166:167], v[166:167], 0, v[164:165]
	s_waitcnt lgkmcnt(0)
	v_pk_fma_f32 v[142:143], v[142:143], v[168:169], v[78:79] op_sel_hi:[1,0,1]
	v_pk_fma_f32 v[134:135], v[134:135], v[168:169], v[70:71] op_sel_hi:[1,0,1]
	v_pk_fma_f32 v[184:185], v[132:133], v[168:169], v[68:69] op_sel_hi:[1,0,1]
	v_pk_fma_f32 v[132:133], v[130:131], v[168:169], v[66:67] op_sel_hi:[1,0,1]
	v_mul_f32_e32 v131, 0xbfb8aa3b, v142
	v_mul_f32_e32 v130, v142, v134
	v_exp_f32_e32 v131, v131
	v_mul_f32_e32 v134, 0xbfb8aa3b, v143
	v_exp_f32_e32 v134, v134
	v_pk_fma_f32 v[144:145], v[144:145], v[168:169], v[80:81] op_sel_hi:[1,0,1]
	v_add_f32_e32 v131, 1.0, v131
	v_rcp_f32_e32 v131, v131
	v_add_f32_e32 v134, 1.0, v134
	v_rcp_f32_e32 v134, v134
	v_pk_fma_f32 v[136:137], v[136:137], v[168:169], v[72:73] op_sel_hi:[1,0,1]
	v_mul_f32_e32 v130, v130, v131
	v_mul_f32_e32 v131, v143, v135
	v_mul_f32_e32 v131, v131, v134
	v_mul_f32_e32 v134, 0xbfb8aa3b, v144
	v_exp_f32_e32 v134, v134
	v_mul_f32_e32 v135, 0xbfb8aa3b, v145
	v_exp_f32_e32 v135, v135
	v_cvt_pk_bf16_f32 v130, v130, v131
	v_add_f32_e32 v134, 1.0, v134
	v_rcp_f32_e32 v134, v134
	v_add_f32_e32 v135, 1.0, v135
	v_rcp_f32_e32 v135, v135
	v_mul_f32_e32 v131, v144, v136
	v_mul_f32_e32 v131, v131, v134
	v_mul_f32_e32 v134, v145, v137
	v_pk_fma_f32 v[138:139], v[138:139], v[168:169], v[74:75] op_sel_hi:[1,0,1]
	v_mul_f32_e32 v134, v134, v135
	v_cvt_pk_bf16_f32 v131, v131, v134
	v_mul_f32_e32 v134, 0xbfb8aa3b, v138
	v_exp_f32_e32 v134, v134
	v_mul_f32_e32 v132, v138, v132
	v_pk_fma_f32 v[140:141], v[140:141], v[168:169], v[76:77] op_sel_hi:[1,0,1]
	v_mul_f32_e32 v133, v139, v133
	v_add_f32_e32 v134, 1.0, v134
	v_rcp_f32_e32 v134, v134
	v_mul_f32_e32 v135, 0xbfb8aa3b, v141
	v_exp_f32_e32 v135, v135
	v_mul_f32_e32 v132, v132, v134
	v_mul_f32_e32 v134, 0xbfb8aa3b, v139
	v_exp_f32_e32 v134, v134
	v_add_f32_e32 v135, 1.0, v135
	v_rcp_f32_e32 v135, v135
	v_add_f32_e32 v134, 1.0, v134
	v_rcp_f32_e32 v134, v134
	s_nop 0
	v_mul_f32_e32 v133, v133, v134
	v_mul_f32_e32 v134, 0xbfb8aa3b, v140
	v_exp_f32_e32 v134, v134
	v_cvt_pk_bf16_f32 v132, v132, v133
	v_mul_f32_e32 v133, v140, v184
	v_add_f32_e32 v134, 1.0, v134
	v_rcp_f32_e32 v134, v134
	s_nop 0
	v_mul_f32_e32 v133, v133, v134
	v_mul_f32_e32 v134, v141, v185
	v_mul_f32_e32 v134, v134, v135
	v_cvt_pk_bf16_f32 v133, v133, v134
	global_store_dwordx4 v[166:167], v[130:133], off
	ds_bpermute_b32 v130, v180, v183 offset:64
	s_nop 0
	v_or_b32_e32 v131, 16, v181
	v_mad_i64_i32 v[132:133], s[2:3], v131, s49, v[162:163]
	s_waitcnt lgkmcnt(0)
; __device__ __forceinline__ unsigned cvt_pk_bf16(float lo, float hi) { unsigned r; asm volatile("v_cvt_pk_bf16_f32 %0, %1, %2" : "=v"(r) : "v"(lo), "v"(hi)); return r; }
; __device__ __forceinline__ float silu_mul(float a, float b) { return a * b * __builtin_amdgcn_rcpf(1.0f + __builtin_amdgcn_exp2f(-a * LOG2E)); }
;     __device__ __forceinline__ void operator()(const f32x4 (&acc)[2][2][4][2], const Unit& u, int wr, int wc, int fr, int fq) const {
;     ...
;             for (int m = 0; m < 4; ++m) { const int row = row0 + ai * HALF + m * 16; const float rs = __shfl(ai ? rsl1 : rsl0, m * 16 + fr); bf16_t* rowp = O + (size_t)row * DFF + col0;
;                 const f32x4 a0 = acc[ai][0][m][0] * rs + ba0, a1 = acc[ai][0][m][1] * rs + ba1, b0 = acc[ai][1][m][0] * rs + bb0, b1 = acc[ai][1][m][1] * rs + bb1;
;                 u32x4 w; w.x = cvt_pk_bf16(silu_mul(a0[0], b0[0]), silu_mul(a0[1], b0[1])); w.y = cvt_pk_bf16(silu_mul(a0[2], b0[2]), silu_mul(a0[3], b0[3]));
;                 w.z = cvt_pk_bf16(silu_mul(a1[0], b1[0]), silu_mul(a1[1], b1[1])); w.w = cvt_pk_bf16(silu_mul(a1[2], b1[2]), silu_mul(a1[3], b1[3]));
;                 *(u32x4*)rowp = w; }
	v_pk_fma_f32 v[126:127], v[126:127], v[130:131], v[78:79] op_sel_hi:[1,0,1]
	v_pk_fma_f32 v[118:119], v[118:119], v[130:131], v[70:71] op_sel_hi:[1,0,1]
	v_pk_fma_f32 v[134:135], v[116:117], v[130:131], v[68:69] op_sel_hi:[1,0,1]
	v_pk_fma_f32 v[116:117], v[114:115], v[130:131], v[66:67] op_sel_hi:[1,0,1]
	v_mul_f32_e32 v115, 0xbfb8aa3b, v126
	v_mul_f32_e32 v114, v126, v118
	v_exp_f32_e32 v115, v115
	v_mul_f32_e32 v118, 0xbfb8aa3b, v127
	v_exp_f32_e32 v118, v118
	v_pk_fma_f32 v[128:129], v[128:129], v[130:131], v[80:81] op_sel_hi:[1,0,1]
	v_add_f32_e32 v115, 1.0, v115
	v_rcp_f32_e32 v115, v115
	v_add_f32_e32 v118, 1.0, v118
	v_rcp_f32_e32 v118, v118
	v_pk_fma_f32 v[120:121], v[120:121], v[130:131], v[72:73] op_sel_hi:[1,0,1]
	v_mul_f32_e32 v114, v114, v115
	v_mul_f32_e32 v115, v127, v119
	v_mul_f32_e32 v115, v115, v118
	v_mul_f32_e32 v118, 0xbfb8aa3b, v128
	v_exp_f32_e32 v118, v118
	v_mul_f32_e32 v119, 0xbfb8aa3b, v129
	v_exp_f32_e32 v119, v119
	v_cvt_pk_bf16_f32 v114, v114, v115
	v_add_f32_e32 v118, 1.0, v118
	v_rcp_f32_e32 v118, v118
	v_add_f32_e32 v119, 1.0, v119
	v_rcp_f32_e32 v119, v119
	v_mul_f32_e32 v115, v128, v120
	v_mul_f32_e32 v115, v115, v118
	v_mul_f32_e32 v118, v129, v121
	v_pk_fma_f32 v[122:123], v[122:123], v[130:131], v[74:75] op_sel_hi:[1,0,1]
	v_mul_f32_e32 v118, v118, v119
	v_cvt_pk_bf16_f32 v115, v115, v118
	v_mul_f32_e32 v118, 0xbfb8aa3b, v122
	v_exp_f32_e32 v118, v118
	v_mul_f32_e32 v116, v122, v116
	v_pk_fma_f32 v[124:125], v[124:125], v[130:131], v[76:77] op_sel_hi:[1,0,1]
	v_mul_f32_e32 v117, v123, v117
	v_add_f32_e32 v118, 1.0, v118
	v_rcp_f32_e32 v118, v118
	v_mul_f32_e32 v119, 0xbfb8aa3b, v125
	v_exp_f32_e32 v119, v119
	v_lshl_add_u64 v[132:133], v[132:133], 0, v[164:165]
	v_mul_f32_e32 v116, v116, v118
	v_mul_f32_e32 v118, 0xbfb8aa3b, v123
	v_exp_f32_e32 v118, v118
	v_add_f32_e32 v119, 1.0, v119
	v_rcp_f32_e32 v119, v119
	v_add_f32_e32 v118, 1.0, v118
	v_rcp_f32_e32 v118, v118
	s_nop 0
	v_mul_f32_e32 v117, v117, v118
	v_mul_f32_e32 v118, 0xbfb8aa3b, v124
	v_exp_f32_e32 v118, v118
	v_cvt_pk_bf16_f32 v116, v116, v117
	v_mul_f32_e32 v117, v124, v134
	v_add_f32_e32 v118, 1.0, v118
	v_rcp_f32_e32 v118, v118
	s_nop 0
	v_mul_f32_e32 v117, v117, v118
	v_mul_f32_e32 v118, v125, v135
	v_mul_f32_e32 v118, v118, v119
	v_cvt_pk_bf16_f32 v117, v117, v118
	global_store_dwordx4 v[132:133], v[114:117], off
	ds_bpermute_b32 v114, v180, v183 offset:128
	s_nop 0
	v_or_b32_e32 v115, 32, v181
	v_mad_i64_i32 v[116:117], s[2:3], v115, s49, v[162:163]
	s_waitcnt lgkmcnt(0)
	v_pk_fma_f32 v[110:111], v[110:111], v[114:115], v[78:79] op_sel_hi:[1,0,1]
	v_pk_fma_f32 v[102:103], v[102:103], v[114:115], v[70:71] op_sel_hi:[1,0,1]
	v_pk_fma_f32 v[118:119], v[100:101], v[114:115], v[68:69] op_sel_hi:[1,0,1]
	v_pk_fma_f32 v[100:101], v[98:99], v[114:115], v[66:67] op_sel_hi:[1,0,1]
	v_mul_f32_e32 v99, 0xbfb8aa3b, v110
	v_mul_f32_e32 v98, v110, v102
	v_exp_f32_e32 v99, v99
	v_mul_f32_e32 v102, 0xbfb8aa3b, v111
	v_exp_f32_e32 v102, v102
	v_pk_fma_f32 v[112:113], v[112:113], v[114:115], v[80:81] op_sel_hi:[1,0,1]
	v_add_f32_e32 v99, 1.0, v99
	v_rcp_f32_e32 v99, v99
	v_add_f32_e32 v102, 1.0, v102
	v_rcp_f32_e32 v102, v102
	v_pk_fma_f32 v[104:105], v[104:105], v[114:115], v[72:73] op_sel_hi:[1,0,1]
	v_mul_f32_e32 v98, v98, v99
	v_mul_f32_e32 v99, v111, v103
	v_mul_f32_e32 v99, v99, v102
	v_mul_f32_e32 v102, 0xbfb8aa3b, v112
	v_exp_f32_e32 v102, v102
	v_mul_f32_e32 v103, 0xbfb8aa3b, v113
	v_exp_f32_e32 v103, v103
	v_cvt_pk_bf16_f32 v98, v98, v99
	v_add_f32_e32 v102, 1.0, v102
	v_rcp_f32_e32 v102, v102
	v_add_f32_e32 v103, 1.0, v103
	v_rcp_f32_e32 v103, v103
	v_mul_f32_e32 v99, v112, v104
	v_mul_f32_e32 v99, v99, v102
	v_mul_f32_e32 v102, v113, v105
	v_pk_fma_f32 v[106:107], v[106:107], v[114:115], v[74:75] op_sel_hi:[1,0,1]
	v_mul_f32_e32 v102, v102, v103
	v_cvt_pk_bf16_f32 v99, v99, v102
	v_mul_f32_e32 v102, 0xbfb8aa3b, v106
	v_exp_f32_e32 v102, v102
	v_mul_f32_e32 v100, v106, v100
	v_pk_fma_f32 v[108:109], v[108:109], v[114:115], v[76:77] op_sel_hi:[1,0,1]
	v_mul_f32_e32 v101, v107, v101
	v_add_f32_e32 v102, 1.0, v102
	v_rcp_f32_e32 v102, v102
	v_mul_f32_e32 v103, 0xbfb8aa3b, v109
	v_exp_f32_e32 v103, v103
	v_lshl_add_u64 v[116:117], v[116:117], 0, v[164:165]
	v_mul_f32_e32 v100, v100, v102
	v_mul_f32_e32 v102, 0xbfb8aa3b, v107
	v_exp_f32_e32 v102, v102
	v_add_f32_e32 v103, 1.0, v103
	v_rcp_f32_e32 v103, v103
	v_add_f32_e32 v102, 1.0, v102
	v_rcp_f32_e32 v102, v102
	s_nop 0
	v_mul_f32_e32 v101, v101, v102
	v_mul_f32_e32 v102, 0xbfb8aa3b, v108
	v_exp_f32_e32 v102, v102
	v_cvt_pk_bf16_f32 v100, v100, v101
	v_mul_f32_e32 v101, v108, v118
	v_add_f32_e32 v102, 1.0, v102
	v_rcp_f32_e32 v102, v102
	s_nop 0
	v_mul_f32_e32 v101, v101, v102
	v_mul_f32_e32 v102, v109, v119
	v_mul_f32_e32 v102, v102, v103
	v_cvt_pk_bf16_f32 v101, v101, v102
	global_store_dwordx4 v[116:117], v[98:101], off
	ds_bpermute_b32 v98, v180, v183 offset:192
	s_nop 0
	v_or_b32_e32 v99, 48, v181
	v_mad_i64_i32 v[100:101], s[2:3], v99, s49, v[162:163]
	s_waitcnt lgkmcnt(0)
; __device__ __forceinline__ unsigned cvt_pk_bf16(float lo, float hi) { unsigned r; asm volatile("v_cvt_pk_bf16_f32 %0, %1, %2" : "=v"(r) : "v"(lo), "v"(hi)); return r; }
; __device__ __forceinline__ float row_rstd(const float* ss, int row) { return 1.0f / sqrtf(ss[row] * (1.0f / DM) + 1e-6f); }
; __device__ __forceinline__ float silu_mul(float a, float b) { return a * b * __builtin_amdgcn_rcpf(1.0f + __builtin_amdgcn_exp2f(-a * LOG2E)); }
;     __device__ __forceinline__ void operator()(const f32x4 (&acc)[2][2][4][2], const Unit& u, int wr, int wc, int fr, int fq) const {
;     ...
;         const float rsl0 = row_rstd(ss, u.pm * BM + wr * 64 + lane), rsl1 = row_rstd(ss, u.pm * BM + HALF + wr * 64 + lane);
;     ...
;             for (int m = 0; m < 4; ++m) { const int row = row0 + ai * HALF + m * 16; const float rs = __shfl(ai ? rsl1 : rsl0, m * 16 + fr); bf16_t* rowp = O + (size_t)row * DFF + col0;
;                 const f32x4 a0 = acc[ai][0][m][0] * rs + ba0, a1 = acc[ai][0][m][1] * rs + ba1, b0 = acc[ai][1][m][0] * rs + bb0, b1 = acc[ai][1][m][1] * rs + bb1;
;                 u32x4 w; w.x = cvt_pk_bf16(silu_mul(a0[0], b0[0]), silu_mul(a0[1], b0[1])); w.y = cvt_pk_bf16(silu_mul(a0[2], b0[2]), silu_mul(a0[3], b0[3]));
;                 w.z = cvt_pk_bf16(silu_mul(a1[0], b1[0]), silu_mul(a1[1], b1[1])); w.w = cvt_pk_bf16(silu_mul(a1[2], b1[2]), silu_mul(a1[3], b1[3]));
;                 *(u32x4*)rowp = w; }
	v_pk_fma_f32 v[94:95], v[94:95], v[98:99], v[78:79] op_sel_hi:[1,0,1]
	v_pk_fma_f32 v[86:87], v[86:87], v[98:99], v[70:71] op_sel_hi:[1,0,1]
	v_pk_fma_f32 v[102:103], v[84:85], v[98:99], v[68:69] op_sel_hi:[1,0,1]
	v_pk_fma_f32 v[84:85], v[82:83], v[98:99], v[66:67] op_sel_hi:[1,0,1]
	v_mul_f32_e32 v83, 0xbfb8aa3b, v94
	v_mul_f32_e32 v82, v94, v86
	v_exp_f32_e32 v83, v83
	v_mul_f32_e32 v86, 0xbfb8aa3b, v95
	v_exp_f32_e32 v86, v86
	v_pk_fma_f32 v[96:97], v[96:97], v[98:99], v[80:81] op_sel_hi:[1,0,1]
	v_add_f32_e32 v83, 1.0, v83
	v_rcp_f32_e32 v83, v83
	v_add_f32_e32 v86, 1.0, v86
	v_rcp_f32_e32 v86, v86
	v_pk_fma_f32 v[88:89], v[88:89], v[98:99], v[72:73] op_sel_hi:[1,0,1]
	v_mul_f32_e32 v82, v82, v83
	v_mul_f32_e32 v83, v95, v87
	v_mul_f32_e32 v83, v83, v86
	v_mul_f32_e32 v86, 0xbfb8aa3b, v96
	v_exp_f32_e32 v86, v86
	v_mul_f32_e32 v87, 0xbfb8aa3b, v97
	v_exp_f32_e32 v87, v87
	v_cvt_pk_bf16_f32 v82, v82, v83
	v_add_f32_e32 v86, 1.0, v86
	v_rcp_f32_e32 v86, v86
	v_add_f32_e32 v87, 1.0, v87
	v_rcp_f32_e32 v87, v87
	v_mul_f32_e32 v83, v96, v88
	v_mul_f32_e32 v83, v83, v86
	v_mul_f32_e32 v86, v97, v89
	v_pk_fma_f32 v[90:91], v[90:91], v[98:99], v[74:75] op_sel_hi:[1,0,1]
	v_mul_f32_e32 v86, v86, v87
	v_cvt_pk_bf16_f32 v83, v83, v86
	v_mul_f32_e32 v86, 0xbfb8aa3b, v90
	v_exp_f32_e32 v86, v86
	v_mul_f32_e32 v84, v90, v84
	v_pk_fma_f32 v[92:93], v[92:93], v[98:99], v[76:77] op_sel_hi:[1,0,1]
	v_mul_f32_e32 v85, v91, v85
	v_add_f32_e32 v86, 1.0, v86
	v_rcp_f32_e32 v86, v86
	v_mul_f32_e32 v87, 0xbfb8aa3b, v93
	v_exp_f32_e32 v87, v87
	v_lshl_add_u64 v[100:101], v[100:101], 0, v[164:165]
	v_mul_f32_e32 v84, v84, v86
	v_mul_f32_e32 v86, 0xbfb8aa3b, v91
	v_exp_f32_e32 v86, v86
	v_add_f32_e32 v87, 1.0, v87
	v_rcp_f32_e32 v87, v87
	v_add_f32_e32 v86, 1.0, v86
	v_rcp_f32_e32 v86, v86
	s_nop 0
	v_mul_f32_e32 v85, v85, v86
	v_mul_f32_e32 v86, 0xbfb8aa3b, v92
	v_exp_f32_e32 v86, v86
	v_cvt_pk_bf16_f32 v84, v84, v85
	v_mul_f32_e32 v85, v92, v102
	v_add_f32_e32 v86, 1.0, v86
	v_rcp_f32_e32 v86, v86
	s_nop 0
	v_mul_f32_e32 v85, v85, v86
	v_mul_f32_e32 v86, v93, v103
	v_mul_f32_e32 v86, v86, v87
	v_cvt_pk_bf16_f32 v85, v85, v86
	global_store_dwordx4 v[100:101], v[82:85], off
	s_nop 1
	v_div_scale_f32 v82, s[2:3], v182, v182, 1.0
	v_rcp_f32_e32 v84, v82
	v_add_u32_e32 v83, 0x80, v181
	v_fma_f32 v85, -v82, v84, 1.0
	v_fmac_f32_e32 v84, v85, v84
	v_div_scale_f32 v85, vcc, 1.0, v182, 1.0
	v_mul_f32_e32 v86, v85, v84
	v_fma_f32 v87, -v82, v86, v85
	v_fmac_f32_e32 v86, v87, v84
	v_fma_f32 v82, -v82, v86, v85
	v_div_fmas_f32 v82, v82, v84, v86
	v_div_fixup_f32 v82, v82, v182, 1.0
	ds_bpermute_b32 v84, v180, v82
	v_mad_i64_i32 v[86:87], s[2:3], v83, s49, v[162:163]
	v_lshl_add_u64 v[86:87], v[86:87], 0, v[164:165]
	s_andn2_b64 vcc, exec, s[38:39]
	s_waitcnt lgkmcnt(0)
	v_pk_fma_f32 v[62:63], v[62:63], v[84:85], v[78:79] op_sel_hi:[1,0,1]
	v_pk_fma_f32 v[54:55], v[54:55], v[84:85], v[70:71] op_sel_hi:[1,0,1]
	v_pk_fma_f32 v[88:89], v[52:53], v[84:85], v[68:69] op_sel_hi:[1,0,1]
	v_pk_fma_f32 v[52:53], v[50:51], v[84:85], v[66:67] op_sel_hi:[1,0,1]
	v_mul_f32_e32 v51, 0xbfb8aa3b, v62
	v_mul_f32_e32 v50, v62, v54
	v_exp_f32_e32 v51, v51
	v_mul_f32_e32 v54, 0xbfb8aa3b, v63
	v_exp_f32_e32 v54, v54
	v_pk_fma_f32 v[64:65], v[64:65], v[84:85], v[80:81] op_sel_hi:[1,0,1]
	v_add_f32_e32 v51, 1.0, v51
	v_rcp_f32_e32 v51, v51
	v_add_f32_e32 v54, 1.0, v54
	v_rcp_f32_e32 v54, v54
	v_pk_fma_f32 v[56:57], v[56:57], v[84:85], v[72:73] op_sel_hi:[1,0,1]
	v_mul_f32_e32 v50, v50, v51
	v_mul_f32_e32 v51, v63, v55
	v_mul_f32_e32 v51, v51, v54
	v_mul_f32_e32 v54, 0xbfb8aa3b, v64
	v_exp_f32_e32 v54, v54
	v_mul_f32_e32 v55, 0xbfb8aa3b, v65
	v_exp_f32_e32 v55, v55
	v_cvt_pk_bf16_f32 v50, v50, v51
	v_add_f32_e32 v54, 1.0, v54
	v_rcp_f32_e32 v54, v54
	v_add_f32_e32 v55, 1.0, v55
	v_rcp_f32_e32 v55, v55
	v_mul_f32_e32 v51, v64, v56
	v_mul_f32_e32 v51, v51, v54
	v_mul_f32_e32 v54, v65, v57
	v_pk_fma_f32 v[58:59], v[58:59], v[84:85], v[74:75] op_sel_hi:[1,0,1]
	v_mul_f32_e32 v54, v54, v55
	v_cvt_pk_bf16_f32 v51, v51, v54
	v_mul_f32_e32 v54, 0xbfb8aa3b, v58
	v_exp_f32_e32 v54, v54
	v_mul_f32_e32 v52, v58, v52
	v_pk_fma_f32 v[60:61], v[60:61], v[84:85], v[76:77] op_sel_hi:[1,0,1]
	v_mul_f32_e32 v53, v59, v53
	v_add_f32_e32 v54, 1.0, v54
	v_rcp_f32_e32 v54, v54
	v_mul_f32_e32 v55, 0xbfb8aa3b, v61
	v_exp_f32_e32 v55, v55
	v_mul_f32_e32 v52, v52, v54
	v_mul_f32_e32 v54, 0xbfb8aa3b, v59
	v_exp_f32_e32 v54, v54
	v_add_f32_e32 v55, 1.0, v55
	v_rcp_f32_e32 v55, v55
	v_add_f32_e32 v54, 1.0, v54
	v_rcp_f32_e32 v54, v54
	s_nop 0
	v_mul_f32_e32 v53, v53, v54
	v_mul_f32_e32 v54, 0xbfb8aa3b, v60
	v_exp_f32_e32 v54, v54
	v_cvt_pk_bf16_f32 v52, v52, v53
	v_mul_f32_e32 v53, v60, v88
	v_add_f32_e32 v54, 1.0, v54
	v_rcp_f32_e32 v54, v54
	s_nop 0
	v_mul_f32_e32 v53, v53, v54
	v_mul_f32_e32 v54, v61, v89
	v_mul_f32_e32 v54, v54, v55
	v_cvt_pk_bf16_f32 v53, v53, v54
	global_store_dwordx4 v[86:87], v[50:53], off
	ds_bpermute_b32 v50, v180, v82 offset:64
	s_nop 0
	v_add_u32_e32 v51, 0x90, v181
	v_mad_i64_i32 v[52:53], s[2:3], v51, s49, v[162:163]
	s_waitcnt lgkmcnt(0)
; __device__ __forceinline__ unsigned cvt_pk_bf16(float lo, float hi) { unsigned r; asm volatile("v_cvt_pk_bf16_f32 %0, %1, %2" : "=v"(r) : "v"(lo), "v"(hi)); return r; }
; __device__ __forceinline__ float silu_mul(float a, float b) { return a * b * __builtin_amdgcn_rcpf(1.0f + __builtin_amdgcn_exp2f(-a * LOG2E)); }
; #define PG8_BAR __builtin_amdgcn_s_barrier()
;     __device__ __forceinline__ void operator()(const f32x4 (&acc)[2][2][4][2], const Unit& u, int wr, int wc, int fr, int fq) const {
;     ...
;             for (int m = 0; m < 4; ++m) { const int row = row0 + ai * HALF + m * 16; const float rs = __shfl(ai ? rsl1 : rsl0, m * 16 + fr); bf16_t* rowp = O + (size_t)row * DFF + col0;
;                 const f32x4 a0 = acc[ai][0][m][0] * rs + ba0, a1 = acc[ai][0][m][1] * rs + ba1, b0 = acc[ai][1][m][0] * rs + bb0, b1 = acc[ai][1][m][1] * rs + bb1;
;                 u32x4 w; w.x = cvt_pk_bf16(silu_mul(a0[0], b0[0]), silu_mul(a0[1], b0[1])); w.y = cvt_pk_bf16(silu_mul(a0[2], b0[2]), silu_mul(a0[3], b0[3]));
;                 w.z = cvt_pk_bf16(silu_mul(a1[0], b1[0]), silu_mul(a1[1], b1[1])); w.w = cvt_pk_bf16(silu_mul(a1[2], b1[2]), silu_mul(a1[3], b1[3]));
;                 *(u32x4*)rowp = w; }
; template <class Epi, class Sched, bool ALIGN_EPI = false, bool SP2 = false>
; __device__ __forceinline__ void gemm_phase(LAS unsigned char* lds, const Gemm g, const Sched& S, const Epi& E) {
;     ...
;         if (!has_next) break;
; #pragma unroll
;         for (int a = 0; a < 2; ++a)
; #pragma unroll
;             for (int b = 0; b < 2; ++b)
; #pragma unroll
;                 for (int m = 0; m < 4; ++m)
; #pragma unroll
;                     for (int n = 0; n < 2; ++n) acc[a][b][m][n] = (f32x4){0.f, 0.f, 0.f, 0.f};
;         cur = nxt; cA = nA; cB = nB; ++ui;
;         if constexpr (ALIGN_EPI) { if (wr == 1) PG8_BAR; }
	v_pk_fma_f32 v[46:47], v[46:47], v[50:51], v[78:79] op_sel_hi:[1,0,1]
	v_pk_fma_f32 v[38:39], v[38:39], v[50:51], v[70:71] op_sel_hi:[1,0,1]
	v_pk_fma_f32 v[54:55], v[36:37], v[50:51], v[68:69] op_sel_hi:[1,0,1]
	v_pk_fma_f32 v[36:37], v[34:35], v[50:51], v[66:67] op_sel_hi:[1,0,1]
	v_mul_f32_e32 v35, 0xbfb8aa3b, v46
	v_mul_f32_e32 v34, v46, v38
	v_exp_f32_e32 v35, v35
	v_mul_f32_e32 v38, 0xbfb8aa3b, v47
	v_exp_f32_e32 v38, v38
	v_pk_fma_f32 v[48:49], v[48:49], v[50:51], v[80:81] op_sel_hi:[1,0,1]
	v_add_f32_e32 v35, 1.0, v35
	v_rcp_f32_e32 v35, v35
	v_add_f32_e32 v38, 1.0, v38
	v_rcp_f32_e32 v38, v38
	v_pk_fma_f32 v[40:41], v[40:41], v[50:51], v[72:73] op_sel_hi:[1,0,1]
	v_mul_f32_e32 v34, v34, v35
	v_mul_f32_e32 v35, v47, v39
	v_mul_f32_e32 v35, v35, v38
	v_mul_f32_e32 v38, 0xbfb8aa3b, v48
	v_exp_f32_e32 v38, v38
	v_mul_f32_e32 v39, 0xbfb8aa3b, v49
	v_exp_f32_e32 v39, v39
	v_cvt_pk_bf16_f32 v34, v34, v35
	v_add_f32_e32 v38, 1.0, v38
	v_rcp_f32_e32 v38, v38
	v_add_f32_e32 v39, 1.0, v39
	v_rcp_f32_e32 v39, v39
	v_mul_f32_e32 v35, v48, v40
	v_mul_f32_e32 v35, v35, v38
	v_mul_f32_e32 v38, v49, v41
	v_pk_fma_f32 v[42:43], v[42:43], v[50:51], v[74:75] op_sel_hi:[1,0,1]
	v_mul_f32_e32 v38, v38, v39
	v_cvt_pk_bf16_f32 v35, v35, v38
	v_mul_f32_e32 v38, 0xbfb8aa3b, v42
	v_exp_f32_e32 v38, v38
	v_mul_f32_e32 v36, v42, v36
	v_pk_fma_f32 v[44:45], v[44:45], v[50:51], v[76:77] op_sel_hi:[1,0,1]
	v_mul_f32_e32 v37, v43, v37
	v_add_f32_e32 v38, 1.0, v38
	v_rcp_f32_e32 v38, v38
	v_mul_f32_e32 v39, 0xbfb8aa3b, v45
	v_exp_f32_e32 v39, v39
	v_lshl_add_u64 v[52:53], v[52:53], 0, v[164:165]
	v_mul_f32_e32 v36, v36, v38
	v_mul_f32_e32 v38, 0xbfb8aa3b, v43
	v_exp_f32_e32 v38, v38
	v_add_f32_e32 v39, 1.0, v39
	v_rcp_f32_e32 v39, v39
	v_add_f32_e32 v38, 1.0, v38
	v_rcp_f32_e32 v38, v38
	s_nop 0
	v_mul_f32_e32 v37, v37, v38
	v_mul_f32_e32 v38, 0xbfb8aa3b, v44
	v_exp_f32_e32 v38, v38
	v_cvt_pk_bf16_f32 v36, v36, v37
	v_mul_f32_e32 v37, v44, v54
	v_add_f32_e32 v38, 1.0, v38
	v_rcp_f32_e32 v38, v38
	s_nop 0
	v_mul_f32_e32 v37, v37, v38
	v_mul_f32_e32 v38, v45, v55
	v_mul_f32_e32 v38, v38, v39
	v_cvt_pk_bf16_f32 v37, v37, v38
	global_store_dwordx4 v[52:53], v[34:37], off
	ds_bpermute_b32 v34, v180, v82 offset:128
	s_nop 0
	v_add_u32_e32 v35, 0xa0, v181
	v_mad_i64_i32 v[36:37], s[2:3], v35, s49, v[162:163]
	s_waitcnt lgkmcnt(0)
	v_pk_fma_f32 v[30:31], v[30:31], v[34:35], v[78:79] op_sel_hi:[1,0,1]
	v_pk_fma_f32 v[22:23], v[22:23], v[34:35], v[70:71] op_sel_hi:[1,0,1]
	v_pk_fma_f32 v[38:39], v[20:21], v[34:35], v[68:69] op_sel_hi:[1,0,1]
	v_pk_fma_f32 v[20:21], v[18:19], v[34:35], v[66:67] op_sel_hi:[1,0,1]
	v_mul_f32_e32 v19, 0xbfb8aa3b, v30
	v_mul_f32_e32 v18, v30, v22
	v_exp_f32_e32 v19, v19
	v_mul_f32_e32 v22, 0xbfb8aa3b, v31
	v_exp_f32_e32 v22, v22
	v_pk_fma_f32 v[32:33], v[32:33], v[34:35], v[80:81] op_sel_hi:[1,0,1]
	v_add_f32_e32 v19, 1.0, v19
	v_rcp_f32_e32 v19, v19
	v_add_f32_e32 v22, 1.0, v22
	v_rcp_f32_e32 v22, v22
	v_pk_fma_f32 v[24:25], v[24:25], v[34:35], v[72:73] op_sel_hi:[1,0,1]
	v_mul_f32_e32 v18, v18, v19
	v_mul_f32_e32 v19, v31, v23
	v_mul_f32_e32 v19, v19, v22
	v_mul_f32_e32 v22, 0xbfb8aa3b, v32
	v_exp_f32_e32 v22, v22
	v_mul_f32_e32 v23, 0xbfb8aa3b, v33
	v_exp_f32_e32 v23, v23
	v_cvt_pk_bf16_f32 v18, v18, v19
	v_add_f32_e32 v22, 1.0, v22
	v_rcp_f32_e32 v22, v22
	v_add_f32_e32 v23, 1.0, v23
	v_rcp_f32_e32 v23, v23
	v_mul_f32_e32 v19, v32, v24
	v_mul_f32_e32 v19, v19, v22
	v_mul_f32_e32 v22, v33, v25
	v_pk_fma_f32 v[26:27], v[26:27], v[34:35], v[74:75] op_sel_hi:[1,0,1]
	v_mul_f32_e32 v22, v22, v23
	v_cvt_pk_bf16_f32 v19, v19, v22
	v_mul_f32_e32 v22, 0xbfb8aa3b, v26
	v_exp_f32_e32 v22, v22
	v_mul_f32_e32 v20, v26, v20
	v_pk_fma_f32 v[28:29], v[28:29], v[34:35], v[76:77] op_sel_hi:[1,0,1]
	v_mul_f32_e32 v21, v27, v21
	v_add_f32_e32 v22, 1.0, v22
	v_rcp_f32_e32 v22, v22
	v_mul_f32_e32 v23, 0xbfb8aa3b, v29
	v_exp_f32_e32 v23, v23
	v_lshl_add_u64 v[36:37], v[36:37], 0, v[164:165]
	v_mul_f32_e32 v20, v20, v22
	v_mul_f32_e32 v22, 0xbfb8aa3b, v27
	v_exp_f32_e32 v22, v22
	v_add_f32_e32 v23, 1.0, v23
	v_rcp_f32_e32 v23, v23
	v_add_f32_e32 v22, 1.0, v22
	v_rcp_f32_e32 v22, v22
	s_nop 0
	v_mul_f32_e32 v21, v21, v22
	v_mul_f32_e32 v22, 0xbfb8aa3b, v28
	v_exp_f32_e32 v22, v22
	v_cvt_pk_bf16_f32 v20, v20, v21
	v_mul_f32_e32 v21, v28, v38
	v_add_f32_e32 v22, 1.0, v22
	v_rcp_f32_e32 v22, v22
	s_nop 0
	v_mul_f32_e32 v21, v21, v22
	v_mul_f32_e32 v22, v29, v39
	v_mul_f32_e32 v22, v22, v23
	v_cvt_pk_bf16_f32 v21, v21, v22
	global_store_dwordx4 v[36:37], v[18:21], off
	ds_bpermute_b32 v18, v180, v82 offset:192
	s_nop 0
	v_add_u32_e32 v19, 0xb0, v181
	v_mad_i64_i32 v[20:21], s[2:3], v19, s49, v[162:163]
	s_waitcnt lgkmcnt(0)
	v_pk_fma_f32 v[14:15], v[14:15], v[18:19], v[78:79] op_sel_hi:[1,0,1]
	v_pk_fma_f32 v[6:7], v[6:7], v[18:19], v[70:71] op_sel_hi:[1,0,1]
	v_pk_fma_f32 v[22:23], v[4:5], v[18:19], v[68:69] op_sel_hi:[1,0,1]
	v_pk_fma_f32 v[4:5], v[2:3], v[18:19], v[66:67] op_sel_hi:[1,0,1]
	v_mul_f32_e32 v3, 0xbfb8aa3b, v14
	v_mul_f32_e32 v2, v14, v6
	v_exp_f32_e32 v3, v3
	v_mul_f32_e32 v6, 0xbfb8aa3b, v15
	v_exp_f32_e32 v6, v6
	v_pk_fma_f32 v[16:17], v[16:17], v[18:19], v[80:81] op_sel_hi:[1,0,1]
	v_add_f32_e32 v3, 1.0, v3
	v_rcp_f32_e32 v3, v3
	v_add_f32_e32 v6, 1.0, v6
	v_rcp_f32_e32 v6, v6
	v_pk_fma_f32 v[8:9], v[8:9], v[18:19], v[72:73] op_sel_hi:[1,0,1]
	v_mul_f32_e32 v2, v2, v3
	v_mul_f32_e32 v3, v15, v7
	v_mul_f32_e32 v3, v3, v6
	v_mul_f32_e32 v6, 0xbfb8aa3b, v16
	v_exp_f32_e32 v6, v6
	v_mul_f32_e32 v7, 0xbfb8aa3b, v17
	v_exp_f32_e32 v7, v7
	v_cvt_pk_bf16_f32 v2, v2, v3
	v_add_f32_e32 v6, 1.0, v6
	v_rcp_f32_e32 v6, v6
	v_add_f32_e32 v7, 1.0, v7
	v_rcp_f32_e32 v7, v7
	v_mul_f32_e32 v3, v16, v8
	v_mul_f32_e32 v3, v3, v6
	v_mul_f32_e32 v6, v17, v9
	v_pk_fma_f32 v[10:11], v[10:11], v[18:19], v[74:75] op_sel_hi:[1,0,1]
	v_mul_f32_e32 v6, v6, v7
	v_cvt_pk_bf16_f32 v3, v3, v6
	v_mul_f32_e32 v6, 0xbfb8aa3b, v10
	v_exp_f32_e32 v6, v6
	v_mul_f32_e32 v4, v10, v4
	v_pk_fma_f32 v[12:13], v[12:13], v[18:19], v[76:77] op_sel_hi:[1,0,1]
	v_mul_f32_e32 v5, v11, v5
	v_add_f32_e32 v6, 1.0, v6
	v_rcp_f32_e32 v6, v6
	v_mul_f32_e32 v7, 0xbfb8aa3b, v13
	v_exp_f32_e32 v7, v7
	v_lshl_add_u64 v[20:21], v[20:21], 0, v[164:165]
	v_mul_f32_e32 v4, v4, v6
	v_mul_f32_e32 v6, 0xbfb8aa3b, v11
	v_exp_f32_e32 v6, v6
	v_add_f32_e32 v7, 1.0, v7
	v_rcp_f32_e32 v7, v7
	s_mov_b64 s[2:3], -1
	v_add_f32_e32 v6, 1.0, v6
	v_rcp_f32_e32 v6, v6
	s_nop 0
	v_mul_f32_e32 v5, v5, v6
	v_mul_f32_e32 v6, 0xbfb8aa3b, v12
	v_exp_f32_e32 v6, v6
	v_cvt_pk_bf16_f32 v4, v4, v5
	v_mul_f32_e32 v5, v12, v22
	v_add_f32_e32 v6, 1.0, v6
	v_rcp_f32_e32 v6, v6
	s_nop 0
	v_mul_f32_e32 v5, v5, v6
	v_mul_f32_e32 v6, v13, v23
	v_mul_f32_e32 v6, v6, v7
	v_cvt_pk_bf16_f32 v5, v5, v6
	global_store_dwordx4 v[20:21], v[2:5], off
	s_cbranch_vccnz .LBB0_1461
	s_andn2_b64 vcc, exec, s[4:5]
	s_cbranch_vccnz .LBB0_1460
	s_barrier
	s_branch .LBB0_1460

; #define PG8_BAR __builtin_amdgcn_s_barrier()
; template <class Epi, class Sched, bool ALIGN_EPI = false, bool SP2 = false>
; __device__ __forceinline__ void gemm_phase(LAS unsigned char* lds, const Gemm g, const Sched& S, const Epi& E) {
;     ...
;         const bool has_next = S.next(ui + 1, nxt);
;         const char* nA = has_next ? (const char*)g.A + (size_t)nxt.pm * tstep + nxt.koff : cA; const char* nB = has_next ? (const char*)g.Bt + (size_t)nxt.pn * tstep + nxt.koff : cB;
;         for (int t = 0; t < nt; t += 2) {
;             const bool last = (t == nt - 2);
;             const char* a1 = cA + (size_t)(t + 1) * kstep;
;             const char* a2 = last ? nA : cA + (size_t)(t + 2) * kstep; const char* b2 = last ? nB : cB + (size_t)(t + 2) * kstep;
;             const char* a3 = a2 + kstep; const char* b3 = b2 + kstep;
;             if (last && has_next) S.a_ready(nxt);
;             if constexpr (SP2) {
;             PG8_LDB(B0, 0, 0); PG8_LDB(B1, 0, 1); PG8_SCHED; PG8_LDA(At, 0, 0); PG8_STAGE(PG8_SA(1, 1), a1 + hstep, voffA);
;             PG8_WAIT_V(8); PG8_WAIT_L(0); PG8_BAR; PG8_MMA(0, 0, At, B0); PG8_MMA(0, 1, At, B1); PG8_BAR; PG8_SCHED;
;             PG8_LDA(At, 0, 1); PG8_STAGE(PG8_SB(0, 0), b2, voffB); PG8_STAGE(PG8_SB(0, 1), b2 + hstepB, voffB); PG8_STAGE(PG8_SA(0, 0), a2, voffA);
;             PG8_WAIT_V(8); PG8_WAIT_L(0); PG8_BAR; PG8_MMA(1, 0, At, B0); PG8_MMA(1, 1, At, B1); PG8_BAR; PG8_SCHED;
;             PG8_LDB(B0, 1, 0); PG8_LDB(B1, 1, 1); PG8_SCHED; PG8_LDA(At, 1, 0); PG8_STAGE(PG8_SA(0, 1), a2 + hstep, voffA);
;             PG8_WAIT_V(8); PG8_WAIT_L(0); PG8_BAR; PG8_MMA(0, 0, At, B0); PG8_MMA(0, 1, At, B1); PG8_BAR; PG8_SCHED;
;             PG8_LDA(At, 1, 1); PG8_STAGE(PG8_SB(1, 0), b3, voffB); PG8_STAGE(PG8_SB(1, 1), b3 + hstepB, voffB); PG8_STAGE(PG8_SA(1, 0), a3, voffA);
;             PG8_WAIT_V(8); PG8_WAIT_L(0); PG8_BAR; PG8_MMA(1, 0, At, B0); PG8_MMA(1, 1, At, B1); PG8_BAR; PG8_SCHED;
;             } else {
;             PG8_LDB(B0, 0, 0); PG8_SCHED; PG8_LDA(At, 0, 0); PG8_STAGE(PG8_SA(1, 1), a1 + hstep, voffA);
;             PG8_WAIT_L(8); PG8_BAR; PG8_WAIT_L(0); PG8_MMA(0, 0, At, B0); PG8_BAR; PG8_SCHED;
;             PG8_LDB(B1, 0, 1); PG8_STAGE(PG8_SB(0, 0), b2, voffB);
;             PG8_BAR; PG8_WAIT_L(0); PG8_MMA(0, 1, At, B1); PG8_BAR;
;             PG8_LDA(At, 0, 1); PG8_STAGE(PG8_SA(0, 0), a2, voffA);
.LBB0_1821:
	s_ashr_i32 s15, s14, 31
	v_cmp_lt_i64_e64 s[38:39], s[18:19], v[158:159]
	s_lshl_b64 s[18:19], s[14:15], 20
	s_add_u32 s18, s93, s18
	s_addc_u32 s19, s92, s19
	s_and_b64 s[20:21], s[38:39], exec
	s_cselect_b32 s3, s19, s23
	s_cselect_b32 s15, s18, s22
	s_ashr_i32 s13, s12, 31
	s_lshl_b64 s[20:21], s[12:13], 20
	s_add_u32 s20, s54, s20
	s_addc_u32 s21, s55, s21
	s_and_b64 s[24:25], s[38:39], exec
	s_cselect_b32 s13, s21, s17
	s_cselect_b32 s24, s20, s16
	s_add_u32 s25, s16, 0x100
	s_addc_u32 s49, s17, 0
	s_add_u32 s16, s22, 0x80080
	v_mov_b32_e32 v2, 0
	s_addc_u32 s17, s23, 0
	s_mov_b32 s50, -2
	v_mov_b32_e32 v3, v2
	v_mov_b32_e32 v4, v2
	v_mov_b32_e32 v5, v2
	v_mov_b32_e32 v6, v2
	v_mov_b32_e32 v7, v2
	v_mov_b32_e32 v8, v2
	v_mov_b32_e32 v9, v2
	v_mov_b32_e32 v18, v2
	v_mov_b32_e32 v19, v2
	v_mov_b32_e32 v20, v2
	v_mov_b32_e32 v21, v2
	v_mov_b32_e32 v22, v2
	v_mov_b32_e32 v23, v2
	v_mov_b32_e32 v24, v2
	v_mov_b32_e32 v25, v2
	v_mov_b32_e32 v34, v2
	v_mov_b32_e32 v35, v2
	v_mov_b32_e32 v36, v2
	v_mov_b32_e32 v37, v2
	v_mov_b32_e32 v38, v2
	v_mov_b32_e32 v39, v2
	v_mov_b32_e32 v40, v2
	v_mov_b32_e32 v41, v2
	v_mov_b32_e32 v50, v2
	v_mov_b32_e32 v51, v2
	v_mov_b32_e32 v52, v2
	v_mov_b32_e32 v53, v2
	v_mov_b32_e32 v54, v2
	v_mov_b32_e32 v55, v2
	v_mov_b32_e32 v56, v2
	v_mov_b32_e32 v57, v2
	v_mov_b32_e32 v10, v2
	v_mov_b32_e32 v11, v2
	v_mov_b32_e32 v12, v2
	v_mov_b32_e32 v13, v2
	v_mov_b32_e32 v14, v2
	v_mov_b32_e32 v15, v2
	v_mov_b32_e32 v16, v2
	v_mov_b32_e32 v17, v2
	v_mov_b32_e32 v26, v2
	v_mov_b32_e32 v27, v2
	v_mov_b32_e32 v28, v2
	v_mov_b32_e32 v29, v2
	v_mov_b32_e32 v30, v2
	v_mov_b32_e32 v31, v2
	v_mov_b32_e32 v32, v2
	v_mov_b32_e32 v33, v2
	v_mov_b32_e32 v42, v2
	v_mov_b32_e32 v43, v2
	v_mov_b32_e32 v44, v2
	v_mov_b32_e32 v45, v2
	v_mov_b32_e32 v46, v2
	v_mov_b32_e32 v47, v2
	v_mov_b32_e32 v48, v2
	v_mov_b32_e32 v49, v2
	v_mov_b32_e32 v58, v2
	v_mov_b32_e32 v59, v2
	v_mov_b32_e32 v60, v2
	v_mov_b32_e32 v61, v2
	v_mov_b32_e32 v62, v2
	v_mov_b32_e32 v63, v2
	v_mov_b32_e32 v64, v2
	v_mov_b32_e32 v65, v2
	v_mov_b32_e32 v82, v2
	v_mov_b32_e32 v83, v2
	v_mov_b32_e32 v84, v2
	v_mov_b32_e32 v85, v2
	v_mov_b32_e32 v86, v2
	v_mov_b32_e32 v87, v2
	v_mov_b32_e32 v88, v2
	v_mov_b32_e32 v89, v2
	s_waitcnt vmcnt(0)
	v_mov_b32_e32 v98, v2
	v_mov_b32_e32 v99, v2
	v_mov_b32_e32 v100, v2
	v_mov_b32_e32 v101, v2
	v_mov_b32_e32 v102, v2
	v_mov_b32_e32 v103, v2
	v_mov_b32_e32 v104, v2
	v_mov_b32_e32 v105, v2
	v_mov_b32_e32 v114, v2
	v_mov_b32_e32 v115, v2
	v_mov_b32_e32 v116, v2
	v_mov_b32_e32 v117, v2
	v_mov_b32_e32 v118, v2
	v_mov_b32_e32 v119, v2
	v_mov_b32_e32 v120, v2
	v_mov_b32_e32 v121, v2
	v_mov_b32_e32 v130, v2
	v_mov_b32_e32 v131, v2
	v_mov_b32_e32 v132, v2
	v_mov_b32_e32 v133, v2
	v_mov_b32_e32 v134, v2
	v_mov_b32_e32 v135, v2
	v_mov_b32_e32 v136, v2
	v_mov_b32_e32 v137, v2
	v_mov_b32_e32 v90, v2
	v_mov_b32_e32 v91, v2
	v_mov_b32_e32 v92, v2
	v_mov_b32_e32 v93, v2
	v_mov_b32_e32 v94, v2
	v_mov_b32_e32 v95, v2
	v_mov_b32_e32 v96, v2
	v_mov_b32_e32 v97, v2
	v_mov_b32_e32 v106, v2
	v_mov_b32_e32 v107, v2
	v_mov_b32_e32 v108, v2
	v_mov_b32_e32 v109, v2
	v_mov_b32_e32 v110, v2
	v_mov_b32_e32 v111, v2
	v_mov_b32_e32 v112, v2
	v_mov_b32_e32 v113, v2
	v_mov_b32_e32 v122, v2
	v_mov_b32_e32 v123, v2
	v_mov_b32_e32 v124, v2
	v_mov_b32_e32 v125, v2
	v_mov_b32_e32 v126, v2
	v_mov_b32_e32 v127, v2
	v_mov_b32_e32 v128, v2
	v_mov_b32_e32 v129, v2
	v_mov_b32_e32 v138, v2
	v_mov_b32_e32 v139, v2
	v_mov_b32_e32 v140, v2
	v_mov_b32_e32 v141, v2
	v_mov_b32_e32 v142, v2
	v_mov_b32_e32 v143, v2
	v_mov_b32_e32 v144, v2
	v_mov_b32_e32 v145, v2
	s_cmpk_gt_i32 s2, 0x7f
	s_mov_b64 s[98:99], 0xb000
	s_cbranch_scc1 .Lpre_up1l1
	s_ashr_i32 s100, s2, 5
	s_mul_hi_i32 s99, s100, 0x2c00
	s_mul_i32 s98, s100, 0x2c00
.Lpre_up1l1:
	s_lshl_b64 s[98:99], s[98:99], 2
	s_add_u32 s98, s36, s98
	s_addc_u32 s99, s37, s99
	s_lshl_b32 s100, s0, 8
	s_ashr_i32 s101, s100, 31
	s_lshl_b64 s[100:101], s[100:101], 2
	s_add_u32 s98, s98, s100
	s_addc_u32 s99, s99, s101
	s_add_u32 s98, s98, s47
	s_addc_u32 s99, s99, 0
	s_lshl_b32 s100, s2, 8
	s_add_i32 s100, s100, s35
	v_or_b32_e32 v162, s100, v170
	v_ashrrev_i32_e32 v163, 31, v162
	v_lshl_add_u64 v[162:163], v[162:163], 2, s[6:7]
	v_add_u32_e32 v164, s100, v171
	v_ashrrev_i32_e32 v165, 31, v164
	v_lshl_add_u64 v[164:165], v[164:165], 2, s[6:7]
	global_load_dwordx4 v[234:237], v176, s[98:99] offset:16
	global_load_dwordx4 v[238:241], v176, s[98:99]
	global_load_dwordx4 v[242:245], v176, s[98:99] offset:528
	global_load_dwordx4 v[246:249], v176, s[98:99] offset:512
	global_load_dword v250, v[162:163], off
	global_load_dword v251, v[164:165], off

; __device__ __forceinline__ unsigned cvt_pk_bf16(float lo, float hi) { unsigned r; asm volatile("v_cvt_pk_bf16_f32 %0, %1, %2" : "=v"(r) : "v"(lo), "v"(hi)); return r; }
; __device__ __forceinline__ float silu_mul(float a, float b) { return a * b * __builtin_amdgcn_rcpf(1.0f + __builtin_amdgcn_exp2f(-a * LOG2E)); }
; __device__ __forceinline__ float row_rstd(const float* ss, int row) { return 1.0f / sqrtf(ss[row] * (1.0f / DM) + 1e-6f); }
;     __device__ __forceinline__ void operator()(const f32x4 (&acc)[2][2][4][2], const Unit& u, int wr, int wc, int fr, int fq) const {
;         const int row0 = u.pm * BM + wr * 64 + fr, col0 = u.pn * HALF + wc * 32 + 8 * fq;
;         const int s = (u.pm < ML / BM) ? (u.pm >> 5) : 4;
;         const float* bp = bias + (size_t)s * BIAS_N + u.pn * BM + wc * 32 + 8 * fq;
;         const f32x4 ba0 = *(const f32x4*)bp, ba1 = *(const f32x4*)(bp + 4), bb0 = *(const f32x4*)(bp + HALF), bb1 = *(const f32x4*)(bp + HALF + 4);
;         const int lane = fq * 16 + fr;
;         const float rsl0 = row_rstd(ss, u.pm * BM + wr * 64 + lane), rsl1 = row_rstd(ss, u.pm * BM + HALF + wr * 64 + lane);
; #pragma unroll
;         for (int ai = 0; ai < 2; ++ai)
; #pragma unroll
;             for (int m = 0; m < 4; ++m) { const int row = row0 + ai * HALF + m * 16; const float rs = __shfl(ai ? rsl1 : rsl0, m * 16 + fr); bf16_t* rowp = O + (size_t)row * DFF + col0;
;                 const f32x4 a0 = acc[ai][0][m][0] * rs + ba0, a1 = acc[ai][0][m][1] * rs + ba1, b0 = acc[ai][1][m][0] * rs + bb0, b1 = acc[ai][1][m][1] * rs + bb1;
;                 u32x4 w; w.x = cvt_pk_bf16(silu_mul(a0[0], b0[0]), silu_mul(a0[1], b0[1])); w.y = cvt_pk_bf16(silu_mul(a0[2], b0[2]), silu_mul(a0[3], b0[3]));
;                 w.z = cvt_pk_bf16(silu_mul(a1[0], b1[0]), silu_mul(a1[1], b1[1])); w.w = cvt_pk_bf16(silu_mul(a1[2], b1[2]), silu_mul(a1[3], b1[3]));
;                 *(u32x4*)rowp = w; }
.LBB0_1827:
	s_lshl_b32 s2, s2, 8
	s_add_i32 s13, s2, s35
	s_lshl_b64 s[2:3], s[16:17], 2
	s_add_u32 s15, s36, s2
	s_addc_u32 s16, s37, s3
	s_lshl_b32 s2, s0, 8
	s_ashr_i32 s3, s2, 31
	s_lshl_b64 s[2:3], s[2:3], 2
	v_lshl_or_b32 v164, s0, 7, v172
	s_add_u32 s0, s15, s2
	s_addc_u32 s3, s16, s3
	v_or_b32_e32 v162, s13, v170
	s_add_u32 s2, s0, s47
	v_ashrrev_i32_e32 v163, 31, v162
	s_addc_u32 s3, s3, 0
	v_lshl_add_u64 v[162:163], v[162:163], 2, s[6:7]
	v_mov_b32_e32 v74, v234
	v_mov_b32_e32 v75, v235
	v_mov_b32_e32 v76, v236
	v_mov_b32_e32 v77, v237
	v_mov_b32_e32 v78, v238
	v_mov_b32_e32 v79, v239
	v_mov_b32_e32 v80, v240
	v_mov_b32_e32 v81, v241
	v_mov_b32_e32 v66, v242
	v_mov_b32_e32 v67, v243
	v_mov_b32_e32 v68, v244
	v_mov_b32_e32 v69, v245
	v_mov_b32_e32 v70, v246
	v_mov_b32_e32 v71, v247
	v_mov_b32_e32 v72, v248
	v_mov_b32_e32 v73, v249
	v_or_b32_e32 v180, s13, v1
	v_mov_b32_e32 v162, v250
	v_fmamk_f32 v162, v162, 0x3a000000, v177
	v_cmp_gt_f32_e32 vcc, s48, v162
	v_mul_f32_e32 v163, 0x4f800000, v162
	s_nop 0
	v_cndmask_b32_e32 v162, v162, v163, vcc
	v_sqrt_f32_e32 v163, v162
	s_nop 0
	v_add_u32_e32 v165, -1, v163
	v_fma_f32 v166, -v165, v163, v162
	v_cmp_ge_f32_e64 s[2:3], 0, v166
	v_add_u32_e32 v166, 1, v163
	s_nop 0
	v_cndmask_b32_e64 v165, v163, v165, s[2:3]
	v_fma_f32 v163, -v166, v163, v162
	v_cmp_lt_f32_e64 s[2:3], 0, v163
	s_nop 1
	v_cndmask_b32_e64 v163, v165, v166, s[2:3]
	v_mul_f32_e32 v165, 0x37800000, v163
	v_cndmask_b32_e32 v163, v163, v165, vcc
	v_cmp_class_f32_e32 vcc, v162, v178
	s_nop 1
	v_cndmask_b32_e32 v166, v163, v162, vcc
	v_add_u32_e32 v162, s13, v171
	v_ashrrev_i32_e32 v163, 31, v162
	v_lshl_add_u64 v[162:163], v[162:163], 2, s[6:7]
	v_mov_b32_e32 v162, v251
	v_fmamk_f32 v162, v162, 0x3a000000, v177
	v_cmp_gt_f32_e32 vcc, s48, v162
	v_mul_f32_e32 v163, 0x4f800000, v162
	s_nop 0
	v_cndmask_b32_e32 v162, v162, v163, vcc
	v_sqrt_f32_e32 v163, v162
	s_nop 0
	v_add_u32_e32 v165, -1, v163
	v_fma_f32 v167, -v165, v163, v162
	v_cmp_ge_f32_e64 s[2:3], 0, v167
	v_add_u32_e32 v167, 1, v163
	s_nop 0
	v_cndmask_b32_e64 v165, v163, v165, s[2:3]
	v_fma_f32 v163, -v167, v163, v162
	v_cmp_lt_f32_e64 s[2:3], 0, v163
	s_nop 1
	v_cndmask_b32_e64 v163, v165, v167, s[2:3]
	v_mul_f32_e32 v165, 0x37800000, v163
	v_cndmask_b32_e32 v163, v163, v165, vcc
	v_cmp_class_f32_e32 vcc, v162, v178
	v_ashrrev_i32_e32 v165, 31, v164
	v_lshlrev_b64 v[164:165], 1, v[164:165]
	v_cndmask_b32_e32 v181, v163, v162, vcc
	v_div_scale_f32 v162, s[2:3], v166, v166, 1.0
	v_rcp_f32_e32 v163, v162
	s_nop 0
	v_fma_f32 v167, -v162, v163, 1.0
	v_fmac_f32_e32 v163, v167, v163
	v_div_scale_f32 v167, vcc, 1.0, v166, 1.0
	v_mul_f32_e32 v168, v167, v163
	v_fma_f32 v182, -v162, v168, v167
	v_fmac_f32_e32 v168, v182, v163
	v_fma_f32 v162, -v162, v168, v167
	v_div_fmas_f32 v162, v162, v163, v168
	v_div_fixup_f32 v182, v162, v166, 1.0
	ds_bpermute_b32 v168, v179, v182
	v_mov_b64_e32 v[162:163], s[96:97]
	v_mad_i64_i32 v[166:167], s[2:3], v180, s46, v[162:163]
	v_lshl_add_u64 v[166:167], v[166:167], 0, v[164:165]
	s_waitcnt lgkmcnt(0)
	v_pk_fma_f32 v[142:143], v[142:143], v[168:169], v[78:79] op_sel_hi:[1,0,1]
	v_pk_fma_f32 v[134:135], v[134:135], v[168:169], v[70:71] op_sel_hi:[1,0,1]
	v_pk_fma_f32 v[184:185], v[132:133], v[168:169], v[68:69] op_sel_hi:[1,0,1]
	v_pk_fma_f32 v[132:133], v[130:131], v[168:169], v[66:67] op_sel_hi:[1,0,1]
	v_mul_f32_e32 v131, 0xbfb8aa3b, v142
	v_mul_f32_e32 v130, v142, v134
	v_exp_f32_e32 v131, v131
	v_mul_f32_e32 v134, 0xbfb8aa3b, v143
	v_exp_f32_e32 v134, v134
	v_pk_fma_f32 v[144:145], v[144:145], v[168:169], v[80:81] op_sel_hi:[1,0,1]
	v_add_f32_e32 v131, 1.0, v131
	v_rcp_f32_e32 v131, v131
	v_add_f32_e32 v134, 1.0, v134
	v_rcp_f32_e32 v134, v134
	v_pk_fma_f32 v[136:137], v[136:137], v[168:169], v[72:73] op_sel_hi:[1,0,1]
	v_mul_f32_e32 v130, v130, v131
	v_mul_f32_e32 v131, v143, v135
	v_mul_f32_e32 v131, v131, v134
	v_mul_f32_e32 v134, 0xbfb8aa3b, v144
	v_exp_f32_e32 v134, v134
	v_mul_f32_e32 v135, 0xbfb8aa3b, v145
	v_exp_f32_e32 v135, v135
	v_cvt_pk_bf16_f32 v130, v130, v131
	v_add_f32_e32 v134, 1.0, v134
	v_rcp_f32_e32 v134, v134
	v_add_f32_e32 v135, 1.0, v135
	v_rcp_f32_e32 v135, v135
	v_mul_f32_e32 v131, v144, v136
	v_mul_f32_e32 v131, v131, v134
	v_mul_f32_e32 v134, v145, v137
	v_pk_fma_f32 v[138:139], v[138:139], v[168:169], v[74:75] op_sel_hi:[1,0,1]
	v_mul_f32_e32 v134, v134, v135
	v_cvt_pk_bf16_f32 v131, v131, v134
	v_mul_f32_e32 v134, 0xbfb8aa3b, v138
	v_exp_f32_e32 v134, v134
	v_mul_f32_e32 v132, v138, v132
	v_pk_fma_f32 v[140:141], v[140:141], v[168:169], v[76:77] op_sel_hi:[1,0,1]
	v_mul_f32_e32 v133, v139, v133
	v_add_f32_e32 v134, 1.0, v134
	v_rcp_f32_e32 v134, v134
	v_mul_f32_e32 v135, 0xbfb8aa3b, v141
	v_exp_f32_e32 v135, v135
	v_mul_f32_e32 v132, v132, v134
	v_mul_f32_e32 v134, 0xbfb8aa3b, v139
	v_exp_f32_e32 v134, v134
	v_add_f32_e32 v135, 1.0, v135
	v_rcp_f32_e32 v135, v135
	v_add_f32_e32 v134, 1.0, v134
	v_rcp_f32_e32 v134, v134
	s_nop 0
	v_mul_f32_e32 v133, v133, v134
	v_mul_f32_e32 v134, 0xbfb8aa3b, v140
	v_exp_f32_e32 v134, v134
	v_cvt_pk_bf16_f32 v132, v132, v133
	v_mul_f32_e32 v133, v140, v184
	v_add_f32_e32 v134, 1.0, v134
	v_rcp_f32_e32 v134, v134
	s_nop 0
	v_mul_f32_e32 v133, v133, v134
	v_mul_f32_e32 v134, v141, v185
	v_mul_f32_e32 v134, v134, v135
	v_cvt_pk_bf16_f32 v133, v133, v134
	global_store_dwordx4 v[166:167], v[130:133], off
	ds_bpermute_b32 v130, v179, v182 offset:64
	s_nop 0
	v_or_b32_e32 v131, 16, v180
	v_mad_i64_i32 v[132:133], s[2:3], v131, s46, v[162:163]
	s_waitcnt lgkmcnt(0)
; __device__ __forceinline__ unsigned cvt_pk_bf16(float lo, float hi) { unsigned r; asm volatile("v_cvt_pk_bf16_f32 %0, %1, %2" : "=v"(r) : "v"(lo), "v"(hi)); return r; }
; __device__ __forceinline__ float silu_mul(float a, float b) { return a * b * __builtin_amdgcn_rcpf(1.0f + __builtin_amdgcn_exp2f(-a * LOG2E)); }
;     __device__ __forceinline__ void operator()(const f32x4 (&acc)[2][2][4][2], const Unit& u, int wr, int wc, int fr, int fq) const {
;     ...
;             for (int m = 0; m < 4; ++m) { const int row = row0 + ai * HALF + m * 16; const float rs = __shfl(ai ? rsl1 : rsl0, m * 16 + fr); bf16_t* rowp = O + (size_t)row * DFF + col0;
;                 const f32x4 a0 = acc[ai][0][m][0] * rs + ba0, a1 = acc[ai][0][m][1] * rs + ba1, b0 = acc[ai][1][m][0] * rs + bb0, b1 = acc[ai][1][m][1] * rs + bb1;
;                 u32x4 w; w.x = cvt_pk_bf16(silu_mul(a0[0], b0[0]), silu_mul(a0[1], b0[1])); w.y = cvt_pk_bf16(silu_mul(a0[2], b0[2]), silu_mul(a0[3], b0[3]));
;                 w.z = cvt_pk_bf16(silu_mul(a1[0], b1[0]), silu_mul(a1[1], b1[1])); w.w = cvt_pk_bf16(silu_mul(a1[2], b1[2]), silu_mul(a1[3], b1[3]));
;                 *(u32x4*)rowp = w; }
	v_pk_fma_f32 v[126:127], v[126:127], v[130:131], v[78:79] op_sel_hi:[1,0,1]
	v_pk_fma_f32 v[118:119], v[118:119], v[130:131], v[70:71] op_sel_hi:[1,0,1]
	v_pk_fma_f32 v[134:135], v[116:117], v[130:131], v[68:69] op_sel_hi:[1,0,1]
	v_pk_fma_f32 v[116:117], v[114:115], v[130:131], v[66:67] op_sel_hi:[1,0,1]
	v_mul_f32_e32 v115, 0xbfb8aa3b, v126
	v_mul_f32_e32 v114, v126, v118
	v_exp_f32_e32 v115, v115
	v_mul_f32_e32 v118, 0xbfb8aa3b, v127
	v_exp_f32_e32 v118, v118
	v_pk_fma_f32 v[128:129], v[128:129], v[130:131], v[80:81] op_sel_hi:[1,0,1]
	v_add_f32_e32 v115, 1.0, v115
	v_rcp_f32_e32 v115, v115
	v_add_f32_e32 v118, 1.0, v118
	v_rcp_f32_e32 v118, v118
	v_pk_fma_f32 v[120:121], v[120:121], v[130:131], v[72:73] op_sel_hi:[1,0,1]
	v_mul_f32_e32 v114, v114, v115
	v_mul_f32_e32 v115, v127, v119
	v_mul_f32_e32 v115, v115, v118
	v_mul_f32_e32 v118, 0xbfb8aa3b, v128
	v_exp_f32_e32 v118, v118
	v_mul_f32_e32 v119, 0xbfb8aa3b, v129
	v_exp_f32_e32 v119, v119
	v_cvt_pk_bf16_f32 v114, v114, v115
	v_add_f32_e32 v118, 1.0, v118
	v_rcp_f32_e32 v118, v118
	v_add_f32_e32 v119, 1.0, v119
	v_rcp_f32_e32 v119, v119
	v_mul_f32_e32 v115, v128, v120
	v_mul_f32_e32 v115, v115, v118
	v_mul_f32_e32 v118, v129, v121
	v_pk_fma_f32 v[122:123], v[122:123], v[130:131], v[74:75] op_sel_hi:[1,0,1]
	v_mul_f32_e32 v118, v118, v119
	v_cvt_pk_bf16_f32 v115, v115, v118
	v_mul_f32_e32 v118, 0xbfb8aa3b, v122
	v_exp_f32_e32 v118, v118
	v_mul_f32_e32 v116, v122, v116
	v_pk_fma_f32 v[124:125], v[124:125], v[130:131], v[76:77] op_sel_hi:[1,0,1]
	v_mul_f32_e32 v117, v123, v117
	v_add_f32_e32 v118, 1.0, v118
	v_rcp_f32_e32 v118, v118
	v_mul_f32_e32 v119, 0xbfb8aa3b, v125
	v_exp_f32_e32 v119, v119
	v_lshl_add_u64 v[132:133], v[132:133], 0, v[164:165]
	v_mul_f32_e32 v116, v116, v118
	v_mul_f32_e32 v118, 0xbfb8aa3b, v123
	v_exp_f32_e32 v118, v118
	v_add_f32_e32 v119, 1.0, v119
	v_rcp_f32_e32 v119, v119
	v_add_f32_e32 v118, 1.0, v118
	v_rcp_f32_e32 v118, v118
	s_nop 0
	v_mul_f32_e32 v117, v117, v118
	v_mul_f32_e32 v118, 0xbfb8aa3b, v124
	v_exp_f32_e32 v118, v118
	v_cvt_pk_bf16_f32 v116, v116, v117
	v_mul_f32_e32 v117, v124, v134
	v_add_f32_e32 v118, 1.0, v118
	v_rcp_f32_e32 v118, v118
	s_nop 0
	v_mul_f32_e32 v117, v117, v118
	v_mul_f32_e32 v118, v125, v135
	v_mul_f32_e32 v118, v118, v119
	v_cvt_pk_bf16_f32 v117, v117, v118
	global_store_dwordx4 v[132:133], v[114:117], off
	ds_bpermute_b32 v114, v179, v182 offset:128
	s_nop 0
	v_or_b32_e32 v115, 32, v180
	v_mad_i64_i32 v[116:117], s[2:3], v115, s46, v[162:163]
	s_waitcnt lgkmcnt(0)
	v_pk_fma_f32 v[110:111], v[110:111], v[114:115], v[78:79] op_sel_hi:[1,0,1]
	v_pk_fma_f32 v[102:103], v[102:103], v[114:115], v[70:71] op_sel_hi:[1,0,1]
	v_pk_fma_f32 v[118:119], v[100:101], v[114:115], v[68:69] op_sel_hi:[1,0,1]
	v_pk_fma_f32 v[100:101], v[98:99], v[114:115], v[66:67] op_sel_hi:[1,0,1]
	v_mul_f32_e32 v99, 0xbfb8aa3b, v110
	v_mul_f32_e32 v98, v110, v102
	v_exp_f32_e32 v99, v99
	v_mul_f32_e32 v102, 0xbfb8aa3b, v111
	v_exp_f32_e32 v102, v102
	v_pk_fma_f32 v[112:113], v[112:113], v[114:115], v[80:81] op_sel_hi:[1,0,1]
	v_add_f32_e32 v99, 1.0, v99
	v_rcp_f32_e32 v99, v99
	v_add_f32_e32 v102, 1.0, v102
	v_rcp_f32_e32 v102, v102
	v_pk_fma_f32 v[104:105], v[104:105], v[114:115], v[72:73] op_sel_hi:[1,0,1]
	v_mul_f32_e32 v98, v98, v99
	v_mul_f32_e32 v99, v111, v103
	v_mul_f32_e32 v99, v99, v102
	v_mul_f32_e32 v102, 0xbfb8aa3b, v112
	v_exp_f32_e32 v102, v102
	v_mul_f32_e32 v103, 0xbfb8aa3b, v113
	v_exp_f32_e32 v103, v103
	v_cvt_pk_bf16_f32 v98, v98, v99
	v_add_f32_e32 v102, 1.0, v102
	v_rcp_f32_e32 v102, v102
	v_add_f32_e32 v103, 1.0, v103
	v_rcp_f32_e32 v103, v103
	v_mul_f32_e32 v99, v112, v104
	v_mul_f32_e32 v99, v99, v102
	v_mul_f32_e32 v102, v113, v105
	v_pk_fma_f32 v[106:107], v[106:107], v[114:115], v[74:75] op_sel_hi:[1,0,1]
	v_mul_f32_e32 v102, v102, v103
	v_cvt_pk_bf16_f32 v99, v99, v102
	v_mul_f32_e32 v102, 0xbfb8aa3b, v106
	v_exp_f32_e32 v102, v102
	v_mul_f32_e32 v100, v106, v100
	v_pk_fma_f32 v[108:109], v[108:109], v[114:115], v[76:77] op_sel_hi:[1,0,1]
	v_mul_f32_e32 v101, v107, v101
	v_add_f32_e32 v102, 1.0, v102
	v_rcp_f32_e32 v102, v102
	v_mul_f32_e32 v103, 0xbfb8aa3b, v109
	v_exp_f32_e32 v103, v103
	v_lshl_add_u64 v[116:117], v[116:117], 0, v[164:165]
	v_mul_f32_e32 v100, v100, v102
	v_mul_f32_e32 v102, 0xbfb8aa3b, v107
	v_exp_f32_e32 v102, v102
	v_add_f32_e32 v103, 1.0, v103
	v_rcp_f32_e32 v103, v103
	v_add_f32_e32 v102, 1.0, v102
	v_rcp_f32_e32 v102, v102
	s_nop 0
	v_mul_f32_e32 v101, v101, v102
	v_mul_f32_e32 v102, 0xbfb8aa3b, v108
	v_exp_f32_e32 v102, v102
	v_cvt_pk_bf16_f32 v100, v100, v101
	v_mul_f32_e32 v101, v108, v118
	v_add_f32_e32 v102, 1.0, v102
	v_rcp_f32_e32 v102, v102
	s_nop 0
	v_mul_f32_e32 v101, v101, v102
	v_mul_f32_e32 v102, v109, v119
	v_mul_f32_e32 v102, v102, v103
	v_cvt_pk_bf16_f32 v101, v101, v102
	global_store_dwordx4 v[116:117], v[98:101], off
	ds_bpermute_b32 v98, v179, v182 offset:192
	s_nop 0
	v_or_b32_e32 v99, 48, v180
	v_mad_i64_i32 v[100:101], s[2:3], v99, s46, v[162:163]
	s_waitcnt lgkmcnt(0)
; __device__ __forceinline__ unsigned cvt_pk_bf16(float lo, float hi) { unsigned r; asm volatile("v_cvt_pk_bf16_f32 %0, %1, %2" : "=v"(r) : "v"(lo), "v"(hi)); return r; }
; __device__ __forceinline__ float row_rstd(const float* ss, int row) { return 1.0f / sqrtf(ss[row] * (1.0f / DM) + 1e-6f); }
; __device__ __forceinline__ float silu_mul(float a, float b) { return a * b * __builtin_amdgcn_rcpf(1.0f + __builtin_amdgcn_exp2f(-a * LOG2E)); }
;     __device__ __forceinline__ void operator()(const f32x4 (&acc)[2][2][4][2], const Unit& u, int wr, int wc, int fr, int fq) const {
;     ...
;         const float rsl0 = row_rstd(ss, u.pm * BM + wr * 64 + lane), rsl1 = row_rstd(ss, u.pm * BM + HALF + wr * 64 + lane);
;     ...
;             for (int m = 0; m < 4; ++m) { const int row = row0 + ai * HALF + m * 16; const float rs = __shfl(ai ? rsl1 : rsl0, m * 16 + fr); bf16_t* rowp = O + (size_t)row * DFF + col0;
;                 const f32x4 a0 = acc[ai][0][m][0] * rs + ba0, a1 = acc[ai][0][m][1] * rs + ba1, b0 = acc[ai][1][m][0] * rs + bb0, b1 = acc[ai][1][m][1] * rs + bb1;
;                 u32x4 w; w.x = cvt_pk_bf16(silu_mul(a0[0], b0[0]), silu_mul(a0[1], b0[1])); w.y = cvt_pk_bf16(silu_mul(a0[2], b0[2]), silu_mul(a0[3], b0[3]));
;                 w.z = cvt_pk_bf16(silu_mul(a1[0], b1[0]), silu_mul(a1[1], b1[1])); w.w = cvt_pk_bf16(silu_mul(a1[2], b1[2]), silu_mul(a1[3], b1[3]));
;                 *(u32x4*)rowp = w; }
	v_pk_fma_f32 v[94:95], v[94:95], v[98:99], v[78:79] op_sel_hi:[1,0,1]
	v_pk_fma_f32 v[86:87], v[86:87], v[98:99], v[70:71] op_sel_hi:[1,0,1]
	v_pk_fma_f32 v[102:103], v[84:85], v[98:99], v[68:69] op_sel_hi:[1,0,1]
	v_pk_fma_f32 v[84:85], v[82:83], v[98:99], v[66:67] op_sel_hi:[1,0,1]
	v_mul_f32_e32 v83, 0xbfb8aa3b, v94
	v_mul_f32_e32 v82, v94, v86
	v_exp_f32_e32 v83, v83
	v_mul_f32_e32 v86, 0xbfb8aa3b, v95
	v_exp_f32_e32 v86, v86
	v_pk_fma_f32 v[96:97], v[96:97], v[98:99], v[80:81] op_sel_hi:[1,0,1]
	v_add_f32_e32 v83, 1.0, v83
	v_rcp_f32_e32 v83, v83
	v_add_f32_e32 v86, 1.0, v86
	v_rcp_f32_e32 v86, v86
	v_pk_fma_f32 v[88:89], v[88:89], v[98:99], v[72:73] op_sel_hi:[1,0,1]
	v_mul_f32_e32 v82, v82, v83
	v_mul_f32_e32 v83, v95, v87
	v_mul_f32_e32 v83, v83, v86
	v_mul_f32_e32 v86, 0xbfb8aa3b, v96
	v_exp_f32_e32 v86, v86
	v_mul_f32_e32 v87, 0xbfb8aa3b, v97
	v_exp_f32_e32 v87, v87
	v_cvt_pk_bf16_f32 v82, v82, v83
	v_add_f32_e32 v86, 1.0, v86
	v_rcp_f32_e32 v86, v86
	v_add_f32_e32 v87, 1.0, v87
	v_rcp_f32_e32 v87, v87
	v_mul_f32_e32 v83, v96, v88
	v_mul_f32_e32 v83, v83, v86
	v_mul_f32_e32 v86, v97, v89
	v_pk_fma_f32 v[90:91], v[90:91], v[98:99], v[74:75] op_sel_hi:[1,0,1]
	v_mul_f32_e32 v86, v86, v87
	v_cvt_pk_bf16_f32 v83, v83, v86
	v_mul_f32_e32 v86, 0xbfb8aa3b, v90
	v_exp_f32_e32 v86, v86
	v_mul_f32_e32 v84, v90, v84
	v_pk_fma_f32 v[92:93], v[92:93], v[98:99], v[76:77] op_sel_hi:[1,0,1]
	v_mul_f32_e32 v85, v91, v85
	v_add_f32_e32 v86, 1.0, v86
	v_rcp_f32_e32 v86, v86
	v_mul_f32_e32 v87, 0xbfb8aa3b, v93
	v_exp_f32_e32 v87, v87
	v_lshl_add_u64 v[100:101], v[100:101], 0, v[164:165]
	v_mul_f32_e32 v84, v84, v86
	v_mul_f32_e32 v86, 0xbfb8aa3b, v91
	v_exp_f32_e32 v86, v86
	v_add_f32_e32 v87, 1.0, v87
	v_rcp_f32_e32 v87, v87
	v_add_f32_e32 v86, 1.0, v86
	v_rcp_f32_e32 v86, v86
	s_nop 0
	v_mul_f32_e32 v85, v85, v86
	v_mul_f32_e32 v86, 0xbfb8aa3b, v92
	v_exp_f32_e32 v86, v86
	v_cvt_pk_bf16_f32 v84, v84, v85
	v_mul_f32_e32 v85, v92, v102
	v_add_f32_e32 v86, 1.0, v86
	v_rcp_f32_e32 v86, v86
	s_nop 0
	v_mul_f32_e32 v85, v85, v86
	v_mul_f32_e32 v86, v93, v103
	v_mul_f32_e32 v86, v86, v87
	v_cvt_pk_bf16_f32 v85, v85, v86
	global_store_dwordx4 v[100:101], v[82:85], off
	s_nop 1
	v_div_scale_f32 v82, s[2:3], v181, v181, 1.0
	v_rcp_f32_e32 v84, v82
	v_add_u32_e32 v83, 0x80, v180
	v_fma_f32 v85, -v82, v84, 1.0
	v_fmac_f32_e32 v84, v85, v84
	v_div_scale_f32 v85, vcc, 1.0, v181, 1.0
	v_mul_f32_e32 v86, v85, v84
	v_fma_f32 v87, -v82, v86, v85
	v_fmac_f32_e32 v86, v87, v84
	v_fma_f32 v82, -v82, v86, v85
	v_div_fmas_f32 v82, v82, v84, v86
	v_div_fixup_f32 v82, v82, v181, 1.0
	ds_bpermute_b32 v84, v179, v82
	v_mad_i64_i32 v[86:87], s[2:3], v83, s46, v[162:163]
	v_lshl_add_u64 v[86:87], v[86:87], 0, v[164:165]
	s_and_b64 vcc, s[38:39], exec
	s_waitcnt lgkmcnt(0)
	v_pk_fma_f32 v[62:63], v[62:63], v[84:85], v[78:79] op_sel_hi:[1,0,1]
	v_pk_fma_f32 v[54:55], v[54:55], v[84:85], v[70:71] op_sel_hi:[1,0,1]
	v_pk_fma_f32 v[88:89], v[52:53], v[84:85], v[68:69] op_sel_hi:[1,0,1]
	v_pk_fma_f32 v[52:53], v[50:51], v[84:85], v[66:67] op_sel_hi:[1,0,1]
	v_mul_f32_e32 v51, 0xbfb8aa3b, v62
	v_mul_f32_e32 v50, v62, v54
	v_exp_f32_e32 v51, v51
	v_mul_f32_e32 v54, 0xbfb8aa3b, v63
	v_exp_f32_e32 v54, v54
	v_pk_fma_f32 v[64:65], v[64:65], v[84:85], v[80:81] op_sel_hi:[1,0,1]
	v_add_f32_e32 v51, 1.0, v51
	v_rcp_f32_e32 v51, v51
	v_add_f32_e32 v54, 1.0, v54
	v_rcp_f32_e32 v54, v54
	v_pk_fma_f32 v[56:57], v[56:57], v[84:85], v[72:73] op_sel_hi:[1,0,1]
	v_mul_f32_e32 v50, v50, v51
	v_mul_f32_e32 v51, v63, v55
	v_mul_f32_e32 v51, v51, v54
	v_mul_f32_e32 v54, 0xbfb8aa3b, v64
	v_exp_f32_e32 v54, v54
	v_mul_f32_e32 v55, 0xbfb8aa3b, v65
	v_exp_f32_e32 v55, v55
	v_cvt_pk_bf16_f32 v50, v50, v51
	v_add_f32_e32 v54, 1.0, v54
	v_rcp_f32_e32 v54, v54
	v_add_f32_e32 v55, 1.0, v55
	v_rcp_f32_e32 v55, v55
	v_mul_f32_e32 v51, v64, v56
	v_mul_f32_e32 v51, v51, v54
	v_mul_f32_e32 v54, v65, v57
	v_pk_fma_f32 v[58:59], v[58:59], v[84:85], v[74:75] op_sel_hi:[1,0,1]
	v_mul_f32_e32 v54, v54, v55
	v_cvt_pk_bf16_f32 v51, v51, v54
	v_mul_f32_e32 v54, 0xbfb8aa3b, v58
	v_exp_f32_e32 v54, v54
	v_mul_f32_e32 v52, v58, v52
	v_pk_fma_f32 v[60:61], v[60:61], v[84:85], v[76:77] op_sel_hi:[1,0,1]
	v_mul_f32_e32 v53, v59, v53
	v_add_f32_e32 v54, 1.0, v54
	v_rcp_f32_e32 v54, v54
	v_mul_f32_e32 v55, 0xbfb8aa3b, v61
	v_exp_f32_e32 v55, v55
	v_mul_f32_e32 v52, v52, v54
	v_mul_f32_e32 v54, 0xbfb8aa3b, v59
	v_exp_f32_e32 v54, v54
	v_add_f32_e32 v55, 1.0, v55
	v_rcp_f32_e32 v55, v55
	v_add_f32_e32 v54, 1.0, v54
	v_rcp_f32_e32 v54, v54
	s_nop 0
	v_mul_f32_e32 v53, v53, v54
	v_mul_f32_e32 v54, 0xbfb8aa3b, v60
	v_exp_f32_e32 v54, v54
	v_cvt_pk_bf16_f32 v52, v52, v53
	v_mul_f32_e32 v53, v60, v88
	v_add_f32_e32 v54, 1.0, v54
	v_rcp_f32_e32 v54, v54
	s_nop 0
	v_mul_f32_e32 v53, v53, v54
	v_mul_f32_e32 v54, v61, v89
	v_mul_f32_e32 v54, v54, v55
	v_cvt_pk_bf16_f32 v53, v53, v54
	global_store_dwordx4 v[86:87], v[50:53], off
	ds_bpermute_b32 v50, v179, v82 offset:64
	s_nop 0
	v_add_u32_e32 v51, 0x90, v180
	v_mad_i64_i32 v[52:53], s[2:3], v51, s46, v[162:163]
	s_waitcnt lgkmcnt(0)
; __device__ __forceinline__ unsigned cvt_pk_bf16(float lo, float hi) { unsigned r; asm volatile("v_cvt_pk_bf16_f32 %0, %1, %2" : "=v"(r) : "v"(lo), "v"(hi)); return r; }
; __device__ __forceinline__ float silu_mul(float a, float b) { return a * b * __builtin_amdgcn_rcpf(1.0f + __builtin_amdgcn_exp2f(-a * LOG2E)); }
; #define PG8_BAR __builtin_amdgcn_s_barrier()
;     __device__ __forceinline__ void operator()(const f32x4 (&acc)[2][2][4][2], const Unit& u, int wr, int wc, int fr, int fq) const {
;     ...
;             for (int m = 0; m < 4; ++m) { const int row = row0 + ai * HALF + m * 16; const float rs = __shfl(ai ? rsl1 : rsl0, m * 16 + fr); bf16_t* rowp = O + (size_t)row * DFF + col0;
;                 const f32x4 a0 = acc[ai][0][m][0] * rs + ba0, a1 = acc[ai][0][m][1] * rs + ba1, b0 = acc[ai][1][m][0] * rs + bb0, b1 = acc[ai][1][m][1] * rs + bb1;
;                 u32x4 w; w.x = cvt_pk_bf16(silu_mul(a0[0], b0[0]), silu_mul(a0[1], b0[1])); w.y = cvt_pk_bf16(silu_mul(a0[2], b0[2]), silu_mul(a0[3], b0[3]));
;                 w.z = cvt_pk_bf16(silu_mul(a1[0], b1[0]), silu_mul(a1[1], b1[1])); w.w = cvt_pk_bf16(silu_mul(a1[2], b1[2]), silu_mul(a1[3], b1[3]));
;                 *(u32x4*)rowp = w; }
; template <class Epi, class Sched, bool ALIGN_EPI = false, bool SP2 = false>
; __device__ __forceinline__ void gemm_phase(LAS unsigned char* lds, const Gemm g, const Sched& S, const Epi& E) {
;     ...
;         if (!has_next) break;
; #pragma unroll
;         for (int a = 0; a < 2; ++a)
; #pragma unroll
;             for (int b = 0; b < 2; ++b)
; #pragma unroll
;                 for (int m = 0; m < 4; ++m)
; #pragma unroll
;                     for (int n = 0; n < 2; ++n) acc[a][b][m][n] = (f32x4){0.f, 0.f, 0.f, 0.f};
;         cur = nxt; cA = nA; cB = nB; ++ui;
;         if constexpr (ALIGN_EPI) { if (wr == 1) PG8_BAR; }
	v_pk_fma_f32 v[46:47], v[46:47], v[50:51], v[78:79] op_sel_hi:[1,0,1]
	v_pk_fma_f32 v[38:39], v[38:39], v[50:51], v[70:71] op_sel_hi:[1,0,1]
	v_pk_fma_f32 v[54:55], v[36:37], v[50:51], v[68:69] op_sel_hi:[1,0,1]
	v_pk_fma_f32 v[36:37], v[34:35], v[50:51], v[66:67] op_sel_hi:[1,0,1]
	v_mul_f32_e32 v35, 0xbfb8aa3b, v46
	v_mul_f32_e32 v34, v46, v38
	v_exp_f32_e32 v35, v35
	v_mul_f32_e32 v38, 0xbfb8aa3b, v47
	v_exp_f32_e32 v38, v38
	v_pk_fma_f32 v[48:49], v[48:49], v[50:51], v[80:81] op_sel_hi:[1,0,1]
	v_add_f32_e32 v35, 1.0, v35
	v_rcp_f32_e32 v35, v35
	v_add_f32_e32 v38, 1.0, v38
	v_rcp_f32_e32 v38, v38
	v_pk_fma_f32 v[40:41], v[40:41], v[50:51], v[72:73] op_sel_hi:[1,0,1]
	v_mul_f32_e32 v34, v34, v35
	v_mul_f32_e32 v35, v47, v39
	v_mul_f32_e32 v35, v35, v38
	v_mul_f32_e32 v38, 0xbfb8aa3b, v48
	v_exp_f32_e32 v38, v38
	v_mul_f32_e32 v39, 0xbfb8aa3b, v49
	v_exp_f32_e32 v39, v39
	v_cvt_pk_bf16_f32 v34, v34, v35
	v_add_f32_e32 v38, 1.0, v38
	v_rcp_f32_e32 v38, v38
	v_add_f32_e32 v39, 1.0, v39
	v_rcp_f32_e32 v39, v39
	v_mul_f32_e32 v35, v48, v40
	v_mul_f32_e32 v35, v35, v38
	v_mul_f32_e32 v38, v49, v41
	v_pk_fma_f32 v[42:43], v[42:43], v[50:51], v[74:75] op_sel_hi:[1,0,1]
	v_mul_f32_e32 v38, v38, v39
	v_cvt_pk_bf16_f32 v35, v35, v38
	v_mul_f32_e32 v38, 0xbfb8aa3b, v42
	v_exp_f32_e32 v38, v38
	v_mul_f32_e32 v36, v42, v36
	v_pk_fma_f32 v[44:45], v[44:45], v[50:51], v[76:77] op_sel_hi:[1,0,1]
	v_mul_f32_e32 v37, v43, v37
	v_add_f32_e32 v38, 1.0, v38
	v_rcp_f32_e32 v38, v38
	v_mul_f32_e32 v39, 0xbfb8aa3b, v45
	v_exp_f32_e32 v39, v39
	v_lshl_add_u64 v[52:53], v[52:53], 0, v[164:165]
	v_mul_f32_e32 v36, v36, v38
	v_mul_f32_e32 v38, 0xbfb8aa3b, v43
	v_exp_f32_e32 v38, v38
	v_add_f32_e32 v39, 1.0, v39
	v_rcp_f32_e32 v39, v39
	v_add_f32_e32 v38, 1.0, v38
	v_rcp_f32_e32 v38, v38
	s_nop 0
	v_mul_f32_e32 v37, v37, v38
	v_mul_f32_e32 v38, 0xbfb8aa3b, v44
	v_exp_f32_e32 v38, v38
	v_cvt_pk_bf16_f32 v36, v36, v37
	v_mul_f32_e32 v37, v44, v54
	v_add_f32_e32 v38, 1.0, v38
	v_rcp_f32_e32 v38, v38
	s_nop 0
	v_mul_f32_e32 v37, v37, v38
	v_mul_f32_e32 v38, v45, v55
	v_mul_f32_e32 v38, v38, v39
	v_cvt_pk_bf16_f32 v37, v37, v38
	global_store_dwordx4 v[52:53], v[34:37], off
	ds_bpermute_b32 v34, v179, v82 offset:128
	s_nop 0
	v_add_u32_e32 v35, 0xa0, v180
	v_mad_i64_i32 v[36:37], s[2:3], v35, s46, v[162:163]
	s_waitcnt lgkmcnt(0)
	v_pk_fma_f32 v[30:31], v[30:31], v[34:35], v[78:79] op_sel_hi:[1,0,1]
	v_pk_fma_f32 v[22:23], v[22:23], v[34:35], v[70:71] op_sel_hi:[1,0,1]
	v_pk_fma_f32 v[38:39], v[20:21], v[34:35], v[68:69] op_sel_hi:[1,0,1]
	v_pk_fma_f32 v[20:21], v[18:19], v[34:35], v[66:67] op_sel_hi:[1,0,1]
	v_mul_f32_e32 v19, 0xbfb8aa3b, v30
	v_mul_f32_e32 v18, v30, v22
	v_exp_f32_e32 v19, v19
	v_mul_f32_e32 v22, 0xbfb8aa3b, v31
	v_exp_f32_e32 v22, v22
	v_pk_fma_f32 v[32:33], v[32:33], v[34:35], v[80:81] op_sel_hi:[1,0,1]
	v_add_f32_e32 v19, 1.0, v19
	v_rcp_f32_e32 v19, v19
	v_add_f32_e32 v22, 1.0, v22
	v_rcp_f32_e32 v22, v22
	v_pk_fma_f32 v[24:25], v[24:25], v[34:35], v[72:73] op_sel_hi:[1,0,1]
	v_mul_f32_e32 v18, v18, v19
	v_mul_f32_e32 v19, v31, v23
	v_mul_f32_e32 v19, v19, v22
	v_mul_f32_e32 v22, 0xbfb8aa3b, v32
	v_exp_f32_e32 v22, v22
	v_mul_f32_e32 v23, 0xbfb8aa3b, v33
	v_exp_f32_e32 v23, v23
	v_cvt_pk_bf16_f32 v18, v18, v19
	v_add_f32_e32 v22, 1.0, v22
	v_rcp_f32_e32 v22, v22
	v_add_f32_e32 v23, 1.0, v23
	v_rcp_f32_e32 v23, v23
	v_mul_f32_e32 v19, v32, v24
	v_mul_f32_e32 v19, v19, v22
	v_mul_f32_e32 v22, v33, v25
	v_pk_fma_f32 v[26:27], v[26:27], v[34:35], v[74:75] op_sel_hi:[1,0,1]
	v_mul_f32_e32 v22, v22, v23
	v_cvt_pk_bf16_f32 v19, v19, v22
	v_mul_f32_e32 v22, 0xbfb8aa3b, v26
	v_exp_f32_e32 v22, v22
	v_mul_f32_e32 v20, v26, v20
	v_pk_fma_f32 v[28:29], v[28:29], v[34:35], v[76:77] op_sel_hi:[1,0,1]
	v_mul_f32_e32 v21, v27, v21
	v_add_f32_e32 v22, 1.0, v22
	v_rcp_f32_e32 v22, v22
	v_mul_f32_e32 v23, 0xbfb8aa3b, v29
	v_exp_f32_e32 v23, v23
	v_lshl_add_u64 v[36:37], v[36:37], 0, v[164:165]
	v_mul_f32_e32 v20, v20, v22
	v_mul_f32_e32 v22, 0xbfb8aa3b, v27
	v_exp_f32_e32 v22, v22
	v_add_f32_e32 v23, 1.0, v23
	v_rcp_f32_e32 v23, v23
	v_add_f32_e32 v22, 1.0, v22
	v_rcp_f32_e32 v22, v22
	s_nop 0
	v_mul_f32_e32 v21, v21, v22
	v_mul_f32_e32 v22, 0xbfb8aa3b, v28
	v_exp_f32_e32 v22, v22
	v_cvt_pk_bf16_f32 v20, v20, v21
	v_mul_f32_e32 v21, v28, v38
	v_add_f32_e32 v22, 1.0, v22
	v_rcp_f32_e32 v22, v22
	s_nop 0
	v_mul_f32_e32 v21, v21, v22
	v_mul_f32_e32 v22, v29, v39
	v_mul_f32_e32 v22, v22, v23
	v_cvt_pk_bf16_f32 v21, v21, v22
	global_store_dwordx4 v[36:37], v[18:21], off
	ds_bpermute_b32 v18, v179, v82 offset:192
	s_nop 0
	v_add_u32_e32 v19, 0xb0, v180
	v_mad_i64_i32 v[20:21], s[2:3], v19, s46, v[162:163]
	s_waitcnt lgkmcnt(0)
	v_pk_fma_f32 v[14:15], v[14:15], v[18:19], v[78:79] op_sel_hi:[1,0,1]
	v_pk_fma_f32 v[6:7], v[6:7], v[18:19], v[70:71] op_sel_hi:[1,0,1]
	v_pk_fma_f32 v[22:23], v[4:5], v[18:19], v[68:69] op_sel_hi:[1,0,1]
	v_pk_fma_f32 v[4:5], v[2:3], v[18:19], v[66:67] op_sel_hi:[1,0,1]
	v_mul_f32_e32 v3, 0xbfb8aa3b, v14
	v_mul_f32_e32 v2, v14, v6
	v_exp_f32_e32 v3, v3
	v_mul_f32_e32 v6, 0xbfb8aa3b, v15
	v_exp_f32_e32 v6, v6
	v_pk_fma_f32 v[16:17], v[16:17], v[18:19], v[80:81] op_sel_hi:[1,0,1]
	v_add_f32_e32 v3, 1.0, v3
	v_rcp_f32_e32 v3, v3
	v_add_f32_e32 v6, 1.0, v6
	v_rcp_f32_e32 v6, v6
	v_pk_fma_f32 v[8:9], v[8:9], v[18:19], v[72:73] op_sel_hi:[1,0,1]
	v_mul_f32_e32 v2, v2, v3
	v_mul_f32_e32 v3, v15, v7
	v_mul_f32_e32 v3, v3, v6
	v_mul_f32_e32 v6, 0xbfb8aa3b, v16
	v_exp_f32_e32 v6, v6
	v_mul_f32_e32 v7, 0xbfb8aa3b, v17
	v_exp_f32_e32 v7, v7
	v_cvt_pk_bf16_f32 v2, v2, v3
	v_add_f32_e32 v6, 1.0, v6
	v_rcp_f32_e32 v6, v6
	v_add_f32_e32 v7, 1.0, v7
	v_rcp_f32_e32 v7, v7
	v_mul_f32_e32 v3, v16, v8
	v_mul_f32_e32 v3, v3, v6
	v_mul_f32_e32 v6, v17, v9
	v_pk_fma_f32 v[10:11], v[10:11], v[18:19], v[74:75] op_sel_hi:[1,0,1]
	v_mul_f32_e32 v6, v6, v7
	v_cvt_pk_bf16_f32 v3, v3, v6
	v_mul_f32_e32 v6, 0xbfb8aa3b, v10
	v_exp_f32_e32 v6, v6
	v_mul_f32_e32 v4, v10, v4
	v_pk_fma_f32 v[12:13], v[12:13], v[18:19], v[76:77] op_sel_hi:[1,0,1]
	v_mul_f32_e32 v5, v11, v5
	v_add_f32_e32 v6, 1.0, v6
	v_rcp_f32_e32 v6, v6
	v_mul_f32_e32 v7, 0xbfb8aa3b, v13
	v_exp_f32_e32 v7, v7
	v_lshl_add_u64 v[20:21], v[20:21], 0, v[164:165]
	v_mul_f32_e32 v4, v4, v6
	v_mul_f32_e32 v6, 0xbfb8aa3b, v11
	v_exp_f32_e32 v6, v6
	v_add_f32_e32 v7, 1.0, v7
	v_rcp_f32_e32 v7, v7
	s_mov_b64 s[2:3], -1
	v_add_f32_e32 v6, 1.0, v6
	v_rcp_f32_e32 v6, v6
	s_nop 0
	v_mul_f32_e32 v5, v5, v6
	v_mul_f32_e32 v6, 0xbfb8aa3b, v12
	v_exp_f32_e32 v6, v6
	v_cvt_pk_bf16_f32 v4, v4, v5
	v_mul_f32_e32 v5, v12, v22
	v_add_f32_e32 v6, 1.0, v6
	v_rcp_f32_e32 v6, v6
	s_nop 0
	v_mul_f32_e32 v5, v5, v6
	v_mul_f32_e32 v6, v13, v23
	v_mul_f32_e32 v6, v6, v7
	v_cvt_pk_bf16_f32 v5, v5, v6
	global_store_dwordx4 v[20:21], v[2:5], off
	s_cbranch_vccz .LBB0_1818
	s_andn2_b64 vcc, exec, s[4:5]
	s_cbranch_vccnz .LBB0_1817
	s_barrier
	s_branch .LBB0_1817

; #define PG8_BAR __builtin_amdgcn_s_barrier()
; template <class Epi, class Sched, bool ALIGN_EPI = false, bool SP2 = false>
; __device__ __forceinline__ void gemm_phase(LAS unsigned char* lds, const Gemm g, const Sched& S, const Epi& E) {
;     ...
;         const bool has_next = S.next(ui + 1, nxt);
;         const char* nA = has_next ? (const char*)g.A + (size_t)nxt.pm * tstep + nxt.koff : cA; const char* nB = has_next ? (const char*)g.Bt + (size_t)nxt.pn * tstep + nxt.koff : cB;
;         for (int t = 0; t < nt; t += 2) {
;             const bool last = (t == nt - 2);
;             const char* a1 = cA + (size_t)(t + 1) * kstep;
;             const char* a2 = last ? nA : cA + (size_t)(t + 2) * kstep; const char* b2 = last ? nB : cB + (size_t)(t + 2) * kstep;
;             const char* a3 = a2 + kstep; const char* b3 = b2 + kstep;
;             if (last && has_next) S.a_ready(nxt);
;             if constexpr (SP2) {
;             PG8_LDB(B0, 0, 0); PG8_LDB(B1, 0, 1); PG8_SCHED; PG8_LDA(At, 0, 0); PG8_STAGE(PG8_SA(1, 1), a1 + hstep, voffA);
;             PG8_WAIT_V(8); PG8_WAIT_L(0); PG8_BAR; PG8_MMA(0, 0, At, B0); PG8_MMA(0, 1, At, B1); PG8_BAR; PG8_SCHED;
;             PG8_LDA(At, 0, 1); PG8_STAGE(PG8_SB(0, 0), b2, voffB); PG8_STAGE(PG8_SB(0, 1), b2 + hstepB, voffB); PG8_STAGE(PG8_SA(0, 0), a2, voffA);
;             PG8_WAIT_V(8); PG8_WAIT_L(0); PG8_BAR; PG8_MMA(1, 0, At, B0); PG8_MMA(1, 1, At, B1); PG8_BAR; PG8_SCHED;
;             PG8_LDB(B0, 1, 0); PG8_LDB(B1, 1, 1); PG8_SCHED; PG8_LDA(At, 1, 0); PG8_STAGE(PG8_SA(0, 1), a2 + hstep, voffA);
;             PG8_WAIT_V(8); PG8_WAIT_L(0); PG8_BAR; PG8_MMA(0, 0, At, B0); PG8_MMA(0, 1, At, B1); PG8_BAR; PG8_SCHED;
;             PG8_LDA(At, 1, 1); PG8_STAGE(PG8_SB(1, 0), b3, voffB); PG8_STAGE(PG8_SB(1, 1), b3 + hstepB, voffB); PG8_STAGE(PG8_SA(1, 0), a3, voffA);
;             PG8_WAIT_V(8); PG8_WAIT_L(0); PG8_BAR; PG8_MMA(1, 0, At, B0); PG8_MMA(1, 1, At, B1); PG8_BAR; PG8_SCHED;
;             } else {
;             PG8_LDB(B0, 0, 0); PG8_SCHED; PG8_LDA(At, 0, 0); PG8_STAGE(PG8_SA(1, 1), a1 + hstep, voffA);
;             PG8_WAIT_L(8); PG8_BAR; PG8_WAIT_L(0); PG8_MMA(0, 0, At, B0); PG8_BAR; PG8_SCHED;
;             PG8_LDB(B1, 0, 1); PG8_STAGE(PG8_SB(0, 0), b2, voffB);
;             PG8_BAR; PG8_WAIT_L(0); PG8_MMA(0, 1, At, B1); PG8_BAR;
;             PG8_LDA(At, 0, 1); PG8_STAGE(PG8_SA(0, 0), a2, voffA);
.LBB0_2915:
	s_ashr_i32 s13, s12, 31
	v_cmp_lt_i64_e64 s[36:37], s[14:15], v[158:159]
	s_lshl_b64 s[14:15], s[12:13], 20
	s_add_u32 s14, s93, s14
	s_addc_u32 s15, s92, s15
	s_and_b64 s[16:17], s[36:37], exec
	s_cselect_b32 s13, s15, s21
	s_cselect_b32 s46, s14, s20
	s_ashr_i32 s11, s10, 31
	s_lshl_b64 s[16:17], s[10:11], 20
	s_add_u32 s16, s78, s16
	s_addc_u32 s17, s79, s17
	s_and_b64 s[22:23], s[36:37], exec
	s_cselect_b32 s11, s17, s19
	s_cselect_b32 s47, s16, s18
	s_add_u32 s48, s18, 0x100
	s_addc_u32 s49, s19, 0
	s_add_u32 s18, s20, 0x80080
	v_mov_b32_e32 v2, 0
	s_addc_u32 s19, s21, 0
	s_mov_b32 s50, -2
	v_mov_b32_e32 v3, v2
	v_mov_b32_e32 v4, v2
	v_mov_b32_e32 v5, v2
	v_mov_b32_e32 v6, v2
	v_mov_b32_e32 v7, v2
	v_mov_b32_e32 v8, v2
	v_mov_b32_e32 v9, v2
	v_mov_b32_e32 v18, v2
	v_mov_b32_e32 v19, v2
	v_mov_b32_e32 v20, v2
	v_mov_b32_e32 v21, v2
	v_mov_b32_e32 v22, v2
	v_mov_b32_e32 v23, v2
	v_mov_b32_e32 v24, v2
	v_mov_b32_e32 v25, v2
	v_mov_b32_e32 v34, v2
	v_mov_b32_e32 v35, v2
	v_mov_b32_e32 v36, v2
	v_mov_b32_e32 v37, v2
	v_mov_b32_e32 v38, v2
	v_mov_b32_e32 v39, v2
	v_mov_b32_e32 v40, v2
	v_mov_b32_e32 v41, v2
	v_mov_b32_e32 v50, v2
	v_mov_b32_e32 v51, v2
	v_mov_b32_e32 v52, v2
	v_mov_b32_e32 v53, v2
	v_mov_b32_e32 v54, v2
	v_mov_b32_e32 v55, v2
	v_mov_b32_e32 v56, v2
	v_mov_b32_e32 v57, v2
	v_mov_b32_e32 v10, v2
	v_mov_b32_e32 v11, v2
	v_mov_b32_e32 v12, v2
	v_mov_b32_e32 v13, v2
	v_mov_b32_e32 v14, v2
	v_mov_b32_e32 v15, v2
	v_mov_b32_e32 v16, v2
	v_mov_b32_e32 v17, v2
	v_mov_b32_e32 v26, v2
	v_mov_b32_e32 v27, v2
	v_mov_b32_e32 v28, v2
	v_mov_b32_e32 v29, v2
	v_mov_b32_e32 v30, v2
	v_mov_b32_e32 v31, v2
	v_mov_b32_e32 v32, v2
	v_mov_b32_e32 v33, v2
	v_mov_b32_e32 v42, v2
	v_mov_b32_e32 v43, v2
	v_mov_b32_e32 v44, v2
	v_mov_b32_e32 v45, v2
	v_mov_b32_e32 v46, v2
	v_mov_b32_e32 v47, v2
	v_mov_b32_e32 v48, v2
	v_mov_b32_e32 v49, v2
	v_mov_b32_e32 v58, v2
	v_mov_b32_e32 v59, v2
	v_mov_b32_e32 v60, v2
	v_mov_b32_e32 v61, v2
	v_mov_b32_e32 v62, v2
	v_mov_b32_e32 v63, v2
	v_mov_b32_e32 v64, v2
	v_mov_b32_e32 v65, v2
	v_mov_b32_e32 v82, v2
	v_mov_b32_e32 v83, v2
	v_mov_b32_e32 v84, v2
	v_mov_b32_e32 v85, v2
	v_mov_b32_e32 v86, v2
	v_mov_b32_e32 v87, v2
	v_mov_b32_e32 v88, v2
	v_mov_b32_e32 v89, v2
	s_waitcnt vmcnt(0)
	v_mov_b32_e32 v98, v2
	v_mov_b32_e32 v99, v2
	v_mov_b32_e32 v100, v2
	v_mov_b32_e32 v101, v2
	v_mov_b32_e32 v102, v2
	v_mov_b32_e32 v103, v2
	v_mov_b32_e32 v104, v2
	v_mov_b32_e32 v105, v2
	v_mov_b32_e32 v114, v2
	v_mov_b32_e32 v115, v2
	v_mov_b32_e32 v116, v2
	v_mov_b32_e32 v117, v2
	v_mov_b32_e32 v118, v2
	v_mov_b32_e32 v119, v2
	v_mov_b32_e32 v120, v2
	v_mov_b32_e32 v121, v2
	v_mov_b32_e32 v130, v2
	v_mov_b32_e32 v131, v2
	v_mov_b32_e32 v132, v2
	v_mov_b32_e32 v133, v2
	v_mov_b32_e32 v134, v2
	v_mov_b32_e32 v135, v2
	v_mov_b32_e32 v136, v2
	v_mov_b32_e32 v137, v2
	v_mov_b32_e32 v90, v2
	v_mov_b32_e32 v91, v2
	v_mov_b32_e32 v92, v2
	v_mov_b32_e32 v93, v2
	v_mov_b32_e32 v94, v2
	v_mov_b32_e32 v95, v2
	v_mov_b32_e32 v96, v2
	v_mov_b32_e32 v97, v2
	v_mov_b32_e32 v106, v2
	v_mov_b32_e32 v107, v2
	v_mov_b32_e32 v108, v2
	v_mov_b32_e32 v109, v2
	v_mov_b32_e32 v110, v2
	v_mov_b32_e32 v111, v2
	v_mov_b32_e32 v112, v2
	v_mov_b32_e32 v113, v2
	v_mov_b32_e32 v122, v2
	v_mov_b32_e32 v123, v2
	v_mov_b32_e32 v124, v2
	v_mov_b32_e32 v125, v2
	v_mov_b32_e32 v126, v2
	v_mov_b32_e32 v127, v2
	v_mov_b32_e32 v128, v2
	v_mov_b32_e32 v129, v2
	v_mov_b32_e32 v138, v2
	v_mov_b32_e32 v139, v2
	v_mov_b32_e32 v140, v2
	v_mov_b32_e32 v141, v2
	v_mov_b32_e32 v142, v2
	v_mov_b32_e32 v143, v2
	v_mov_b32_e32 v144, v2
	v_mov_b32_e32 v145, v2
	s_cmpk_gt_i32 s2, 0x7f
	s_mov_b64 s[98:99], 0xb000
	s_cbranch_scc1 .Lpre_up2l1
	s_ashr_i32 s100, s2, 5
	s_mul_hi_i32 s99, s100, 0x2c00
	s_mul_i32 s98, s100, 0x2c00
.Lpre_up2l1:
	s_lshl_b64 s[98:99], s[98:99], 2
	s_add_u32 s98, s35, s98
	s_addc_u32 s99, s38, s99
	s_lshl_b32 s100, s3, 8
	s_ashr_i32 s101, s100, 31
	s_lshl_b64 s[100:101], s[100:101], 2
	s_add_u32 s98, s98, s100
	s_addc_u32 s99, s99, s101
	s_add_u32 s98, s98, s44
	s_addc_u32 s99, s99, 0
	s_lshl_b32 s100, s2, 8
	s_add_i32 s100, s100, s34
	v_or_b32_e32 v162, s100, v170
	v_ashrrev_i32_e32 v163, 31, v162
	v_lshl_add_u64 v[162:163], v[162:163], 2, s[0:1]
	v_add_u32_e32 v164, s100, v171
	v_ashrrev_i32_e32 v165, 31, v164
	v_lshl_add_u64 v[164:165], v[164:165], 2, s[0:1]
	global_load_dwordx4 v[234:237], v176, s[98:99] offset:16
	global_load_dwordx4 v[238:241], v176, s[98:99]
	global_load_dwordx4 v[242:245], v176, s[98:99] offset:528
	global_load_dwordx4 v[246:249], v176, s[98:99] offset:512
	global_load_dword v250, v[162:163], off
	global_load_dword v251, v[164:165], off

; __device__ __forceinline__ unsigned cvt_pk_bf16(float lo, float hi) { unsigned r; asm volatile("v_cvt_pk_bf16_f32 %0, %1, %2" : "=v"(r) : "v"(lo), "v"(hi)); return r; }
; __device__ __forceinline__ float silu_mul(float a, float b) { return a * b * __builtin_amdgcn_rcpf(1.0f + __builtin_amdgcn_exp2f(-a * LOG2E)); }
; __device__ __forceinline__ float row_rstd(const float* ss, int row) { return 1.0f / sqrtf(ss[row] * (1.0f / DM) + 1e-6f); }
;     __device__ __forceinline__ void operator()(const f32x4 (&acc)[2][2][4][2], const Unit& u, int wr, int wc, int fr, int fq) const {
;         const int row0 = u.pm * BM + wr * 64 + fr, col0 = u.pn * HALF + wc * 32 + 8 * fq;
;         const int s = (u.pm < ML / BM) ? (u.pm >> 5) : 4;
;         const float* bp = bias + (size_t)s * BIAS_N + u.pn * BM + wc * 32 + 8 * fq;
;         const f32x4 ba0 = *(const f32x4*)bp, ba1 = *(const f32x4*)(bp + 4), bb0 = *(const f32x4*)(bp + HALF), bb1 = *(const f32x4*)(bp + HALF + 4);
;         const int lane = fq * 16 + fr;
;         const float rsl0 = row_rstd(ss, u.pm * BM + wr * 64 + lane), rsl1 = row_rstd(ss, u.pm * BM + HALF + wr * 64 + lane);
; #pragma unroll
;         for (int ai = 0; ai < 2; ++ai)
; #pragma unroll
;             for (int m = 0; m < 4; ++m) { const int row = row0 + ai * HALF + m * 16; const float rs = __shfl(ai ? rsl1 : rsl0, m * 16 + fr); bf16_t* rowp = O + (size_t)row * DFF + col0;
;                 const f32x4 a0 = acc[ai][0][m][0] * rs + ba0, a1 = acc[ai][0][m][1] * rs + ba1, b0 = acc[ai][1][m][0] * rs + bb0, b1 = acc[ai][1][m][1] * rs + bb1;
;                 u32x4 w; w.x = cvt_pk_bf16(silu_mul(a0[0], b0[0]), silu_mul(a0[1], b0[1])); w.y = cvt_pk_bf16(silu_mul(a0[2], b0[2]), silu_mul(a0[3], b0[3]));
;                 w.z = cvt_pk_bf16(silu_mul(a1[0], b1[0]), silu_mul(a1[1], b1[1])); w.w = cvt_pk_bf16(silu_mul(a1[2], b1[2]), silu_mul(a1[3], b1[3]));
;                 *(u32x4*)rowp = w; }
.LBB0_2921:
	s_lshl_b32 s2, s2, 8
	s_add_i32 s11, s2, s34
	s_lshl_b64 s[18:19], s[18:19], 2
	s_add_u32 s13, s35, s18
	s_addc_u32 s18, s38, s19
	s_lshl_b32 s2, s3, 8
	v_lshl_or_b32 v164, s3, 7, v172
	s_ashr_i32 s3, s2, 31
	s_lshl_b64 s[2:3], s[2:3], 2
	s_add_u32 s2, s13, s2
	s_addc_u32 s3, s18, s3
	v_or_b32_e32 v162, s11, v170
	s_add_u32 s2, s2, s44
	v_ashrrev_i32_e32 v163, 31, v162
	s_addc_u32 s3, s3, 0
	v_lshl_add_u64 v[162:163], v[162:163], 2, s[0:1]
	v_mov_b32_e32 v74, v234
	v_mov_b32_e32 v75, v235
	v_mov_b32_e32 v76, v236
	v_mov_b32_e32 v77, v237
	v_mov_b32_e32 v78, v238
	v_mov_b32_e32 v79, v239
	v_mov_b32_e32 v80, v240
	v_mov_b32_e32 v81, v241
	v_mov_b32_e32 v66, v242
	v_mov_b32_e32 v67, v243
	v_mov_b32_e32 v68, v244
	v_mov_b32_e32 v69, v245
	v_mov_b32_e32 v70, v246
	v_mov_b32_e32 v71, v247
	v_mov_b32_e32 v72, v248
	v_mov_b32_e32 v73, v249
	v_or_b32_e32 v180, s11, v1
	v_mov_b32_e32 v162, v250
	v_fmamk_f32 v162, v162, 0x3a000000, v177
	v_cmp_gt_f32_e32 vcc, s45, v162
	v_mul_f32_e32 v163, 0x4f800000, v162
	s_nop 0
	v_cndmask_b32_e32 v162, v162, v163, vcc
	v_sqrt_f32_e32 v163, v162
	s_nop 0
	v_add_u32_e32 v165, -1, v163
	v_fma_f32 v166, -v165, v163, v162
	v_cmp_ge_f32_e64 s[2:3], 0, v166
	v_add_u32_e32 v166, 1, v163
	s_nop 0
	v_cndmask_b32_e64 v165, v163, v165, s[2:3]
	v_fma_f32 v163, -v166, v163, v162
	v_cmp_lt_f32_e64 s[2:3], 0, v163
	s_nop 1
	v_cndmask_b32_e64 v163, v165, v166, s[2:3]
	v_mul_f32_e32 v165, 0x37800000, v163
	v_cndmask_b32_e32 v163, v163, v165, vcc
	v_cmp_class_f32_e32 vcc, v162, v178
	s_nop 1
	v_cndmask_b32_e32 v166, v163, v162, vcc
	v_add_u32_e32 v162, s11, v171
	v_ashrrev_i32_e32 v163, 31, v162
	v_lshl_add_u64 v[162:163], v[162:163], 2, s[0:1]
	v_mov_b32_e32 v162, v251
	v_fmamk_f32 v162, v162, 0x3a000000, v177
	v_cmp_gt_f32_e32 vcc, s45, v162
	v_mul_f32_e32 v163, 0x4f800000, v162
	s_nop 0
	v_cndmask_b32_e32 v162, v162, v163, vcc
	v_sqrt_f32_e32 v163, v162
	s_nop 0
	v_add_u32_e32 v165, -1, v163
	v_fma_f32 v167, -v165, v163, v162
	v_cmp_ge_f32_e64 s[2:3], 0, v167
	v_add_u32_e32 v167, 1, v163
	s_nop 0
	v_cndmask_b32_e64 v165, v163, v165, s[2:3]
	v_fma_f32 v163, -v167, v163, v162
	v_cmp_lt_f32_e64 s[2:3], 0, v163
	s_nop 1
	v_cndmask_b32_e64 v163, v165, v167, s[2:3]
	v_mul_f32_e32 v165, 0x37800000, v163
	v_cndmask_b32_e32 v163, v163, v165, vcc
	v_cmp_class_f32_e32 vcc, v162, v178
	v_ashrrev_i32_e32 v165, 31, v164
	v_lshlrev_b64 v[164:165], 1, v[164:165]
	v_cndmask_b32_e32 v181, v163, v162, vcc
	v_div_scale_f32 v162, s[2:3], v166, v166, 1.0
	v_rcp_f32_e32 v163, v162
	s_nop 0
	v_fma_f32 v167, -v162, v163, 1.0
	v_fmac_f32_e32 v163, v167, v163
	v_div_scale_f32 v167, vcc, 1.0, v166, 1.0
	v_mul_f32_e32 v168, v167, v163
	v_fma_f32 v182, -v162, v168, v167
	v_fmac_f32_e32 v168, v182, v163
	v_fma_f32 v162, -v162, v168, v167
	v_div_fmas_f32 v162, v162, v163, v168
	v_div_fixup_f32 v182, v162, v166, 1.0
	ds_bpermute_b32 v168, v179, v182
	v_mov_b64_e32 v[162:163], s[96:97]
	v_mad_i64_i32 v[166:167], s[2:3], v180, s43, v[162:163]
	v_lshl_add_u64 v[166:167], v[166:167], 0, v[164:165]
	s_waitcnt lgkmcnt(0)
	v_pk_fma_f32 v[142:143], v[142:143], v[168:169], v[78:79] op_sel_hi:[1,0,1]
	v_pk_fma_f32 v[134:135], v[134:135], v[168:169], v[70:71] op_sel_hi:[1,0,1]
	v_pk_fma_f32 v[184:185], v[132:133], v[168:169], v[68:69] op_sel_hi:[1,0,1]
	v_pk_fma_f32 v[132:133], v[130:131], v[168:169], v[66:67] op_sel_hi:[1,0,1]
	v_mul_f32_e32 v131, 0xbfb8aa3b, v142
	v_mul_f32_e32 v130, v142, v134
	v_exp_f32_e32 v131, v131
	v_mul_f32_e32 v134, 0xbfb8aa3b, v143
	v_exp_f32_e32 v134, v134
	v_pk_fma_f32 v[144:145], v[144:145], v[168:169], v[80:81] op_sel_hi:[1,0,1]
	v_add_f32_e32 v131, 1.0, v131
	v_rcp_f32_e32 v131, v131
	v_add_f32_e32 v134, 1.0, v134
	v_rcp_f32_e32 v134, v134
	v_pk_fma_f32 v[136:137], v[136:137], v[168:169], v[72:73] op_sel_hi:[1,0,1]
	v_mul_f32_e32 v130, v130, v131
	v_mul_f32_e32 v131, v143, v135
	v_mul_f32_e32 v131, v131, v134
	v_mul_f32_e32 v134, 0xbfb8aa3b, v144
	v_exp_f32_e32 v134, v134
	v_mul_f32_e32 v135, 0xbfb8aa3b, v145
	v_exp_f32_e32 v135, v135
	v_cvt_pk_bf16_f32 v130, v130, v131
	v_add_f32_e32 v134, 1.0, v134
	v_rcp_f32_e32 v134, v134
	v_add_f32_e32 v135, 1.0, v135
	v_rcp_f32_e32 v135, v135
	v_mul_f32_e32 v131, v144, v136
	v_mul_f32_e32 v131, v131, v134
	v_mul_f32_e32 v134, v145, v137
	v_pk_fma_f32 v[138:139], v[138:139], v[168:169], v[74:75] op_sel_hi:[1,0,1]
	v_mul_f32_e32 v134, v134, v135
	v_cvt_pk_bf16_f32 v131, v131, v134
	v_mul_f32_e32 v134, 0xbfb8aa3b, v138
	v_exp_f32_e32 v134, v134
	v_mul_f32_e32 v132, v138, v132
	v_pk_fma_f32 v[140:141], v[140:141], v[168:169], v[76:77] op_sel_hi:[1,0,1]
	v_mul_f32_e32 v133, v139, v133
	v_add_f32_e32 v134, 1.0, v134
	v_rcp_f32_e32 v134, v134
	v_mul_f32_e32 v135, 0xbfb8aa3b, v141
	v_exp_f32_e32 v135, v135
	v_mul_f32_e32 v132, v132, v134
	v_mul_f32_e32 v134, 0xbfb8aa3b, v139
	v_exp_f32_e32 v134, v134
	v_add_f32_e32 v135, 1.0, v135
	v_rcp_f32_e32 v135, v135
	v_add_f32_e32 v134, 1.0, v134
	v_rcp_f32_e32 v134, v134
	s_nop 0
	v_mul_f32_e32 v133, v133, v134
	v_mul_f32_e32 v134, 0xbfb8aa3b, v140
	v_exp_f32_e32 v134, v134
	v_cvt_pk_bf16_f32 v132, v132, v133
	v_mul_f32_e32 v133, v140, v184
	v_add_f32_e32 v134, 1.0, v134
	v_rcp_f32_e32 v134, v134
	s_nop 0
	v_mul_f32_e32 v133, v133, v134
	v_mul_f32_e32 v134, v141, v185
	v_mul_f32_e32 v134, v134, v135
	v_cvt_pk_bf16_f32 v133, v133, v134
	global_store_dwordx4 v[166:167], v[130:133], off
	ds_bpermute_b32 v130, v179, v182 offset:64
	s_nop 0
	v_or_b32_e32 v131, 16, v180
	v_mad_i64_i32 v[132:133], s[2:3], v131, s43, v[162:163]
	s_waitcnt lgkmcnt(0)
; __device__ __forceinline__ unsigned cvt_pk_bf16(float lo, float hi) { unsigned r; asm volatile("v_cvt_pk_bf16_f32 %0, %1, %2" : "=v"(r) : "v"(lo), "v"(hi)); return r; }
; __device__ __forceinline__ float silu_mul(float a, float b) { return a * b * __builtin_amdgcn_rcpf(1.0f + __builtin_amdgcn_exp2f(-a * LOG2E)); }
;     __device__ __forceinline__ void operator()(const f32x4 (&acc)[2][2][4][2], const Unit& u, int wr, int wc, int fr, int fq) const {
;     ...
;             for (int m = 0; m < 4; ++m) { const int row = row0 + ai * HALF + m * 16; const float rs = __shfl(ai ? rsl1 : rsl0, m * 16 + fr); bf16_t* rowp = O + (size_t)row * DFF + col0;
;                 const f32x4 a0 = acc[ai][0][m][0] * rs + ba0, a1 = acc[ai][0][m][1] * rs + ba1, b0 = acc[ai][1][m][0] * rs + bb0, b1 = acc[ai][1][m][1] * rs + bb1;
;                 u32x4 w; w.x = cvt_pk_bf16(silu_mul(a0[0], b0[0]), silu_mul(a0[1], b0[1])); w.y = cvt_pk_bf16(silu_mul(a0[2], b0[2]), silu_mul(a0[3], b0[3]));
;                 w.z = cvt_pk_bf16(silu_mul(a1[0], b1[0]), silu_mul(a1[1], b1[1])); w.w = cvt_pk_bf16(silu_mul(a1[2], b1[2]), silu_mul(a1[3], b1[3]));
;                 *(u32x4*)rowp = w; }
	v_pk_fma_f32 v[126:127], v[126:127], v[130:131], v[78:79] op_sel_hi:[1,0,1]
	v_pk_fma_f32 v[118:119], v[118:119], v[130:131], v[70:71] op_sel_hi:[1,0,1]
	v_pk_fma_f32 v[134:135], v[116:117], v[130:131], v[68:69] op_sel_hi:[1,0,1]
	v_pk_fma_f32 v[116:117], v[114:115], v[130:131], v[66:67] op_sel_hi:[1,0,1]
	v_mul_f32_e32 v115, 0xbfb8aa3b, v126
	v_mul_f32_e32 v114, v126, v118
	v_exp_f32_e32 v115, v115
	v_mul_f32_e32 v118, 0xbfb8aa3b, v127
	v_exp_f32_e32 v118, v118
	v_pk_fma_f32 v[128:129], v[128:129], v[130:131], v[80:81] op_sel_hi:[1,0,1]
	v_add_f32_e32 v115, 1.0, v115
	v_rcp_f32_e32 v115, v115
	v_add_f32_e32 v118, 1.0, v118
	v_rcp_f32_e32 v118, v118
	v_pk_fma_f32 v[120:121], v[120:121], v[130:131], v[72:73] op_sel_hi:[1,0,1]
	v_mul_f32_e32 v114, v114, v115
	v_mul_f32_e32 v115, v127, v119
	v_mul_f32_e32 v115, v115, v118
	v_mul_f32_e32 v118, 0xbfb8aa3b, v128
	v_exp_f32_e32 v118, v118
	v_mul_f32_e32 v119, 0xbfb8aa3b, v129
	v_exp_f32_e32 v119, v119
	v_cvt_pk_bf16_f32 v114, v114, v115
	v_add_f32_e32 v118, 1.0, v118
	v_rcp_f32_e32 v118, v118
	v_add_f32_e32 v119, 1.0, v119
	v_rcp_f32_e32 v119, v119
	v_mul_f32_e32 v115, v128, v120
	v_mul_f32_e32 v115, v115, v118
	v_mul_f32_e32 v118, v129, v121
	v_pk_fma_f32 v[122:123], v[122:123], v[130:131], v[74:75] op_sel_hi:[1,0,1]
	v_mul_f32_e32 v118, v118, v119
	v_cvt_pk_bf16_f32 v115, v115, v118
	v_mul_f32_e32 v118, 0xbfb8aa3b, v122
	v_exp_f32_e32 v118, v118
	v_mul_f32_e32 v116, v122, v116
	v_pk_fma_f32 v[124:125], v[124:125], v[130:131], v[76:77] op_sel_hi:[1,0,1]
	v_mul_f32_e32 v117, v123, v117
	v_add_f32_e32 v118, 1.0, v118
	v_rcp_f32_e32 v118, v118
	v_mul_f32_e32 v119, 0xbfb8aa3b, v125
	v_exp_f32_e32 v119, v119
	v_lshl_add_u64 v[132:133], v[132:133], 0, v[164:165]
	v_mul_f32_e32 v116, v116, v118
	v_mul_f32_e32 v118, 0xbfb8aa3b, v123
	v_exp_f32_e32 v118, v118
	v_add_f32_e32 v119, 1.0, v119
	v_rcp_f32_e32 v119, v119
	v_add_f32_e32 v118, 1.0, v118
	v_rcp_f32_e32 v118, v118
	s_nop 0
	v_mul_f32_e32 v117, v117, v118
	v_mul_f32_e32 v118, 0xbfb8aa3b, v124
	v_exp_f32_e32 v118, v118
	v_cvt_pk_bf16_f32 v116, v116, v117
	v_mul_f32_e32 v117, v124, v134
	v_add_f32_e32 v118, 1.0, v118
	v_rcp_f32_e32 v118, v118
	s_nop 0
	v_mul_f32_e32 v117, v117, v118
	v_mul_f32_e32 v118, v125, v135
	v_mul_f32_e32 v118, v118, v119
	v_cvt_pk_bf16_f32 v117, v117, v118
	global_store_dwordx4 v[132:133], v[114:117], off
	ds_bpermute_b32 v114, v179, v182 offset:128
	s_nop 0
	v_or_b32_e32 v115, 32, v180
	v_mad_i64_i32 v[116:117], s[2:3], v115, s43, v[162:163]
	s_waitcnt lgkmcnt(0)
	v_pk_fma_f32 v[110:111], v[110:111], v[114:115], v[78:79] op_sel_hi:[1,0,1]
	v_pk_fma_f32 v[102:103], v[102:103], v[114:115], v[70:71] op_sel_hi:[1,0,1]
	v_pk_fma_f32 v[118:119], v[100:101], v[114:115], v[68:69] op_sel_hi:[1,0,1]
	v_pk_fma_f32 v[100:101], v[98:99], v[114:115], v[66:67] op_sel_hi:[1,0,1]
	v_mul_f32_e32 v99, 0xbfb8aa3b, v110
	v_mul_f32_e32 v98, v110, v102
	v_exp_f32_e32 v99, v99
	v_mul_f32_e32 v102, 0xbfb8aa3b, v111
	v_exp_f32_e32 v102, v102
	v_pk_fma_f32 v[112:113], v[112:113], v[114:115], v[80:81] op_sel_hi:[1,0,1]
	v_add_f32_e32 v99, 1.0, v99
	v_rcp_f32_e32 v99, v99
	v_add_f32_e32 v102, 1.0, v102
	v_rcp_f32_e32 v102, v102
	v_pk_fma_f32 v[104:105], v[104:105], v[114:115], v[72:73] op_sel_hi:[1,0,1]
	v_mul_f32_e32 v98, v98, v99
	v_mul_f32_e32 v99, v111, v103
	v_mul_f32_e32 v99, v99, v102
	v_mul_f32_e32 v102, 0xbfb8aa3b, v112
	v_exp_f32_e32 v102, v102
	v_mul_f32_e32 v103, 0xbfb8aa3b, v113
	v_exp_f32_e32 v103, v103
	v_cvt_pk_bf16_f32 v98, v98, v99
	v_add_f32_e32 v102, 1.0, v102
	v_rcp_f32_e32 v102, v102
	v_add_f32_e32 v103, 1.0, v103
	v_rcp_f32_e32 v103, v103
	v_mul_f32_e32 v99, v112, v104
	v_mul_f32_e32 v99, v99, v102
	v_mul_f32_e32 v102, v113, v105
	v_pk_fma_f32 v[106:107], v[106:107], v[114:115], v[74:75] op_sel_hi:[1,0,1]
	v_mul_f32_e32 v102, v102, v103
	v_cvt_pk_bf16_f32 v99, v99, v102
	v_mul_f32_e32 v102, 0xbfb8aa3b, v106
	v_exp_f32_e32 v102, v102
	v_mul_f32_e32 v100, v106, v100
	v_pk_fma_f32 v[108:109], v[108:109], v[114:115], v[76:77] op_sel_hi:[1,0,1]
	v_mul_f32_e32 v101, v107, v101
	v_add_f32_e32 v102, 1.0, v102
	v_rcp_f32_e32 v102, v102
	v_mul_f32_e32 v103, 0xbfb8aa3b, v109
	v_exp_f32_e32 v103, v103
	v_lshl_add_u64 v[116:117], v[116:117], 0, v[164:165]
	v_mul_f32_e32 v100, v100, v102
	v_mul_f32_e32 v102, 0xbfb8aa3b, v107
	v_exp_f32_e32 v102, v102
	v_add_f32_e32 v103, 1.0, v103
	v_rcp_f32_e32 v103, v103
	v_add_f32_e32 v102, 1.0, v102
	v_rcp_f32_e32 v102, v102
	s_nop 0
	v_mul_f32_e32 v101, v101, v102
	v_mul_f32_e32 v102, 0xbfb8aa3b, v108
	v_exp_f32_e32 v102, v102
	v_cvt_pk_bf16_f32 v100, v100, v101
	v_mul_f32_e32 v101, v108, v118
	v_add_f32_e32 v102, 1.0, v102
	v_rcp_f32_e32 v102, v102
	s_nop 0
	v_mul_f32_e32 v101, v101, v102
	v_mul_f32_e32 v102, v109, v119
	v_mul_f32_e32 v102, v102, v103
	v_cvt_pk_bf16_f32 v101, v101, v102
	global_store_dwordx4 v[116:117], v[98:101], off
	ds_bpermute_b32 v98, v179, v182 offset:192
	s_nop 0
	v_or_b32_e32 v99, 48, v180
	v_mad_i64_i32 v[100:101], s[2:3], v99, s43, v[162:163]
	s_waitcnt lgkmcnt(0)
; __device__ __forceinline__ unsigned cvt_pk_bf16(float lo, float hi) { unsigned r; asm volatile("v_cvt_pk_bf16_f32 %0, %1, %2" : "=v"(r) : "v"(lo), "v"(hi)); return r; }
; __device__ __forceinline__ float row_rstd(const float* ss, int row) { return 1.0f / sqrtf(ss[row] * (1.0f / DM) + 1e-6f); }
; __device__ __forceinline__ float silu_mul(float a, float b) { return a * b * __builtin_amdgcn_rcpf(1.0f + __builtin_amdgcn_exp2f(-a * LOG2E)); }
;     __device__ __forceinline__ void operator()(const f32x4 (&acc)[2][2][4][2], const Unit& u, int wr, int wc, int fr, int fq) const {
;     ...
;         const float rsl0 = row_rstd(ss, u.pm * BM + wr * 64 + lane), rsl1 = row_rstd(ss, u.pm * BM + HALF + wr * 64 + lane);
;     ...
;             for (int m = 0; m < 4; ++m) { const int row = row0 + ai * HALF + m * 16; const float rs = __shfl(ai ? rsl1 : rsl0, m * 16 + fr); bf16_t* rowp = O + (size_t)row * DFF + col0;
;                 const f32x4 a0 = acc[ai][0][m][0] * rs + ba0, a1 = acc[ai][0][m][1] * rs + ba1, b0 = acc[ai][1][m][0] * rs + bb0, b1 = acc[ai][1][m][1] * rs + bb1;
;                 u32x4 w; w.x = cvt_pk_bf16(silu_mul(a0[0], b0[0]), silu_mul(a0[1], b0[1])); w.y = cvt_pk_bf16(silu_mul(a0[2], b0[2]), silu_mul(a0[3], b0[3]));
;                 w.z = cvt_pk_bf16(silu_mul(a1[0], b1[0]), silu_mul(a1[1], b1[1])); w.w = cvt_pk_bf16(silu_mul(a1[2], b1[2]), silu_mul(a1[3], b1[3]));
;                 *(u32x4*)rowp = w; }
	v_pk_fma_f32 v[94:95], v[94:95], v[98:99], v[78:79] op_sel_hi:[1,0,1]
	v_pk_fma_f32 v[86:87], v[86:87], v[98:99], v[70:71] op_sel_hi:[1,0,1]
	v_pk_fma_f32 v[102:103], v[84:85], v[98:99], v[68:69] op_sel_hi:[1,0,1]
	v_pk_fma_f32 v[84:85], v[82:83], v[98:99], v[66:67] op_sel_hi:[1,0,1]
	v_mul_f32_e32 v83, 0xbfb8aa3b, v94
	v_mul_f32_e32 v82, v94, v86
	v_exp_f32_e32 v83, v83
	v_mul_f32_e32 v86, 0xbfb8aa3b, v95
	v_exp_f32_e32 v86, v86
	v_pk_fma_f32 v[96:97], v[96:97], v[98:99], v[80:81] op_sel_hi:[1,0,1]
	v_add_f32_e32 v83, 1.0, v83
	v_rcp_f32_e32 v83, v83
	v_add_f32_e32 v86, 1.0, v86
	v_rcp_f32_e32 v86, v86
	v_pk_fma_f32 v[88:89], v[88:89], v[98:99], v[72:73] op_sel_hi:[1,0,1]
	v_mul_f32_e32 v82, v82, v83
	v_mul_f32_e32 v83, v95, v87
	v_mul_f32_e32 v83, v83, v86
	v_mul_f32_e32 v86, 0xbfb8aa3b, v96
	v_exp_f32_e32 v86, v86
	v_mul_f32_e32 v87, 0xbfb8aa3b, v97
	v_exp_f32_e32 v87, v87
	v_cvt_pk_bf16_f32 v82, v82, v83
	v_add_f32_e32 v86, 1.0, v86
	v_rcp_f32_e32 v86, v86
	v_add_f32_e32 v87, 1.0, v87
	v_rcp_f32_e32 v87, v87
	v_mul_f32_e32 v83, v96, v88
	v_mul_f32_e32 v83, v83, v86
	v_mul_f32_e32 v86, v97, v89
	v_pk_fma_f32 v[90:91], v[90:91], v[98:99], v[74:75] op_sel_hi:[1,0,1]
	v_mul_f32_e32 v86, v86, v87
	v_cvt_pk_bf16_f32 v83, v83, v86
	v_mul_f32_e32 v86, 0xbfb8aa3b, v90
	v_exp_f32_e32 v86, v86
	v_mul_f32_e32 v84, v90, v84
	v_pk_fma_f32 v[92:93], v[92:93], v[98:99], v[76:77] op_sel_hi:[1,0,1]
	v_mul_f32_e32 v85, v91, v85
	v_add_f32_e32 v86, 1.0, v86
	v_rcp_f32_e32 v86, v86
	v_mul_f32_e32 v87, 0xbfb8aa3b, v93
	v_exp_f32_e32 v87, v87
	v_lshl_add_u64 v[100:101], v[100:101], 0, v[164:165]
	v_mul_f32_e32 v84, v84, v86
	v_mul_f32_e32 v86, 0xbfb8aa3b, v91
	v_exp_f32_e32 v86, v86
	v_add_f32_e32 v87, 1.0, v87
	v_rcp_f32_e32 v87, v87
	v_add_f32_e32 v86, 1.0, v86
	v_rcp_f32_e32 v86, v86
	s_nop 0
	v_mul_f32_e32 v85, v85, v86
	v_mul_f32_e32 v86, 0xbfb8aa3b, v92
	v_exp_f32_e32 v86, v86
	v_cvt_pk_bf16_f32 v84, v84, v85
	v_mul_f32_e32 v85, v92, v102
	v_add_f32_e32 v86, 1.0, v86
	v_rcp_f32_e32 v86, v86
	s_nop 0
	v_mul_f32_e32 v85, v85, v86
	v_mul_f32_e32 v86, v93, v103
	v_mul_f32_e32 v86, v86, v87
	v_cvt_pk_bf16_f32 v85, v85, v86
	global_store_dwordx4 v[100:101], v[82:85], off
	s_nop 1
	v_div_scale_f32 v82, s[2:3], v181, v181, 1.0
	v_rcp_f32_e32 v84, v82
	v_add_u32_e32 v83, 0x80, v180
	v_fma_f32 v85, -v82, v84, 1.0
	v_fmac_f32_e32 v84, v85, v84
	v_div_scale_f32 v85, vcc, 1.0, v181, 1.0
	v_mul_f32_e32 v86, v85, v84
	v_fma_f32 v87, -v82, v86, v85
	v_fmac_f32_e32 v86, v87, v84
	v_fma_f32 v82, -v82, v86, v85
	v_div_fmas_f32 v82, v82, v84, v86
	v_div_fixup_f32 v82, v82, v181, 1.0
	ds_bpermute_b32 v84, v179, v82
	v_mad_i64_i32 v[86:87], s[2:3], v83, s43, v[162:163]
	v_lshl_add_u64 v[86:87], v[86:87], 0, v[164:165]
	s_and_b64 vcc, s[36:37], exec
	s_waitcnt lgkmcnt(0)
	v_pk_fma_f32 v[62:63], v[62:63], v[84:85], v[78:79] op_sel_hi:[1,0,1]
	v_pk_fma_f32 v[54:55], v[54:55], v[84:85], v[70:71] op_sel_hi:[1,0,1]
	v_pk_fma_f32 v[88:89], v[52:53], v[84:85], v[68:69] op_sel_hi:[1,0,1]
	v_pk_fma_f32 v[52:53], v[50:51], v[84:85], v[66:67] op_sel_hi:[1,0,1]
	v_mul_f32_e32 v51, 0xbfb8aa3b, v62
	v_mul_f32_e32 v50, v62, v54
	v_exp_f32_e32 v51, v51
	v_mul_f32_e32 v54, 0xbfb8aa3b, v63
	v_exp_f32_e32 v54, v54
	v_pk_fma_f32 v[64:65], v[64:65], v[84:85], v[80:81] op_sel_hi:[1,0,1]
	v_add_f32_e32 v51, 1.0, v51
	v_rcp_f32_e32 v51, v51
	v_add_f32_e32 v54, 1.0, v54
	v_rcp_f32_e32 v54, v54
	v_pk_fma_f32 v[56:57], v[56:57], v[84:85], v[72:73] op_sel_hi:[1,0,1]
	v_mul_f32_e32 v50, v50, v51
	v_mul_f32_e32 v51, v63, v55
	v_mul_f32_e32 v51, v51, v54
	v_mul_f32_e32 v54, 0xbfb8aa3b, v64
	v_exp_f32_e32 v54, v54
	v_mul_f32_e32 v55, 0xbfb8aa3b, v65
	v_exp_f32_e32 v55, v55
	v_cvt_pk_bf16_f32 v50, v50, v51
	v_add_f32_e32 v54, 1.0, v54
	v_rcp_f32_e32 v54, v54
	v_add_f32_e32 v55, 1.0, v55
	v_rcp_f32_e32 v55, v55
	v_mul_f32_e32 v51, v64, v56
	v_mul_f32_e32 v51, v51, v54
	v_mul_f32_e32 v54, v65, v57
	v_pk_fma_f32 v[58:59], v[58:59], v[84:85], v[74:75] op_sel_hi:[1,0,1]
	v_mul_f32_e32 v54, v54, v55
	v_cvt_pk_bf16_f32 v51, v51, v54
	v_mul_f32_e32 v54, 0xbfb8aa3b, v58
	v_exp_f32_e32 v54, v54
	v_mul_f32_e32 v52, v58, v52
	v_pk_fma_f32 v[60:61], v[60:61], v[84:85], v[76:77] op_sel_hi:[1,0,1]
	v_mul_f32_e32 v53, v59, v53
	v_add_f32_e32 v54, 1.0, v54
	v_rcp_f32_e32 v54, v54
	v_mul_f32_e32 v55, 0xbfb8aa3b, v61
	v_exp_f32_e32 v55, v55
	v_mul_f32_e32 v52, v52, v54
	v_mul_f32_e32 v54, 0xbfb8aa3b, v59
	v_exp_f32_e32 v54, v54
	v_add_f32_e32 v55, 1.0, v55
	v_rcp_f32_e32 v55, v55
	v_add_f32_e32 v54, 1.0, v54
	v_rcp_f32_e32 v54, v54
	s_nop 0
	v_mul_f32_e32 v53, v53, v54
	v_mul_f32_e32 v54, 0xbfb8aa3b, v60
	v_exp_f32_e32 v54, v54
	v_cvt_pk_bf16_f32 v52, v52, v53
	v_mul_f32_e32 v53, v60, v88
	v_add_f32_e32 v54, 1.0, v54
	v_rcp_f32_e32 v54, v54
	s_nop 0
	v_mul_f32_e32 v53, v53, v54
	v_mul_f32_e32 v54, v61, v89
	v_mul_f32_e32 v54, v54, v55
	v_cvt_pk_bf16_f32 v53, v53, v54
	global_store_dwordx4 v[86:87], v[50:53], off
	ds_bpermute_b32 v50, v179, v82 offset:64
	s_nop 0
	v_add_u32_e32 v51, 0x90, v180
	v_mad_i64_i32 v[52:53], s[2:3], v51, s43, v[162:163]
	s_waitcnt lgkmcnt(0)
; __device__ __forceinline__ unsigned cvt_pk_bf16(float lo, float hi) { unsigned r; asm volatile("v_cvt_pk_bf16_f32 %0, %1, %2" : "=v"(r) : "v"(lo), "v"(hi)); return r; }
; __device__ __forceinline__ float silu_mul(float a, float b) { return a * b * __builtin_amdgcn_rcpf(1.0f + __builtin_amdgcn_exp2f(-a * LOG2E)); }
; #define PG8_BAR __builtin_amdgcn_s_barrier()
;     __device__ __forceinline__ void operator()(const f32x4 (&acc)[2][2][4][2], const Unit& u, int wr, int wc, int fr, int fq) const {
;     ...
;             for (int m = 0; m < 4; ++m) { const int row = row0 + ai * HALF + m * 16; const float rs = __shfl(ai ? rsl1 : rsl0, m * 16 + fr); bf16_t* rowp = O + (size_t)row * DFF + col0;
;                 const f32x4 a0 = acc[ai][0][m][0] * rs + ba0, a1 = acc[ai][0][m][1] * rs + ba1, b0 = acc[ai][1][m][0] * rs + bb0, b1 = acc[ai][1][m][1] * rs + bb1;
;                 u32x4 w; w.x = cvt_pk_bf16(silu_mul(a0[0], b0[0]), silu_mul(a0[1], b0[1])); w.y = cvt_pk_bf16(silu_mul(a0[2], b0[2]), silu_mul(a0[3], b0[3]));
;                 w.z = cvt_pk_bf16(silu_mul(a1[0], b1[0]), silu_mul(a1[1], b1[1])); w.w = cvt_pk_bf16(silu_mul(a1[2], b1[2]), silu_mul(a1[3], b1[3]));
;                 *(u32x4*)rowp = w; }
; template <class Epi, class Sched, bool ALIGN_EPI = false, bool SP2 = false>
; __device__ __forceinline__ void gemm_phase(LAS unsigned char* lds, const Gemm g, const Sched& S, const Epi& E) {
;     ...
;         if (!has_next) break;
; #pragma unroll
;         for (int a = 0; a < 2; ++a)
; #pragma unroll
;             for (int b = 0; b < 2; ++b)
; #pragma unroll
;                 for (int m = 0; m < 4; ++m)
; #pragma unroll
;                     for (int n = 0; n < 2; ++n) acc[a][b][m][n] = (f32x4){0.f, 0.f, 0.f, 0.f};
;         cur = nxt; cA = nA; cB = nB; ++ui;
;         if constexpr (ALIGN_EPI) { if (wr == 1) PG8_BAR; }
	v_pk_fma_f32 v[46:47], v[46:47], v[50:51], v[78:79] op_sel_hi:[1,0,1]
	v_pk_fma_f32 v[38:39], v[38:39], v[50:51], v[70:71] op_sel_hi:[1,0,1]
	v_pk_fma_f32 v[54:55], v[36:37], v[50:51], v[68:69] op_sel_hi:[1,0,1]
	v_pk_fma_f32 v[36:37], v[34:35], v[50:51], v[66:67] op_sel_hi:[1,0,1]
	v_mul_f32_e32 v35, 0xbfb8aa3b, v46
	v_mul_f32_e32 v34, v46, v38
	v_exp_f32_e32 v35, v35
	v_mul_f32_e32 v38, 0xbfb8aa3b, v47
	v_exp_f32_e32 v38, v38
	v_pk_fma_f32 v[48:49], v[48:49], v[50:51], v[80:81] op_sel_hi:[1,0,1]
	v_add_f32_e32 v35, 1.0, v35
	v_rcp_f32_e32 v35, v35
	v_add_f32_e32 v38, 1.0, v38
	v_rcp_f32_e32 v38, v38
	v_pk_fma_f32 v[40:41], v[40:41], v[50:51], v[72:73] op_sel_hi:[1,0,1]
	v_mul_f32_e32 v34, v34, v35
	v_mul_f32_e32 v35, v47, v39
	v_mul_f32_e32 v35, v35, v38
	v_mul_f32_e32 v38, 0xbfb8aa3b, v48
	v_exp_f32_e32 v38, v38
	v_mul_f32_e32 v39, 0xbfb8aa3b, v49
	v_exp_f32_e32 v39, v39
	v_cvt_pk_bf16_f32 v34, v34, v35
	v_add_f32_e32 v38, 1.0, v38
	v_rcp_f32_e32 v38, v38
	v_add_f32_e32 v39, 1.0, v39
	v_rcp_f32_e32 v39, v39
	v_mul_f32_e32 v35, v48, v40
	v_mul_f32_e32 v35, v35, v38
	v_mul_f32_e32 v38, v49, v41
	v_pk_fma_f32 v[42:43], v[42:43], v[50:51], v[74:75] op_sel_hi:[1,0,1]
	v_mul_f32_e32 v38, v38, v39
	v_cvt_pk_bf16_f32 v35, v35, v38
	v_mul_f32_e32 v38, 0xbfb8aa3b, v42
	v_exp_f32_e32 v38, v38
	v_mul_f32_e32 v36, v42, v36
	v_pk_fma_f32 v[44:45], v[44:45], v[50:51], v[76:77] op_sel_hi:[1,0,1]
	v_mul_f32_e32 v37, v43, v37
	v_add_f32_e32 v38, 1.0, v38
	v_rcp_f32_e32 v38, v38
	v_mul_f32_e32 v39, 0xbfb8aa3b, v45
	v_exp_f32_e32 v39, v39
	v_lshl_add_u64 v[52:53], v[52:53], 0, v[164:165]
	v_mul_f32_e32 v36, v36, v38
	v_mul_f32_e32 v38, 0xbfb8aa3b, v43
	v_exp_f32_e32 v38, v38
	v_add_f32_e32 v39, 1.0, v39
	v_rcp_f32_e32 v39, v39
	v_add_f32_e32 v38, 1.0, v38
	v_rcp_f32_e32 v38, v38
	s_nop 0
	v_mul_f32_e32 v37, v37, v38
	v_mul_f32_e32 v38, 0xbfb8aa3b, v44
	v_exp_f32_e32 v38, v38
	v_cvt_pk_bf16_f32 v36, v36, v37
	v_mul_f32_e32 v37, v44, v54
	v_add_f32_e32 v38, 1.0, v38
	v_rcp_f32_e32 v38, v38
	s_nop 0
	v_mul_f32_e32 v37, v37, v38
	v_mul_f32_e32 v38, v45, v55
	v_mul_f32_e32 v38, v38, v39
	v_cvt_pk_bf16_f32 v37, v37, v38
	global_store_dwordx4 v[52:53], v[34:37], off
	ds_bpermute_b32 v34, v179, v82 offset:128
	s_nop 0
	v_add_u32_e32 v35, 0xa0, v180
	v_mad_i64_i32 v[36:37], s[2:3], v35, s43, v[162:163]
	s_waitcnt lgkmcnt(0)
	v_pk_fma_f32 v[30:31], v[30:31], v[34:35], v[78:79] op_sel_hi:[1,0,1]
	v_pk_fma_f32 v[22:23], v[22:23], v[34:35], v[70:71] op_sel_hi:[1,0,1]
	v_pk_fma_f32 v[38:39], v[20:21], v[34:35], v[68:69] op_sel_hi:[1,0,1]
	v_pk_fma_f32 v[20:21], v[18:19], v[34:35], v[66:67] op_sel_hi:[1,0,1]
	v_mul_f32_e32 v19, 0xbfb8aa3b, v30
	v_mul_f32_e32 v18, v30, v22
	v_exp_f32_e32 v19, v19
	v_mul_f32_e32 v22, 0xbfb8aa3b, v31
	v_exp_f32_e32 v22, v22
	v_pk_fma_f32 v[32:33], v[32:33], v[34:35], v[80:81] op_sel_hi:[1,0,1]
	v_add_f32_e32 v19, 1.0, v19
	v_rcp_f32_e32 v19, v19
	v_add_f32_e32 v22, 1.0, v22
	v_rcp_f32_e32 v22, v22
	v_pk_fma_f32 v[24:25], v[24:25], v[34:35], v[72:73] op_sel_hi:[1,0,1]
	v_mul_f32_e32 v18, v18, v19
	v_mul_f32_e32 v19, v31, v23
	v_mul_f32_e32 v19, v19, v22
	v_mul_f32_e32 v22, 0xbfb8aa3b, v32
	v_exp_f32_e32 v22, v22
	v_mul_f32_e32 v23, 0xbfb8aa3b, v33
	v_exp_f32_e32 v23, v23
	v_cvt_pk_bf16_f32 v18, v18, v19
	v_add_f32_e32 v22, 1.0, v22
	v_rcp_f32_e32 v22, v22
	v_add_f32_e32 v23, 1.0, v23
	v_rcp_f32_e32 v23, v23
	v_mul_f32_e32 v19, v32, v24
	v_mul_f32_e32 v19, v19, v22
	v_mul_f32_e32 v22, v33, v25
	v_pk_fma_f32 v[26:27], v[26:27], v[34:35], v[74:75] op_sel_hi:[1,0,1]
	v_mul_f32_e32 v22, v22, v23
	v_cvt_pk_bf16_f32 v19, v19, v22
	v_mul_f32_e32 v22, 0xbfb8aa3b, v26
	v_exp_f32_e32 v22, v22
	v_mul_f32_e32 v20, v26, v20
	v_pk_fma_f32 v[28:29], v[28:29], v[34:35], v[76:77] op_sel_hi:[1,0,1]
	v_mul_f32_e32 v21, v27, v21
	v_add_f32_e32 v22, 1.0, v22
	v_rcp_f32_e32 v22, v22
	v_mul_f32_e32 v23, 0xbfb8aa3b, v29
	v_exp_f32_e32 v23, v23
	v_lshl_add_u64 v[36:37], v[36:37], 0, v[164:165]
	v_mul_f32_e32 v20, v20, v22
	v_mul_f32_e32 v22, 0xbfb8aa3b, v27
	v_exp_f32_e32 v22, v22
	v_add_f32_e32 v23, 1.0, v23
	v_rcp_f32_e32 v23, v23
	v_add_f32_e32 v22, 1.0, v22
	v_rcp_f32_e32 v22, v22
	s_nop 0
	v_mul_f32_e32 v21, v21, v22
	v_mul_f32_e32 v22, 0xbfb8aa3b, v28
	v_exp_f32_e32 v22, v22
	v_cvt_pk_bf16_f32 v20, v20, v21
	v_mul_f32_e32 v21, v28, v38
	v_add_f32_e32 v22, 1.0, v22
	v_rcp_f32_e32 v22, v22
	s_nop 0
	v_mul_f32_e32 v21, v21, v22
	v_mul_f32_e32 v22, v29, v39
	v_mul_f32_e32 v22, v22, v23
	v_cvt_pk_bf16_f32 v21, v21, v22
	global_store_dwordx4 v[36:37], v[18:21], off
	ds_bpermute_b32 v18, v179, v82 offset:192
	s_nop 0
	v_add_u32_e32 v19, 0xb0, v180
	v_mad_i64_i32 v[20:21], s[2:3], v19, s43, v[162:163]
	s_waitcnt lgkmcnt(0)
	v_pk_fma_f32 v[14:15], v[14:15], v[18:19], v[78:79] op_sel_hi:[1,0,1]
	v_pk_fma_f32 v[6:7], v[6:7], v[18:19], v[70:71] op_sel_hi:[1,0,1]
	v_pk_fma_f32 v[22:23], v[4:5], v[18:19], v[68:69] op_sel_hi:[1,0,1]
	v_pk_fma_f32 v[4:5], v[2:3], v[18:19], v[66:67] op_sel_hi:[1,0,1]
	v_mul_f32_e32 v3, 0xbfb8aa3b, v14
	v_mul_f32_e32 v2, v14, v6
	v_exp_f32_e32 v3, v3
	v_mul_f32_e32 v6, 0xbfb8aa3b, v15
	v_exp_f32_e32 v6, v6
	v_pk_fma_f32 v[16:17], v[16:17], v[18:19], v[80:81] op_sel_hi:[1,0,1]
	v_add_f32_e32 v3, 1.0, v3
	v_rcp_f32_e32 v3, v3
	v_add_f32_e32 v6, 1.0, v6
	v_rcp_f32_e32 v6, v6
	v_pk_fma_f32 v[8:9], v[8:9], v[18:19], v[72:73] op_sel_hi:[1,0,1]
	v_mul_f32_e32 v2, v2, v3
	v_mul_f32_e32 v3, v15, v7
	v_mul_f32_e32 v3, v3, v6
	v_mul_f32_e32 v6, 0xbfb8aa3b, v16
	v_exp_f32_e32 v6, v6
	v_mul_f32_e32 v7, 0xbfb8aa3b, v17
	v_exp_f32_e32 v7, v7
	v_cvt_pk_bf16_f32 v2, v2, v3
	v_add_f32_e32 v6, 1.0, v6
	v_rcp_f32_e32 v6, v6
	v_add_f32_e32 v7, 1.0, v7
	v_rcp_f32_e32 v7, v7
	v_mul_f32_e32 v3, v16, v8
	v_mul_f32_e32 v3, v3, v6
	v_mul_f32_e32 v6, v17, v9
	v_pk_fma_f32 v[10:11], v[10:11], v[18:19], v[74:75] op_sel_hi:[1,0,1]
	v_mul_f32_e32 v6, v6, v7
	v_cvt_pk_bf16_f32 v3, v3, v6
	v_mul_f32_e32 v6, 0xbfb8aa3b, v10
	v_exp_f32_e32 v6, v6
	v_mul_f32_e32 v4, v10, v4
	v_pk_fma_f32 v[12:13], v[12:13], v[18:19], v[76:77] op_sel_hi:[1,0,1]
	v_mul_f32_e32 v5, v11, v5
	v_add_f32_e32 v6, 1.0, v6
	v_rcp_f32_e32 v6, v6
	v_mul_f32_e32 v7, 0xbfb8aa3b, v13
	v_exp_f32_e32 v7, v7
	v_lshl_add_u64 v[20:21], v[20:21], 0, v[164:165]
	v_mul_f32_e32 v4, v4, v6
	v_mul_f32_e32 v6, 0xbfb8aa3b, v11
	v_exp_f32_e32 v6, v6
	v_add_f32_e32 v7, 1.0, v7
	v_rcp_f32_e32 v7, v7
	s_mov_b64 s[2:3], -1
	v_add_f32_e32 v6, 1.0, v6
	v_rcp_f32_e32 v6, v6
	s_nop 0
	v_mul_f32_e32 v5, v5, v6
	v_mul_f32_e32 v6, 0xbfb8aa3b, v12
	v_exp_f32_e32 v6, v6
	v_cvt_pk_bf16_f32 v4, v4, v5
	v_mul_f32_e32 v5, v12, v22
	v_add_f32_e32 v6, 1.0, v6
	v_rcp_f32_e32 v6, v6
	s_nop 0
	v_mul_f32_e32 v5, v5, v6
	v_mul_f32_e32 v6, v13, v23
	v_mul_f32_e32 v6, v6, v7
	v_cvt_pk_bf16_f32 v5, v5, v6
	global_store_dwordx4 v[20:21], v[2:5], off
	s_cbranch_vccz .LBB0_2912
	s_andn2_b64 vcc, exec, s[4:5]
	s_cbranch_vccnz .LBB0_2911
	s_barrier
	s_branch .LBB0_2911

; template <int PHMASK> __global__ void __launch_bounds__(512, 2) fwd_kernel(Args args) {
	.amdhsa_kernel _Z10fwd_kernelILi4095EEv4Args
		.amdhsa_group_segment_fixed_size 0
		.amdhsa_private_segment_fixed_size 0
		.amdhsa_kernarg_size 432
		.amdhsa_user_sgpr_count 2
		.amdhsa_user_sgpr_dispatch_ptr 0
		.amdhsa_user_sgpr_queue_ptr 0
		.amdhsa_user_sgpr_kernarg_segment_ptr 1
		.amdhsa_user_sgpr_dispatch_id 0
		.amdhsa_user_sgpr_kernarg_preload_length 0
		.amdhsa_user_sgpr_kernarg_preload_offset 0
		.amdhsa_user_sgpr_private_segment_size 0
		.amdhsa_uses_dynamic_stack 0
		.amdhsa_enable_private_segment 0
		.amdhsa_system_sgpr_workgroup_id_x 1
		.amdhsa_system_sgpr_workgroup_id_y 0
		.amdhsa_system_sgpr_workgroup_id_z 0
		.amdhsa_system_sgpr_workgroup_info 0
		.amdhsa_system_vgpr_workitem_id 0
		.amdhsa_next_free_vgpr 255
		.amdhsa_next_free_sgpr 102
		.amdhsa_accum_offset 256
		.amdhsa_reserve_vcc 1
		.amdhsa_float_round_mode_32 0
		.amdhsa_float_round_mode_16_64 0
		.amdhsa_float_denorm_mode_32 3
		.amdhsa_float_denorm_mode_16_64 3
		.amdhsa_dx10_clamp 1
		.amdhsa_ieee_mode 1
		.amdhsa_fp16_overflow 0
		.amdhsa_tg_split 0
		.amdhsa_exception_fp_ieee_invalid_op 0
		.amdhsa_exception_fp_denorm_src 0
		.amdhsa_exception_fp_ieee_div_zero 0
		.amdhsa_exception_fp_ieee_overflow 0
		.amdhsa_exception_fp_ieee_underflow 0
		.amdhsa_exception_fp_ieee_inexact 0
		.amdhsa_exception_int_div_zero 0
	.end_amdhsa_kernel

; template <int PHMASK> __global__ void __launch_bounds__(512, 2) fwd_kernel(Args args) {
.Lfunc_end0:
	.size	_Z10fwd_kernelILi4095EEv4Args, .Lfunc_end0-_Z10fwd_kernelILi4095EEv4Args
	.set _Z10fwd_kernelILi4095EEv4Args.num_vgpr, 255
	.set _Z10fwd_kernelILi4095EEv4Args.num_agpr, 0
	.set _Z10fwd_kernelILi4095EEv4Args.numbered_sgpr, 102
	.set _Z10fwd_kernelILi4095EEv4Args.num_named_barrier, 0
	.set _Z10fwd_kernelILi4095EEv4Args.private_seg_size, 0
	.set _Z10fwd_kernelILi4095EEv4Args.uses_vcc, 1
	.set _Z10fwd_kernelILi4095EEv4Args.uses_flat_scratch, 0
	.set _Z10fwd_kernelILi4095EEv4Args.has_dyn_sized_stack, 0
	.set _Z10fwd_kernelILi4095EEv4Args.has_recursion, 0
	.set _Z10fwd_kernelILi4095EEv4Args.has_indirect_call, 0

; template <int PHMASK> __global__ void __launch_bounds__(512, 2) fwd_kernel(Args args) {
amdhsa.kernels:
  - .agpr_count:     0
    .args:
      - .offset:         0
        .size:           176
        .value_kind:     by_value
      - .offset:         176
        .size:           4
        .value_kind:     hidden_block_count_x
      - .offset:         180
        .size:           4
        .value_kind:     hidden_block_count_y
      - .offset:         184
        .size:           4
        .value_kind:     hidden_block_count_z
      - .offset:         188
        .size:           2
        .value_kind:     hidden_group_size_x
      - .offset:         190
        .size:           2
        .value_kind:     hidden_group_size_y
      - .offset:         192
        .size:           2
        .value_kind:     hidden_group_size_z
      - .offset:         194
        .size:           2
        .value_kind:     hidden_remainder_x
      - .offset:         196
        .size:           2
        .value_kind:     hidden_remainder_y
      - .offset:         198
        .size:           2
        .value_kind:     hidden_remainder_z
      - .offset:         216
        .size:           8
        .value_kind:     hidden_global_offset_x
      - .offset:         224
        .size:           8
        .value_kind:     hidden_global_offset_y
      - .offset:         232
        .size:           8
        .value_kind:     hidden_global_offset_z
      - .offset:         240
        .size:           2
        .value_kind:     hidden_grid_dims
      - .offset:         296
        .size:           4
        .value_kind:     hidden_dynamic_lds_size
    .group_segment_fixed_size: 0
    .kernarg_segment_align: 8
    .kernarg_segment_size: 432
    .language:       OpenCL C
    .language_version:
      - 2
      - 0
    .max_flat_workgroup_size: 512
    .name:           _Z10fwd_kernelILi4095EEv4Args
    .private_segment_fixed_size: 0
    .sgpr_count:     108
    .sgpr_spill_count: 185
    .symbol:         _Z10fwd_kernelILi4095EEv4Args.kd
    .uniform_work_group_size: 1
    .uses_dynamic_stack: false
    .vgpr_count:     255
    .vgpr_spill_count: 0
    .wavefront_size: 64
